# SSM scan: A^16/A^32/A^64 multiplier tables precomputed once per item in LDS and read with ds_read instead of recomputing the squarings on the VALU every chunk (both passes)
# speedup vs baseline: 1.0038x; 1.0038x over previous
; #define LAS __attribute__((address_space(3)))
; template <bool PASS2>
; __device__ __forceinline__ void ssm_phase(const Params& p, const Frame& F0) {
;     ...
;         { const u32x4* src = (const u32x4*)((const bf16_t*)(p.ws + WS_SSMW) + (size_t)g * SSM_FRAG_ELEMS);
;           for (int e = F.tid; e < SSM_FRAG_ELEMS / 8; e += 512) ((LAS u32x4*)F.lds)[e] = src[e];
;           if (F.tid < 64) ((LAS f32x2*)(F.lds + SSM_M1_OFF))[F.tid] = ((const f32x2*)(p.ws + WS_M1))[g * 64 + F.tid]; }
.LBB0_524:
	s_or_b64 exec, exec, s[16:17]
	s_lshl_b32 s0, s23, 2
	s_and_b32 s0, s0, 28
	s_and_b32 s1, s24, 3
	s_or_b32 s16, s0, s1
	s_and_saveexec_b64 s[0:1], s[4:5]
	s_cbranch_execz .LBB0_526
	v_lshl_add_u32 v0, s16, 6, v36
	v_ashrrev_i32_e32 v1, 31, v0
	v_lshl_add_u64 v[0:1], v[0:1], 3, s[12:13]
	global_load_dwordx2 v[0:1], v[0:1], off
	s_waitcnt vmcnt(0)
	ds_write_b64 v104, v[0:1]
	v_bfe_u32 v4, v104, 3, 1
	v_lshlrev_b32_e32 v4, 2, v4
	v_sub_u32_e32 v4, v104, v4
	v_mul_f32_e32 v5, v1, v1
	v_add_f32_e32 v6, v0, v0
	v_fma_f32 v7, v0, v0, -v5
	v_mul_f32_e32 v8, v6, v1
	ds_write_b32 v4, v7 offset:512
	ds_write_b32 v4, v8 offset:520
	v_mul_f32_e32 v5, v8, v8
	v_add_f32_e32 v6, v7, v7
	v_fma_f32 v9, v7, v7, -v5
	v_mul_f32_e32 v10, v6, v8
	ds_write_b32 v4, v9 offset:1024
	ds_write_b32 v4, v10 offset:1032
	v_mul_f32_e32 v5, v10, v10
	v_add_f32_e32 v6, v9, v9
	v_fma_f32 v7, v9, v9, -v5
	v_mul_f32_e32 v8, v6, v10
	ds_write_b32 v4, v7 offset:1536
	ds_write_b32 v4, v8 offset:1544

; #define SSM_SCAN_STEP(D, SQ) { _Pragma("unroll") for (int r = 0; r < 4; ++r) { \
;                     const float sr = dppf<DPP_SHR(D)>(Er[r]), si = dppf<DPP_SHR(D)>(Ei[r]); \
;                     Er[r] += mr[r] * sr - mi[r] * si; Ei[r] += mr[r] * si + mi[r] * sr; \
;                     if (SQ) { const float nr = mr[r] * mr[r] - mi[r] * mi[r], ni = 2.f * mr[r] * mi[r]; mr[r] = nr; mi[r] = ni; } } }
; template <bool PASS2>
; __device__ __forceinline__ void ssm_phase(const Params& p, const Frame& F0) {
;     ...
;             for (int i = 0; i < 4; ++i) {
;                 __builtin_amdgcn_sched_barrier(0);
;                 f32x4 Er = (f32x4){0.f, 0.f, 0.f, 0.f}, Ei = Er;
; #pragma unroll
;                 for (int ks = 0; ks < 4; ++ks) { Er = __builtin_amdgcn_mfma_f32_16x16x32_bf16(frag[(i * 4 + ks) * 64], uf[ks], Er, 0, 0, 0);
;                                                  Ei = __builtin_amdgcn_mfma_f32_16x16x32_bf16(frag[((i + 4) * 4 + ks) * 64], uf[ks], Ei, 0, 0, 0); }
;                 const f32x4 ma = m1t[8 * i], mb = m1t[8 * i + 1];
;                 float mr[4] = {ma[0], ma[2], mb[0], mb[2]}, mi[4] = {ma[1], ma[3], mb[1], mb[3]};
;                 float hr[4], hi[4];
; #pragma unroll
;                 for (int r = 0; r < 4; ++r) { hr[r] = dppf<DPP_ROR(1)>(xs[i][r]); hi[r] = dppf<DPP_ROR(1)>(xs[i + 4][r]);
;                     if (j == 0) { Er[r] += mr[r] * hr[r] - mi[r] * hi[r]; Ei[r] += mr[r] * hi[r] + mi[r] * hr[r]; } }
;     ...
;                 SSM_SCAN_STEP(1, 1) SSM_SCAN_STEP(2, 1) SSM_SCAN_STEP(4, 1) SSM_SCAN_STEP(8, 0)
.LBB0_527:
	s_waitcnt vmcnt(0)
	v_mov_b64_e32 v[18:19], v[2:3]
	v_mov_b64_e32 v[26:27], v[6:7]
	v_mov_b64_e32 v[16:17], v[0:1]
	v_add_u32_e32 v1, s0, v80
	v_mov_b64_e32 v[24:25], v[4:5]
	v_add_u32_e32 v0, 0x80, v1
	v_add_u32_e32 v2, 0x82, v1
	v_add_u32_e32 v4, 0x84, v1
	v_add_u32_e32 v6, 0x86, v1
	v_ashrrev_i32_e32 v1, 31, v0
	v_ashrrev_i32_e32 v3, 31, v2
	v_ashrrev_i32_e32 v5, 31, v4
	v_mov_b64_e32 v[22:23], v[10:11]
	v_ashrrev_i32_e32 v7, 31, v6
	v_lshlrev_b64 v[0:1], 10, v[0:1]
	v_lshlrev_b64 v[2:3], 10, v[2:3]
	v_lshlrev_b64 v[4:5], 10, v[4:5]
	v_mov_b64_e32 v[30:31], v[14:15]
	v_mov_b64_e32 v[20:21], v[8:9]
	v_lshlrev_b64 v[6:7], 10, v[6:7]
	v_lshl_add_u64 v[0:1], v[64:65], 0, v[0:1]
	v_lshl_add_u64 v[2:3], v[64:65], 0, v[2:3]
	v_lshl_add_u64 v[8:9], v[64:65], 0, v[4:5]
	v_mov_b64_e32 v[28:29], v[12:13]
	v_lshl_add_u64 v[32:33], v[64:65], 0, v[6:7]
	global_load_dwordx4 v[12:15], v[0:1], off
	global_load_dwordx4 v[4:7], v[2:3], off
	s_nop 0
	global_load_dwordx4 v[8:11], v[8:9], off
	s_nop 0
	global_load_dwordx4 v[0:3], v[32:33], off
	v_mov_b32_dpp v79, v72 row_ror:1 row_mask:0xf bank_mask:0xf bound_ctrl:1
	v_mov_b32_dpp v78, v70 row_ror:1 row_mask:0xf bank_mask:0xf bound_ctrl:1
	v_mov_b32_dpp v73, v73 row_ror:1 row_mask:0xf bank_mask:0xf bound_ctrl:1
	v_mov_b32_dpp v72, v71 row_ror:1 row_mask:0xf bank_mask:0xf bound_ctrl:1
	v_mfma_f32_16x16x32_bf16 v[32:35], v[130:133], v[28:31], 0
	v_mfma_f32_16x16x32_bf16 v[32:35], v[134:137], v[24:27], v[32:35]
	v_mfma_f32_16x16x32_bf16 v[82:85], v[194:197], v[28:31], 0
	v_mfma_f32_16x16x32_bf16 v[82:85], v[198:201], v[24:27], v[82:85]
	v_mfma_f32_16x16x32_bf16 v[32:35], v[138:141], v[20:23], v[32:35]
	v_mfma_f32_16x16x32_bf16 v[82:85], v[204:207], v[20:23], v[82:85]
	v_mfma_f32_16x16x32_bf16 v[86:89], v[142:145], v[16:19], v[32:35]
	s_nop 2
	v_mfma_f32_16x16x32_bf16 v[82:85], v[208:211], v[16:19], v[82:85]
	ds_read_b128 v[90:93], v109
	s_nop 0
	ds_read_b128 v[32:35], v109 offset:16
	ds_read_b128 v[100:103], v109 offset:1024
	ds_read_b128 v[110:113], v109 offset:1536
	s_waitcnt lgkmcnt(3)
	v_pk_mul_f32 v[94:95], v[90:91], v[78:79] op_sel:[0,1] op_sel_hi:[1,0]
	s_nop 0
	v_sub_f32_e32 v70, v94, v95
	v_pk_mul_f32 v[78:79], v[90:91], v[78:79]
	v_add_f32_e32 v81, v86, v70
	v_add_f32_e32 v70, v79, v78
	v_add_f32_e32 v78, v82, v70
	v_pk_mul_f32 v[70:71], v[92:93], v[72:73] op_sel:[0,1] op_sel_hi:[1,0]
	v_mov_b32_e32 v96, v91
	v_sub_f32_e32 v70, v70, v71
	v_add_f32_e32 v79, v70, v87
	v_pk_mul_f32 v[70:71], v[92:93], v[72:73]
	v_mov_b32_e32 v97, v93
	v_add_f32_e32 v70, v71, v70
	v_add_f32_e32 v94, v70, v83
	v_mov_b32_dpp v71, v76 row_ror:1 row_mask:0xf bank_mask:0xf bound_ctrl:1
	v_mov_b32_dpp v70, v74 row_ror:1 row_mask:0xf bank_mask:0xf bound_ctrl:1
	s_waitcnt lgkmcnt(2)
	v_pk_mul_f32 v[72:73], v[32:33], v[70:71] op_sel:[0,1] op_sel_hi:[1,0]
	v_pk_mul_f32 v[70:71], v[32:33], v[70:71]
	v_sub_f32_e32 v72, v72, v73
	v_add_f32_e32 v70, v71, v70
	v_add_f32_e32 v76, v70, v84
	v_mov_b32_dpp v71, v77 row_ror:1 row_mask:0xf bank_mask:0xf bound_ctrl:1
	v_mov_b32_dpp v70, v75 row_ror:1 row_mask:0xf bank_mask:0xf bound_ctrl:1
	v_add_f32_e32 v74, v72, v88
	v_pk_mul_f32 v[72:73], v[34:35], v[70:71] op_sel:[0,1] op_sel_hi:[1,0]
	v_pk_mul_f32 v[70:71], v[34:35], v[70:71]
	v_sub_f32_e32 v72, v72, v73
	v_add_f32_e32 v70, v71, v70
	v_add_f32_e32 v70, v70, v85
	v_add_f32_e32 v72, v72, v89
	v_cndmask_b32_e64 v85, v85, v70, s[6:7]
	v_cndmask_b32_e64 v71, v83, v94, s[6:7]
	v_cndmask_b32_e64 v70, v82, v78, s[6:7]
	v_cndmask_b32_e64 v75, v89, v72, s[6:7]
	v_cndmask_b32_e64 v74, v88, v74, s[6:7]
	v_cndmask_b32_e64 v73, v87, v79, s[6:7]
	v_cndmask_b32_e64 v72, v86, v81, s[6:7]
	v_mov_b32_dpp v86, v70 row_shr:1 row_mask:0xf bank_mask:0xf bound_ctrl:1
	v_mov_b32_dpp v87, v71 row_shr:1 row_mask:0xf bank_mask:0xf bound_ctrl:1
	v_mov_b32_e32 v88, v90
	v_mov_b32_e32 v89, v92
	ds_read_b128 v[90:93], v109 offset:512
	v_mov_b32_dpp v82, v72 row_shr:1 row_mask:0xf bank_mask:0xf bound_ctrl:1
	v_mov_b32_dpp v83, v73 row_shr:1 row_mask:0xf bank_mask:0xf bound_ctrl:1
	v_pk_mul_f32 v[94:95], v[88:89], v[86:87]
	v_pk_fma_f32 v[94:95], v[96:97], v[82:83], v[94:95]
	v_pk_add_f32 v[70:71], v[94:95], v[70:71]
	v_pk_mul_f32 v[86:87], v[96:97], v[86:87]
	v_pk_fma_f32 v[82:83], v[88:89], v[82:83], v[86:87] neg_lo:[0,0,1] neg_hi:[0,0,1]
	v_mov_b32_dpp v94, v70 row_shr:2 row_mask:0xf bank_mask:0xf bound_ctrl:1
	v_mov_b32_dpp v95, v71 row_shr:2 row_mask:0xf bank_mask:0xf bound_ctrl:1
	v_pk_add_f32 v[72:73], v[82:83], v[72:73]
	s_waitcnt lgkmcnt(0)
; #define SSM_SCAN_STEP(D, SQ) { _Pragma("unroll") for (int r = 0; r < 4; ++r) { \
;                     const float sr = dppf<DPP_SHR(D)>(Er[r]), si = dppf<DPP_SHR(D)>(Ei[r]); \
;                     Er[r] += mr[r] * sr - mi[r] * si; Ei[r] += mr[r] * si + mi[r] * sr; \
;                     if (SQ) { const float nr = mr[r] * mr[r] - mi[r] * mi[r], ni = 2.f * mr[r] * mi[r]; mr[r] = nr; mi[r] = ni; } } }
; template <bool PASS2>
; __device__ __forceinline__ void ssm_phase(const Params& p, const Frame& F0) {
;     ...
;             for (int i = 0; i < 4; ++i) {
;                 __builtin_amdgcn_sched_barrier(0);
;                 f32x4 Er = (f32x4){0.f, 0.f, 0.f, 0.f}, Ei = Er;
; #pragma unroll
;                 for (int ks = 0; ks < 4; ++ks) { Er = __builtin_amdgcn_mfma_f32_16x16x32_bf16(frag[(i * 4 + ks) * 64], uf[ks], Er, 0, 0, 0);
;                                                  Ei = __builtin_amdgcn_mfma_f32_16x16x32_bf16(frag[((i + 4) * 4 + ks) * 64], uf[ks], Ei, 0, 0, 0); }
;                 const f32x4 ma = m1t[8 * i], mb = m1t[8 * i + 1];
;                 float mr[4] = {ma[0], ma[2], mb[0], mb[2]}, mi[4] = {ma[1], ma[3], mb[1], mb[3]};
;                 float hr[4], hi[4];
; #pragma unroll
;                 for (int r = 0; r < 4; ++r) { hr[r] = dppf<DPP_ROR(1)>(xs[i][r]); hi[r] = dppf<DPP_ROR(1)>(xs[i + 4][r]);
;                     if (j == 0) { Er[r] += mr[r] * hr[r] - mi[r] * hi[r]; Ei[r] += mr[r] * hi[r] + mi[r] * hr[r]; } }
;     ...
;                 SSM_SCAN_STEP(1, 1) SSM_SCAN_STEP(2, 1) SSM_SCAN_STEP(4, 1) SSM_SCAN_STEP(8, 0)
	v_pk_mul_f32 v[98:99], v[90:91], v[94:95]
	v_pk_mul_f32 v[86:87], v[92:93], v[94:95]
	v_mov_b32_dpp v82, v72 row_shr:2 row_mask:0xf bank_mask:0xf bound_ctrl:1
	v_mov_b32_dpp v83, v73 row_shr:2 row_mask:0xf bank_mask:0xf bound_ctrl:1
	v_pk_fma_f32 v[86:87], v[90:91], v[82:83], v[86:87] neg_lo:[0,0,1] neg_hi:[0,0,1]
	v_pk_fma_f32 v[82:83], v[92:93], v[82:83], v[98:99]
	ds_read_b128 v[92:95], v109 offset:1040
	ds_read_b128 v[96:99], v109 offset:1552
	v_pk_add_f32 v[70:71], v[70:71], v[82:83]
	v_pk_add_f32 v[72:73], v[86:87], v[72:73]
	s_nop 0
	v_mov_b32_dpp v86, v70 row_shr:4 row_mask:0xf bank_mask:0xf bound_ctrl:1
	v_mov_b32_dpp v87, v71 row_shr:4 row_mask:0xf bank_mask:0xf bound_ctrl:1
	v_mov_b32_dpp v82, v72 row_shr:4 row_mask:0xf bank_mask:0xf bound_ctrl:1
	v_mov_b32_dpp v83, v73 row_shr:4 row_mask:0xf bank_mask:0xf bound_ctrl:1
	v_pk_mul_f32 v[88:89], v[102:103], v[86:87]
	v_pk_mul_f32 v[86:87], v[100:101], v[86:87]
	v_pk_fma_f32 v[88:89], v[100:101], v[82:83], v[88:89] neg_lo:[0,0,1] neg_hi:[0,0,1]
	v_pk_fma_f32 v[82:83], v[102:103], v[82:83], v[86:87]
	v_pk_add_f32 v[70:71], v[70:71], v[82:83]
	v_pk_add_f32 v[72:73], v[72:73], v[88:89]
	s_nop 0
	v_mov_b32_dpp v86, v70 row_shr:8 row_mask:0xf bank_mask:0xf bound_ctrl:1
	v_mov_b32_dpp v87, v71 row_shr:8 row_mask:0xf bank_mask:0xf bound_ctrl:1
	v_mov_b32_dpp v82, v72 row_shr:8 row_mask:0xf bank_mask:0xf bound_ctrl:1
	v_mov_b32_dpp v83, v73 row_shr:8 row_mask:0xf bank_mask:0xf bound_ctrl:1
	v_pk_mul_f32 v[88:89], v[112:113], v[86:87]
	v_pk_mul_f32 v[86:87], v[110:111], v[86:87]
	v_cndmask_b32_e64 v84, v84, v76, s[6:7]
	v_pk_fma_f32 v[88:89], v[110:111], v[82:83], v[88:89] neg_lo:[0,0,1] neg_hi:[0,0,1]
	v_pk_fma_f32 v[82:83], v[112:113], v[82:83], v[86:87]
	v_mov_b32_dpp v78, v84 row_shr:1 row_mask:0xf bank_mask:0xf bound_ctrl:1
	v_mov_b32_dpp v79, v85 row_shr:1 row_mask:0xf bank_mask:0xf bound_ctrl:1
	v_pk_add_f32 v[70:71], v[70:71], v[82:83]
	v_mov_b32_e32 v82, v32
	v_mov_b32_e32 v83, v34
	v_mov_b32_dpp v76, v74 row_shr:1 row_mask:0xf bank_mask:0xf bound_ctrl:1
	v_mov_b32_dpp v77, v75 row_shr:1 row_mask:0xf bank_mask:0xf bound_ctrl:1
	v_pk_add_f32 v[72:73], v[72:73], v[88:89]
	v_pk_mul_f32 v[86:87], v[82:83], v[78:79]
	v_mov_b32_e32 v88, v33
	ds_read_b64 v[32:33], v109 offset:528
	v_mov_b32_e32 v89, v35
	ds_read_b64 v[34:35], v109 offset:536
	v_pk_fma_f32 v[86:87], v[88:89], v[76:77], v[86:87]
	v_pk_mul_f32 v[78:79], v[88:89], v[78:79]
	v_pk_add_f32 v[84:85], v[86:87], v[84:85]
	v_pk_fma_f32 v[76:77], v[82:83], v[76:77], v[78:79] neg_lo:[0,0,1] neg_hi:[0,0,1]
	s_nop 0
	v_mov_b32_dpp v86, v84 row_shr:2 row_mask:0xf bank_mask:0xf bound_ctrl:1
	v_mov_b32_dpp v87, v85 row_shr:2 row_mask:0xf bank_mask:0xf bound_ctrl:1
	v_pk_add_f32 v[74:75], v[76:77], v[74:75]
	s_waitcnt lgkmcnt(1)
	v_pk_mul_f32 v[90:91], v[32:33], v[86:87]
	v_mov_b32_dpp v76, v74 row_shr:2 row_mask:0xf bank_mask:0xf bound_ctrl:1
	v_mov_b32_dpp v77, v75 row_shr:2 row_mask:0xf bank_mask:0xf bound_ctrl:1
	s_waitcnt lgkmcnt(0)
	v_pk_mul_f32 v[78:79], v[34:35], v[86:87]
	v_pk_fma_f32 v[34:35], v[34:35], v[76:77], v[90:91]
	v_pk_fma_f32 v[32:33], v[32:33], v[76:77], v[78:79] neg_lo:[0,0,1] neg_hi:[0,0,1]
	v_pk_add_f32 v[34:35], v[84:85], v[34:35]
	v_pk_add_f32 v[32:33], v[74:75], v[32:33]
	s_nop 0
	v_mov_b32_dpp v76, v34 row_shr:4 row_mask:0xf bank_mask:0xf bound_ctrl:1
	v_mov_b32_dpp v77, v35 row_shr:4 row_mask:0xf bank_mask:0xf bound_ctrl:1
	v_mov_b32_dpp v74, v32 row_shr:4 row_mask:0xf bank_mask:0xf bound_ctrl:1
	v_mov_b32_dpp v75, v33 row_shr:4 row_mask:0xf bank_mask:0xf bound_ctrl:1
	v_pk_mul_f32 v[78:79], v[94:95], v[76:77]
	v_pk_mul_f32 v[76:77], v[92:93], v[76:77]
	v_pk_fma_f32 v[78:79], v[92:93], v[74:75], v[78:79] neg_lo:[0,0,1] neg_hi:[0,0,1]
	v_pk_fma_f32 v[74:75], v[94:95], v[74:75], v[76:77]
	v_pk_add_f32 v[34:35], v[34:35], v[74:75]
	v_pk_add_f32 v[32:33], v[32:33], v[78:79]
	s_nop 0
	v_mov_b32_dpp v78, v34 row_shr:8 row_mask:0xf bank_mask:0xf bound_ctrl:1
	v_mov_b32_dpp v79, v35 row_shr:8 row_mask:0xf bank_mask:0xf bound_ctrl:1
	v_mov_b32_dpp v74, v32 row_shr:8 row_mask:0xf bank_mask:0xf bound_ctrl:1
	v_mov_b32_dpp v75, v33 row_shr:8 row_mask:0xf bank_mask:0xf bound_ctrl:1
	v_pk_mul_f32 v[76:77], v[98:99], v[78:79]
	s_nop 0
	v_pk_fma_f32 v[76:77], v[96:97], v[74:75], v[76:77] neg_lo:[0,0,1] neg_hi:[0,0,1]
	s_nop 0
	v_pk_add_f32 v[76:77], v[32:33], v[76:77]
	v_pk_mul_f32 v[32:33], v[96:97], v[78:79]
	s_nop 0
	v_pk_fma_f32 v[32:33], v[98:99], v[74:75], v[32:33]
	s_nop 0
	v_pk_add_f32 v[74:75], v[34:35], v[32:33]
	v_mov_b32_dpp v79, v62 row_ror:1 row_mask:0xf bank_mask:0xf bound_ctrl:1
	v_mov_b32_dpp v78, v60 row_ror:1 row_mask:0xf bank_mask:0xf bound_ctrl:1
	v_mov_b32_dpp v63, v63 row_ror:1 row_mask:0xf bank_mask:0xf bound_ctrl:1
	v_mov_b32_dpp v62, v61 row_ror:1 row_mask:0xf bank_mask:0xf bound_ctrl:1
	v_mfma_f32_16x16x32_bf16 v[32:35], v[146:149], v[28:31], 0
	v_mfma_f32_16x16x32_bf16 v[32:35], v[150:153], v[24:27], v[32:35]
	v_mfma_f32_16x16x32_bf16 v[82:85], v[212:215], v[28:31], 0
	v_mfma_f32_16x16x32_bf16 v[82:85], v[216:219], v[24:27], v[82:85]
	v_mfma_f32_16x16x32_bf16 v[32:35], v[154:157], v[20:23], v[32:35]
	v_mfma_f32_16x16x32_bf16 v[82:85], v[220:223], v[20:23], v[82:85]
	v_mfma_f32_16x16x32_bf16 v[86:89], v[158:161], v[16:19], v[32:35]
	s_nop 2
	v_mfma_f32_16x16x32_bf16 v[82:85], v[224:227], v[16:19], v[82:85]
	ds_read_b128 v[90:93], v109 offset:128
	s_nop 0
	ds_read_b128 v[32:35], v109 offset:144
	ds_read_b128 v[100:103], v109 offset:1152
	ds_read_b128 v[110:113], v109 offset:1664
	s_waitcnt lgkmcnt(3)
; #define SSM_SCAN_STEP(D, SQ) { _Pragma("unroll") for (int r = 0; r < 4; ++r) { \
;                     const float sr = dppf<DPP_SHR(D)>(Er[r]), si = dppf<DPP_SHR(D)>(Ei[r]); \
;                     Er[r] += mr[r] * sr - mi[r] * si; Ei[r] += mr[r] * si + mi[r] * sr; \
;                     if (SQ) { const float nr = mr[r] * mr[r] - mi[r] * mi[r], ni = 2.f * mr[r] * mi[r]; mr[r] = nr; mi[r] = ni; } } }
; template <bool PASS2>
; __device__ __forceinline__ void ssm_phase(const Params& p, const Frame& F0) {
;     ...
;             for (int i = 0; i < 4; ++i) {
;                 __builtin_amdgcn_sched_barrier(0);
;                 f32x4 Er = (f32x4){0.f, 0.f, 0.f, 0.f}, Ei = Er;
; #pragma unroll
;                 for (int ks = 0; ks < 4; ++ks) { Er = __builtin_amdgcn_mfma_f32_16x16x32_bf16(frag[(i * 4 + ks) * 64], uf[ks], Er, 0, 0, 0);
;                                                  Ei = __builtin_amdgcn_mfma_f32_16x16x32_bf16(frag[((i + 4) * 4 + ks) * 64], uf[ks], Ei, 0, 0, 0); }
;                 const f32x4 ma = m1t[8 * i], mb = m1t[8 * i + 1];
;                 float mr[4] = {ma[0], ma[2], mb[0], mb[2]}, mi[4] = {ma[1], ma[3], mb[1], mb[3]};
;                 float hr[4], hi[4];
; #pragma unroll
;                 for (int r = 0; r < 4; ++r) { hr[r] = dppf<DPP_ROR(1)>(xs[i][r]); hi[r] = dppf<DPP_ROR(1)>(xs[i + 4][r]);
;                     if (j == 0) { Er[r] += mr[r] * hr[r] - mi[r] * hi[r]; Ei[r] += mr[r] * hi[r] + mi[r] * hr[r]; } }
;     ...
;                 SSM_SCAN_STEP(1, 1) SSM_SCAN_STEP(2, 1) SSM_SCAN_STEP(4, 1) SSM_SCAN_STEP(8, 0)
	v_pk_mul_f32 v[94:95], v[90:91], v[78:79] op_sel:[0,1] op_sel_hi:[1,0]
	s_nop 0
	v_sub_f32_e32 v60, v94, v95
	v_pk_mul_f32 v[78:79], v[90:91], v[78:79]
	v_add_f32_e32 v81, v86, v60
	v_add_f32_e32 v60, v79, v78
	v_add_f32_e32 v78, v82, v60
	v_pk_mul_f32 v[60:61], v[92:93], v[62:63] op_sel:[0,1] op_sel_hi:[1,0]
	v_mov_b32_e32 v96, v91
	v_sub_f32_e32 v60, v60, v61
	v_add_f32_e32 v79, v60, v87
	v_pk_mul_f32 v[60:61], v[92:93], v[62:63]
	v_mov_b32_e32 v97, v93
	v_add_f32_e32 v60, v61, v60
	v_add_f32_e32 v94, v60, v83
	v_mov_b32_dpp v61, v68 row_ror:1 row_mask:0xf bank_mask:0xf bound_ctrl:1
	v_mov_b32_dpp v60, v66 row_ror:1 row_mask:0xf bank_mask:0xf bound_ctrl:1
	s_waitcnt lgkmcnt(2)
	v_pk_mul_f32 v[62:63], v[32:33], v[60:61] op_sel:[0,1] op_sel_hi:[1,0]
	v_pk_mul_f32 v[60:61], v[32:33], v[60:61]
	v_sub_f32_e32 v62, v62, v63
	v_add_f32_e32 v60, v61, v60
	v_add_f32_e32 v68, v60, v84
	v_mov_b32_dpp v61, v69 row_ror:1 row_mask:0xf bank_mask:0xf bound_ctrl:1
	v_mov_b32_dpp v60, v67 row_ror:1 row_mask:0xf bank_mask:0xf bound_ctrl:1
	v_add_f32_e32 v66, v62, v88
	v_pk_mul_f32 v[62:63], v[34:35], v[60:61] op_sel:[0,1] op_sel_hi:[1,0]
	v_pk_mul_f32 v[60:61], v[34:35], v[60:61]
	v_sub_f32_e32 v62, v62, v63
	v_add_f32_e32 v60, v61, v60
	v_add_f32_e32 v60, v60, v85
	v_add_f32_e32 v62, v62, v89
	v_cndmask_b32_e64 v85, v85, v60, s[6:7]
	v_cndmask_b32_e64 v61, v83, v94, s[6:7]
	v_cndmask_b32_e64 v60, v82, v78, s[6:7]
	v_cndmask_b32_e64 v67, v89, v62, s[6:7]
	v_cndmask_b32_e64 v66, v88, v66, s[6:7]
	v_cndmask_b32_e64 v63, v87, v79, s[6:7]
	v_cndmask_b32_e64 v62, v86, v81, s[6:7]
	v_mov_b32_dpp v86, v60 row_shr:1 row_mask:0xf bank_mask:0xf bound_ctrl:1
	v_mov_b32_dpp v87, v61 row_shr:1 row_mask:0xf bank_mask:0xf bound_ctrl:1
	v_mov_b32_e32 v88, v90
	v_mov_b32_e32 v89, v92
	ds_read_b128 v[90:93], v109 offset:640
	v_mov_b32_dpp v82, v62 row_shr:1 row_mask:0xf bank_mask:0xf bound_ctrl:1
	v_mov_b32_dpp v83, v63 row_shr:1 row_mask:0xf bank_mask:0xf bound_ctrl:1
	v_pk_mul_f32 v[94:95], v[88:89], v[86:87]
	v_pk_fma_f32 v[94:95], v[96:97], v[82:83], v[94:95]
	v_pk_add_f32 v[60:61], v[94:95], v[60:61]
	v_pk_mul_f32 v[86:87], v[96:97], v[86:87]
	v_pk_fma_f32 v[82:83], v[88:89], v[82:83], v[86:87] neg_lo:[0,0,1] neg_hi:[0,0,1]
	v_mov_b32_dpp v94, v60 row_shr:2 row_mask:0xf bank_mask:0xf bound_ctrl:1
	v_mov_b32_dpp v95, v61 row_shr:2 row_mask:0xf bank_mask:0xf bound_ctrl:1
	v_pk_add_f32 v[62:63], v[82:83], v[62:63]
	s_waitcnt lgkmcnt(0)
	v_pk_mul_f32 v[98:99], v[90:91], v[94:95]
	v_pk_mul_f32 v[86:87], v[92:93], v[94:95]
	v_mov_b32_dpp v82, v62 row_shr:2 row_mask:0xf bank_mask:0xf bound_ctrl:1
	v_mov_b32_dpp v83, v63 row_shr:2 row_mask:0xf bank_mask:0xf bound_ctrl:1
	v_pk_fma_f32 v[86:87], v[90:91], v[82:83], v[86:87] neg_lo:[0,0,1] neg_hi:[0,0,1]
	v_pk_fma_f32 v[82:83], v[92:93], v[82:83], v[98:99]
	ds_read_b128 v[92:95], v109 offset:1168
	ds_read_b128 v[96:99], v109 offset:1680
	v_pk_add_f32 v[60:61], v[60:61], v[82:83]
	v_pk_add_f32 v[62:63], v[86:87], v[62:63]
	s_nop 0
	v_mov_b32_dpp v86, v60 row_shr:4 row_mask:0xf bank_mask:0xf bound_ctrl:1
	v_mov_b32_dpp v87, v61 row_shr:4 row_mask:0xf bank_mask:0xf bound_ctrl:1
	v_mov_b32_dpp v82, v62 row_shr:4 row_mask:0xf bank_mask:0xf bound_ctrl:1
	v_mov_b32_dpp v83, v63 row_shr:4 row_mask:0xf bank_mask:0xf bound_ctrl:1
	v_pk_mul_f32 v[88:89], v[102:103], v[86:87]
	v_pk_mul_f32 v[86:87], v[100:101], v[86:87]
	v_pk_fma_f32 v[88:89], v[100:101], v[82:83], v[88:89] neg_lo:[0,0,1] neg_hi:[0,0,1]
	v_pk_fma_f32 v[82:83], v[102:103], v[82:83], v[86:87]
	v_pk_add_f32 v[60:61], v[60:61], v[82:83]
	v_pk_add_f32 v[62:63], v[62:63], v[88:89]
	s_nop 0
	v_mov_b32_dpp v86, v60 row_shr:8 row_mask:0xf bank_mask:0xf bound_ctrl:1
	v_mov_b32_dpp v87, v61 row_shr:8 row_mask:0xf bank_mask:0xf bound_ctrl:1
	v_mov_b32_dpp v82, v62 row_shr:8 row_mask:0xf bank_mask:0xf bound_ctrl:1
	v_mov_b32_dpp v83, v63 row_shr:8 row_mask:0xf bank_mask:0xf bound_ctrl:1
	v_pk_mul_f32 v[88:89], v[112:113], v[86:87]
	v_pk_mul_f32 v[86:87], v[110:111], v[86:87]
	v_cndmask_b32_e64 v84, v84, v68, s[6:7]
	v_pk_fma_f32 v[88:89], v[110:111], v[82:83], v[88:89] neg_lo:[0,0,1] neg_hi:[0,0,1]
	v_pk_fma_f32 v[82:83], v[112:113], v[82:83], v[86:87]
	v_mov_b32_dpp v78, v84 row_shr:1 row_mask:0xf bank_mask:0xf bound_ctrl:1
	v_mov_b32_dpp v79, v85 row_shr:1 row_mask:0xf bank_mask:0xf bound_ctrl:1
	v_pk_add_f32 v[60:61], v[60:61], v[82:83]
	v_mov_b32_e32 v82, v32
	v_mov_b32_e32 v83, v34
	v_mov_b32_dpp v68, v66 row_shr:1 row_mask:0xf bank_mask:0xf bound_ctrl:1
	v_mov_b32_dpp v69, v67 row_shr:1 row_mask:0xf bank_mask:0xf bound_ctrl:1
	v_pk_add_f32 v[62:63], v[62:63], v[88:89]
	v_pk_mul_f32 v[86:87], v[82:83], v[78:79]
	v_mov_b32_e32 v88, v33
	ds_read_b64 v[32:33], v109 offset:656
	v_mov_b32_e32 v89, v35
	ds_read_b64 v[34:35], v109 offset:664
	v_pk_fma_f32 v[86:87], v[88:89], v[68:69], v[86:87]
	v_pk_mul_f32 v[78:79], v[88:89], v[78:79]
	v_pk_add_f32 v[84:85], v[86:87], v[84:85]
	v_pk_fma_f32 v[68:69], v[82:83], v[68:69], v[78:79] neg_lo:[0,0,1] neg_hi:[0,0,1]
	s_nop 0
	v_mov_b32_dpp v86, v84 row_shr:2 row_mask:0xf bank_mask:0xf bound_ctrl:1
	v_mov_b32_dpp v87, v85 row_shr:2 row_mask:0xf bank_mask:0xf bound_ctrl:1
	v_pk_add_f32 v[66:67], v[68:69], v[66:67]
	s_waitcnt lgkmcnt(1)
	v_pk_mul_f32 v[90:91], v[32:33], v[86:87]
	v_mov_b32_dpp v68, v66 row_shr:2 row_mask:0xf bank_mask:0xf bound_ctrl:1
	v_mov_b32_dpp v69, v67 row_shr:2 row_mask:0xf bank_mask:0xf bound_ctrl:1
	s_waitcnt lgkmcnt(0)
; #define SSM_SCAN_STEP(D, SQ) { _Pragma("unroll") for (int r = 0; r < 4; ++r) { \
;                     const float sr = dppf<DPP_SHR(D)>(Er[r]), si = dppf<DPP_SHR(D)>(Ei[r]); \
;                     Er[r] += mr[r] * sr - mi[r] * si; Ei[r] += mr[r] * si + mi[r] * sr; \
;                     if (SQ) { const float nr = mr[r] * mr[r] - mi[r] * mi[r], ni = 2.f * mr[r] * mi[r]; mr[r] = nr; mi[r] = ni; } } }
; template <bool PASS2>
; __device__ __forceinline__ void ssm_phase(const Params& p, const Frame& F0) {
;     ...
;             for (int i = 0; i < 4; ++i) {
;                 __builtin_amdgcn_sched_barrier(0);
;                 f32x4 Er = (f32x4){0.f, 0.f, 0.f, 0.f}, Ei = Er;
; #pragma unroll
;                 for (int ks = 0; ks < 4; ++ks) { Er = __builtin_amdgcn_mfma_f32_16x16x32_bf16(frag[(i * 4 + ks) * 64], uf[ks], Er, 0, 0, 0);
;                                                  Ei = __builtin_amdgcn_mfma_f32_16x16x32_bf16(frag[((i + 4) * 4 + ks) * 64], uf[ks], Ei, 0, 0, 0); }
;                 const f32x4 ma = m1t[8 * i], mb = m1t[8 * i + 1];
;                 float mr[4] = {ma[0], ma[2], mb[0], mb[2]}, mi[4] = {ma[1], ma[3], mb[1], mb[3]};
;                 float hr[4], hi[4];
; #pragma unroll
;                 for (int r = 0; r < 4; ++r) { hr[r] = dppf<DPP_ROR(1)>(xs[i][r]); hi[r] = dppf<DPP_ROR(1)>(xs[i + 4][r]);
;                     if (j == 0) { Er[r] += mr[r] * hr[r] - mi[r] * hi[r]; Ei[r] += mr[r] * hi[r] + mi[r] * hr[r]; } }
;     ...
;                 SSM_SCAN_STEP(1, 1) SSM_SCAN_STEP(2, 1) SSM_SCAN_STEP(4, 1) SSM_SCAN_STEP(8, 0)
	v_pk_mul_f32 v[78:79], v[34:35], v[86:87]
	v_pk_fma_f32 v[34:35], v[34:35], v[68:69], v[90:91]
	v_pk_fma_f32 v[32:33], v[32:33], v[68:69], v[78:79] neg_lo:[0,0,1] neg_hi:[0,0,1]
	v_pk_add_f32 v[34:35], v[84:85], v[34:35]
	v_pk_add_f32 v[32:33], v[66:67], v[32:33]
	s_nop 0
	v_mov_b32_dpp v68, v34 row_shr:4 row_mask:0xf bank_mask:0xf bound_ctrl:1
	v_mov_b32_dpp v69, v35 row_shr:4 row_mask:0xf bank_mask:0xf bound_ctrl:1
	v_mov_b32_dpp v66, v32 row_shr:4 row_mask:0xf bank_mask:0xf bound_ctrl:1
	v_mov_b32_dpp v67, v33 row_shr:4 row_mask:0xf bank_mask:0xf bound_ctrl:1
	v_pk_mul_f32 v[78:79], v[94:95], v[68:69]
	v_pk_mul_f32 v[68:69], v[92:93], v[68:69]
	v_pk_fma_f32 v[78:79], v[92:93], v[66:67], v[78:79] neg_lo:[0,0,1] neg_hi:[0,0,1]
	v_pk_fma_f32 v[66:67], v[94:95], v[66:67], v[68:69]
	v_pk_add_f32 v[34:35], v[34:35], v[66:67]
	v_pk_add_f32 v[32:33], v[32:33], v[78:79]
	s_nop 0
	v_mov_b32_dpp v78, v34 row_shr:8 row_mask:0xf bank_mask:0xf bound_ctrl:1
	v_mov_b32_dpp v79, v35 row_shr:8 row_mask:0xf bank_mask:0xf bound_ctrl:1
	v_mov_b32_dpp v66, v32 row_shr:8 row_mask:0xf bank_mask:0xf bound_ctrl:1
	v_mov_b32_dpp v67, v33 row_shr:8 row_mask:0xf bank_mask:0xf bound_ctrl:1
	v_pk_mul_f32 v[68:69], v[98:99], v[78:79]
	s_nop 0
	v_pk_fma_f32 v[68:69], v[96:97], v[66:67], v[68:69] neg_lo:[0,0,1] neg_hi:[0,0,1]
	s_nop 0
	v_pk_add_f32 v[68:69], v[32:33], v[68:69]
	v_pk_mul_f32 v[32:33], v[96:97], v[78:79]
	s_nop 0
	v_pk_fma_f32 v[32:33], v[98:99], v[66:67], v[32:33]
	s_nop 0
	v_pk_add_f32 v[66:67], v[34:35], v[32:33]
	v_mov_b32_dpp v79, v54 row_ror:1 row_mask:0xf bank_mask:0xf bound_ctrl:1
	v_mov_b32_dpp v78, v52 row_ror:1 row_mask:0xf bank_mask:0xf bound_ctrl:1
	v_mov_b32_dpp v55, v55 row_ror:1 row_mask:0xf bank_mask:0xf bound_ctrl:1
	v_mov_b32_dpp v54, v53 row_ror:1 row_mask:0xf bank_mask:0xf bound_ctrl:1
	v_mfma_f32_16x16x32_bf16 v[32:35], v[162:165], v[28:31], 0
	v_mfma_f32_16x16x32_bf16 v[32:35], v[166:169], v[24:27], v[32:35]
	v_mfma_f32_16x16x32_bf16 v[82:85], v[228:231], v[28:31], 0
	v_mfma_f32_16x16x32_bf16 v[82:85], v[232:235], v[24:27], v[82:85]
	v_mfma_f32_16x16x32_bf16 v[32:35], v[170:173], v[20:23], v[32:35]
	v_mfma_f32_16x16x32_bf16 v[82:85], v[236:239], v[20:23], v[82:85]
	v_mfma_f32_16x16x32_bf16 v[86:89], v[174:177], v[16:19], v[32:35]
	s_nop 2
	v_mfma_f32_16x16x32_bf16 v[82:85], v[240:243], v[16:19], v[82:85]
	ds_read_b128 v[90:93], v109 offset:256
	s_nop 0
	ds_read_b128 v[32:35], v109 offset:272
	ds_read_b128 v[100:103], v109 offset:1280
	ds_read_b128 v[110:113], v109 offset:1792
	s_waitcnt lgkmcnt(3)
	v_pk_mul_f32 v[94:95], v[90:91], v[78:79] op_sel:[0,1] op_sel_hi:[1,0]
	s_nop 0
	v_sub_f32_e32 v52, v94, v95
	v_pk_mul_f32 v[78:79], v[90:91], v[78:79]
	v_add_f32_e32 v81, v86, v52
	v_add_f32_e32 v52, v79, v78
	v_add_f32_e32 v78, v82, v52
	v_pk_mul_f32 v[52:53], v[92:93], v[54:55] op_sel:[0,1] op_sel_hi:[1,0]
	v_mov_b32_e32 v96, v91
	v_sub_f32_e32 v52, v52, v53
	v_add_f32_e32 v79, v52, v87
	v_pk_mul_f32 v[52:53], v[92:93], v[54:55]
	v_mov_b32_e32 v97, v93
	v_add_f32_e32 v52, v53, v52
	v_add_f32_e32 v94, v52, v83
	v_mov_b32_dpp v53, v58 row_ror:1 row_mask:0xf bank_mask:0xf bound_ctrl:1
	v_mov_b32_dpp v52, v56 row_ror:1 row_mask:0xf bank_mask:0xf bound_ctrl:1
	s_waitcnt lgkmcnt(2)
	v_pk_mul_f32 v[54:55], v[32:33], v[52:53] op_sel:[0,1] op_sel_hi:[1,0]
	v_pk_mul_f32 v[52:53], v[32:33], v[52:53]
	v_sub_f32_e32 v54, v54, v55
	v_add_f32_e32 v52, v53, v52
	v_add_f32_e32 v58, v52, v84
	v_mov_b32_dpp v53, v59 row_ror:1 row_mask:0xf bank_mask:0xf bound_ctrl:1
	v_mov_b32_dpp v52, v57 row_ror:1 row_mask:0xf bank_mask:0xf bound_ctrl:1
	v_add_f32_e32 v56, v54, v88
	v_pk_mul_f32 v[54:55], v[34:35], v[52:53] op_sel:[0,1] op_sel_hi:[1,0]
	v_pk_mul_f32 v[52:53], v[34:35], v[52:53]
	v_sub_f32_e32 v54, v54, v55
	v_add_f32_e32 v52, v53, v52
	v_add_f32_e32 v52, v52, v85
	v_add_f32_e32 v54, v54, v89
	v_cndmask_b32_e64 v85, v85, v52, s[6:7]
	v_cndmask_b32_e64 v53, v83, v94, s[6:7]
	v_cndmask_b32_e64 v52, v82, v78, s[6:7]
	v_cndmask_b32_e64 v57, v89, v54, s[6:7]
	v_cndmask_b32_e64 v56, v88, v56, s[6:7]
	v_cndmask_b32_e64 v55, v87, v79, s[6:7]
	v_cndmask_b32_e64 v54, v86, v81, s[6:7]
	v_mov_b32_dpp v86, v52 row_shr:1 row_mask:0xf bank_mask:0xf bound_ctrl:1
	v_mov_b32_dpp v87, v53 row_shr:1 row_mask:0xf bank_mask:0xf bound_ctrl:1
	v_mov_b32_e32 v88, v90
	v_mov_b32_e32 v89, v92
	ds_read_b128 v[90:93], v109 offset:768
	v_mov_b32_dpp v82, v54 row_shr:1 row_mask:0xf bank_mask:0xf bound_ctrl:1
	v_mov_b32_dpp v83, v55 row_shr:1 row_mask:0xf bank_mask:0xf bound_ctrl:1
	v_pk_mul_f32 v[94:95], v[88:89], v[86:87]
	v_pk_fma_f32 v[94:95], v[96:97], v[82:83], v[94:95]
	v_pk_add_f32 v[52:53], v[94:95], v[52:53]
	v_pk_mul_f32 v[86:87], v[96:97], v[86:87]
	v_pk_fma_f32 v[82:83], v[88:89], v[82:83], v[86:87] neg_lo:[0,0,1] neg_hi:[0,0,1]
	v_mov_b32_dpp v94, v52 row_shr:2 row_mask:0xf bank_mask:0xf bound_ctrl:1
	v_mov_b32_dpp v95, v53 row_shr:2 row_mask:0xf bank_mask:0xf bound_ctrl:1
	v_pk_add_f32 v[54:55], v[82:83], v[54:55]
	s_waitcnt lgkmcnt(0)
; #define SSM_SCAN_STEP(D, SQ) { _Pragma("unroll") for (int r = 0; r < 4; ++r) { \
;                     const float sr = dppf<DPP_SHR(D)>(Er[r]), si = dppf<DPP_SHR(D)>(Ei[r]); \
;                     Er[r] += mr[r] * sr - mi[r] * si; Ei[r] += mr[r] * si + mi[r] * sr; \
;                     if (SQ) { const float nr = mr[r] * mr[r] - mi[r] * mi[r], ni = 2.f * mr[r] * mi[r]; mr[r] = nr; mi[r] = ni; } } }
; template <bool PASS2>
; __device__ __forceinline__ void ssm_phase(const Params& p, const Frame& F0) {
;     ...
;             for (int i = 0; i < 4; ++i) {
;                 __builtin_amdgcn_sched_barrier(0);
;                 f32x4 Er = (f32x4){0.f, 0.f, 0.f, 0.f}, Ei = Er;
; #pragma unroll
;                 for (int ks = 0; ks < 4; ++ks) { Er = __builtin_amdgcn_mfma_f32_16x16x32_bf16(frag[(i * 4 + ks) * 64], uf[ks], Er, 0, 0, 0);
;                                                  Ei = __builtin_amdgcn_mfma_f32_16x16x32_bf16(frag[((i + 4) * 4 + ks) * 64], uf[ks], Ei, 0, 0, 0); }
;                 const f32x4 ma = m1t[8 * i], mb = m1t[8 * i + 1];
;                 float mr[4] = {ma[0], ma[2], mb[0], mb[2]}, mi[4] = {ma[1], ma[3], mb[1], mb[3]};
;                 float hr[4], hi[4];
; #pragma unroll
;                 for (int r = 0; r < 4; ++r) { hr[r] = dppf<DPP_ROR(1)>(xs[i][r]); hi[r] = dppf<DPP_ROR(1)>(xs[i + 4][r]);
;                     if (j == 0) { Er[r] += mr[r] * hr[r] - mi[r] * hi[r]; Ei[r] += mr[r] * hi[r] + mi[r] * hr[r]; } }
;     ...
;                 SSM_SCAN_STEP(1, 1) SSM_SCAN_STEP(2, 1) SSM_SCAN_STEP(4, 1) SSM_SCAN_STEP(8, 0)
	v_pk_mul_f32 v[98:99], v[90:91], v[94:95]
	v_pk_mul_f32 v[86:87], v[92:93], v[94:95]
	v_mov_b32_dpp v82, v54 row_shr:2 row_mask:0xf bank_mask:0xf bound_ctrl:1
	v_mov_b32_dpp v83, v55 row_shr:2 row_mask:0xf bank_mask:0xf bound_ctrl:1
	v_pk_fma_f32 v[86:87], v[90:91], v[82:83], v[86:87] neg_lo:[0,0,1] neg_hi:[0,0,1]
	v_pk_fma_f32 v[82:83], v[92:93], v[82:83], v[98:99]
	ds_read_b128 v[92:95], v109 offset:1296
	ds_read_b128 v[96:99], v109 offset:1808
	v_pk_add_f32 v[52:53], v[52:53], v[82:83]
	v_pk_add_f32 v[54:55], v[86:87], v[54:55]
	s_nop 0
	v_mov_b32_dpp v86, v52 row_shr:4 row_mask:0xf bank_mask:0xf bound_ctrl:1
	v_mov_b32_dpp v87, v53 row_shr:4 row_mask:0xf bank_mask:0xf bound_ctrl:1
	v_mov_b32_dpp v82, v54 row_shr:4 row_mask:0xf bank_mask:0xf bound_ctrl:1
	v_mov_b32_dpp v83, v55 row_shr:4 row_mask:0xf bank_mask:0xf bound_ctrl:1
	v_pk_mul_f32 v[88:89], v[102:103], v[86:87]
	v_pk_mul_f32 v[86:87], v[100:101], v[86:87]
	v_pk_fma_f32 v[88:89], v[100:101], v[82:83], v[88:89] neg_lo:[0,0,1] neg_hi:[0,0,1]
	v_pk_fma_f32 v[82:83], v[102:103], v[82:83], v[86:87]
	v_pk_add_f32 v[52:53], v[52:53], v[82:83]
	v_pk_add_f32 v[54:55], v[54:55], v[88:89]
	s_nop 0
	v_mov_b32_dpp v86, v52 row_shr:8 row_mask:0xf bank_mask:0xf bound_ctrl:1
	v_mov_b32_dpp v87, v53 row_shr:8 row_mask:0xf bank_mask:0xf bound_ctrl:1
	v_mov_b32_dpp v82, v54 row_shr:8 row_mask:0xf bank_mask:0xf bound_ctrl:1
	v_mov_b32_dpp v83, v55 row_shr:8 row_mask:0xf bank_mask:0xf bound_ctrl:1
	v_pk_mul_f32 v[88:89], v[112:113], v[86:87]
	v_pk_mul_f32 v[86:87], v[110:111], v[86:87]
	v_cndmask_b32_e64 v84, v84, v58, s[6:7]
	v_pk_fma_f32 v[88:89], v[110:111], v[82:83], v[88:89] neg_lo:[0,0,1] neg_hi:[0,0,1]
	v_pk_fma_f32 v[82:83], v[112:113], v[82:83], v[86:87]
	v_mov_b32_dpp v78, v84 row_shr:1 row_mask:0xf bank_mask:0xf bound_ctrl:1
	v_mov_b32_dpp v79, v85 row_shr:1 row_mask:0xf bank_mask:0xf bound_ctrl:1
	v_pk_add_f32 v[52:53], v[52:53], v[82:83]
	v_mov_b32_e32 v82, v32
	v_mov_b32_e32 v83, v34
	v_mov_b32_dpp v58, v56 row_shr:1 row_mask:0xf bank_mask:0xf bound_ctrl:1
	v_mov_b32_dpp v59, v57 row_shr:1 row_mask:0xf bank_mask:0xf bound_ctrl:1
	v_pk_add_f32 v[54:55], v[54:55], v[88:89]
	v_pk_mul_f32 v[86:87], v[82:83], v[78:79]
	v_mov_b32_e32 v88, v33
	ds_read_b64 v[32:33], v109 offset:784
	v_mov_b32_e32 v89, v35
	ds_read_b64 v[34:35], v109 offset:792
	v_pk_fma_f32 v[86:87], v[88:89], v[58:59], v[86:87]
	v_pk_mul_f32 v[78:79], v[88:89], v[78:79]
	v_pk_add_f32 v[84:85], v[86:87], v[84:85]
	v_pk_fma_f32 v[58:59], v[82:83], v[58:59], v[78:79] neg_lo:[0,0,1] neg_hi:[0,0,1]
	s_nop 0
	v_mov_b32_dpp v86, v84 row_shr:2 row_mask:0xf bank_mask:0xf bound_ctrl:1
	v_mov_b32_dpp v87, v85 row_shr:2 row_mask:0xf bank_mask:0xf bound_ctrl:1
	v_pk_add_f32 v[56:57], v[58:59], v[56:57]
	s_waitcnt lgkmcnt(1)
	v_pk_mul_f32 v[90:91], v[32:33], v[86:87]
	v_mov_b32_dpp v58, v56 row_shr:2 row_mask:0xf bank_mask:0xf bound_ctrl:1
	v_mov_b32_dpp v59, v57 row_shr:2 row_mask:0xf bank_mask:0xf bound_ctrl:1
	s_waitcnt lgkmcnt(0)
	v_pk_mul_f32 v[78:79], v[34:35], v[86:87]
	v_pk_fma_f32 v[34:35], v[34:35], v[58:59], v[90:91]
	v_pk_fma_f32 v[32:33], v[32:33], v[58:59], v[78:79] neg_lo:[0,0,1] neg_hi:[0,0,1]
	v_pk_add_f32 v[34:35], v[84:85], v[34:35]
	v_pk_add_f32 v[32:33], v[56:57], v[32:33]
	s_nop 0
	v_mov_b32_dpp v58, v34 row_shr:4 row_mask:0xf bank_mask:0xf bound_ctrl:1
	v_mov_b32_dpp v59, v35 row_shr:4 row_mask:0xf bank_mask:0xf bound_ctrl:1
	v_mov_b32_dpp v56, v32 row_shr:4 row_mask:0xf bank_mask:0xf bound_ctrl:1
	v_mov_b32_dpp v57, v33 row_shr:4 row_mask:0xf bank_mask:0xf bound_ctrl:1
	v_pk_mul_f32 v[78:79], v[94:95], v[58:59]
	v_pk_mul_f32 v[58:59], v[92:93], v[58:59]
	v_pk_fma_f32 v[78:79], v[92:93], v[56:57], v[78:79] neg_lo:[0,0,1] neg_hi:[0,0,1]
	v_pk_fma_f32 v[56:57], v[94:95], v[56:57], v[58:59]
	v_pk_add_f32 v[34:35], v[34:35], v[56:57]
	v_pk_add_f32 v[32:33], v[32:33], v[78:79]
	s_nop 0
	v_mov_b32_dpp v78, v34 row_shr:8 row_mask:0xf bank_mask:0xf bound_ctrl:1
	v_mov_b32_dpp v79, v35 row_shr:8 row_mask:0xf bank_mask:0xf bound_ctrl:1
	v_mov_b32_dpp v56, v32 row_shr:8 row_mask:0xf bank_mask:0xf bound_ctrl:1
	v_mov_b32_dpp v57, v33 row_shr:8 row_mask:0xf bank_mask:0xf bound_ctrl:1
	v_pk_mul_f32 v[58:59], v[98:99], v[78:79]
	s_nop 0
	v_pk_fma_f32 v[58:59], v[96:97], v[56:57], v[58:59] neg_lo:[0,0,1] neg_hi:[0,0,1]
	s_nop 0
	v_pk_add_f32 v[58:59], v[32:33], v[58:59]
	v_pk_mul_f32 v[32:33], v[96:97], v[78:79]
	s_nop 0
	v_pk_fma_f32 v[32:33], v[98:99], v[56:57], v[32:33]
	s_nop 0
	v_pk_add_f32 v[56:57], v[34:35], v[32:33]
	v_mfma_f32_16x16x32_bf16 v[32:35], v[178:181], v[28:31], 0
	v_mfma_f32_16x16x32_bf16 v[28:31], v[244:247], v[28:31], 0
	v_mfma_f32_16x16x32_bf16 v[32:35], v[182:185], v[24:27], v[32:35]
	v_mfma_f32_16x16x32_bf16 v[24:27], v[248:251], v[24:27], v[28:31]
	s_nop 2
	v_mfma_f32_16x16x32_bf16 v[28:31], v[186:189], v[20:23], v[32:35]
	s_nop 2
	v_mfma_f32_16x16x32_bf16 v[20:23], v[114:117], v[20:23], v[24:27]
	s_nop 2
	v_mov_b32_dpp v33, v46 row_ror:1 row_mask:0xf bank_mask:0xf bound_ctrl:1
	v_mov_b32_dpp v32, v44 row_ror:1 row_mask:0xf bank_mask:0xf bound_ctrl:1
	v_mfma_f32_16x16x32_bf16 v[24:27], v[190:193], v[16:19], v[28:31]
	s_nop 2
	v_mfma_f32_16x16x32_bf16 v[20:23], v[118:121], v[16:19], v[20:23]
	ds_read_b128 v[28:31], v109 offset:384
	ds_read_b128 v[16:19], v109 offset:400
	ds_read_b128 v[84:87], v109 offset:1408
	ds_read_b128 v[88:91], v109 offset:1920
	s_waitcnt lgkmcnt(3)
; #define SSM_SCAN_STEP(D, SQ) { _Pragma("unroll") for (int r = 0; r < 4; ++r) { \
;                     const float sr = dppf<DPP_SHR(D)>(Er[r]), si = dppf<DPP_SHR(D)>(Ei[r]); \
;                     Er[r] += mr[r] * sr - mi[r] * si; Ei[r] += mr[r] * si + mi[r] * sr; \
;                     if (SQ) { const float nr = mr[r] * mr[r] - mi[r] * mi[r], ni = 2.f * mr[r] * mi[r]; mr[r] = nr; mi[r] = ni; } } }
; template <bool PASS2>
; __device__ __forceinline__ void ssm_phase(const Params& p, const Frame& F0) {
;     ...
;             for (int i = 0; i < 4; ++i) {
;                 __builtin_amdgcn_sched_barrier(0);
;                 f32x4 Er = (f32x4){0.f, 0.f, 0.f, 0.f}, Ei = Er;
; #pragma unroll
;                 for (int ks = 0; ks < 4; ++ks) { Er = __builtin_amdgcn_mfma_f32_16x16x32_bf16(frag[(i * 4 + ks) * 64], uf[ks], Er, 0, 0, 0);
;                                                  Ei = __builtin_amdgcn_mfma_f32_16x16x32_bf16(frag[((i + 4) * 4 + ks) * 64], uf[ks], Ei, 0, 0, 0); }
;                 const f32x4 ma = m1t[8 * i], mb = m1t[8 * i + 1];
;                 float mr[4] = {ma[0], ma[2], mb[0], mb[2]}, mi[4] = {ma[1], ma[3], mb[1], mb[3]};
;                 float hr[4], hi[4];
; #pragma unroll
;                 for (int r = 0; r < 4; ++r) { hr[r] = dppf<DPP_ROR(1)>(xs[i][r]); hi[r] = dppf<DPP_ROR(1)>(xs[i + 4][r]);
;                     if (j == 0) { Er[r] += mr[r] * hr[r] - mi[r] * hi[r]; Ei[r] += mr[r] * hi[r] + mi[r] * hr[r]; } }
;     ...
;                 SSM_SCAN_STEP(1, 1) SSM_SCAN_STEP(2, 1) SSM_SCAN_STEP(4, 1) SSM_SCAN_STEP(8, 0)
	v_pk_mul_f32 v[34:35], v[28:29], v[32:33] op_sel:[0,1] op_sel_hi:[1,0]
	v_pk_mul_f32 v[32:33], v[28:29], v[32:33]
	v_sub_f32_e32 v34, v34, v35
	v_add_f32_e32 v32, v33, v32
	s_nop 0
	v_add_f32_e32 v46, v20, v32
	v_mov_b32_dpp v33, v47 row_ror:1 row_mask:0xf bank_mask:0xf bound_ctrl:1
	v_mov_b32_dpp v32, v45 row_ror:1 row_mask:0xf bank_mask:0xf bound_ctrl:1
	v_add_f32_e32 v44, v24, v34
	v_pk_mul_f32 v[34:35], v[30:31], v[32:33] op_sel:[0,1] op_sel_hi:[1,0]
	v_pk_mul_f32 v[32:33], v[30:31], v[32:33]
	v_sub_f32_e32 v34, v34, v35
	v_add_f32_e32 v32, v33, v32
	v_add_f32_e32 v47, v32, v21
	v_mov_b32_dpp v33, v50 row_ror:1 row_mask:0xf bank_mask:0xf bound_ctrl:1
	v_mov_b32_dpp v32, v48 row_ror:1 row_mask:0xf bank_mask:0xf bound_ctrl:1
	v_add_f32_e32 v45, v34, v25
	s_waitcnt lgkmcnt(2)
	v_pk_mul_f32 v[34:35], v[16:17], v[32:33] op_sel:[0,1] op_sel_hi:[1,0]
	v_pk_mul_f32 v[32:33], v[16:17], v[32:33]
	v_sub_f32_e32 v34, v34, v35
	v_add_f32_e32 v32, v33, v32
	v_add_f32_e32 v50, v32, v22
	v_mov_b32_dpp v33, v51 row_ror:1 row_mask:0xf bank_mask:0xf bound_ctrl:1
	v_mov_b32_dpp v32, v49 row_ror:1 row_mask:0xf bank_mask:0xf bound_ctrl:1
	v_add_f32_e32 v48, v34, v26
	v_pk_mul_f32 v[34:35], v[18:19], v[32:33] op_sel:[0,1] op_sel_hi:[1,0]
	v_pk_mul_f32 v[32:33], v[18:19], v[32:33]
	v_sub_f32_e32 v34, v34, v35
	v_add_f32_e32 v49, v34, v27
	v_add_f32_e32 v32, v33, v32
	v_cndmask_b32_e64 v35, v21, v47, s[6:7]
	v_cndmask_b32_e64 v34, v20, v46, s[6:7]
	v_add_f32_e32 v32, v32, v23
	v_cndmask_b32_e64 v21, v27, v49, s[6:7]
	v_cndmask_b32_e64 v20, v26, v48, s[6:7]
	v_cndmask_b32_e64 v27, v25, v45, s[6:7]
	v_cndmask_b32_e64 v26, v24, v44, s[6:7]
	v_mov_b32_dpp v46, v34 row_shr:1 row_mask:0xf bank_mask:0xf bound_ctrl:1
	v_mov_b32_dpp v47, v35 row_shr:1 row_mask:0xf bank_mask:0xf bound_ctrl:1
	v_mov_b32_e32 v48, v28
	v_mov_b32_e32 v49, v30
	v_cndmask_b32_e64 v33, v23, v32, s[6:7]
	v_cndmask_b32_e64 v32, v22, v50, s[6:7]
	v_mov_b32_dpp v44, v26 row_shr:1 row_mask:0xf bank_mask:0xf bound_ctrl:1
	v_mov_b32_dpp v45, v27 row_shr:1 row_mask:0xf bank_mask:0xf bound_ctrl:1
	v_pk_mul_f32 v[50:51], v[48:49], v[46:47]
	v_mov_b32_e32 v78, v29
	ds_read_b64 v[28:29], v109 offset:896
	v_mov_b32_e32 v79, v31
	ds_read_b64 v[30:31], v109 offset:904
	v_pk_fma_f32 v[50:51], v[78:79], v[44:45], v[50:51]
	v_pk_add_f32 v[34:35], v[50:51], v[34:35]
	v_pk_mul_f32 v[46:47], v[78:79], v[46:47]
	ds_read_b64 v[78:79], v109 offset:1936
	v_pk_fma_f32 v[44:45], v[48:49], v[44:45], v[46:47] neg_lo:[0,0,1] neg_hi:[0,0,1]
	v_mov_b32_dpp v50, v34 row_shr:2 row_mask:0xf bank_mask:0xf bound_ctrl:1
	v_mov_b32_dpp v51, v35 row_shr:2 row_mask:0xf bank_mask:0xf bound_ctrl:1
	v_pk_add_f32 v[26:27], v[44:45], v[26:27]
	s_waitcnt lgkmcnt(1)
	v_pk_mul_f32 v[46:47], v[30:31], v[50:51]
	v_mov_b32_dpp v44, v26 row_shr:2 row_mask:0xf bank_mask:0xf bound_ctrl:1
	v_mov_b32_dpp v45, v27 row_shr:2 row_mask:0xf bank_mask:0xf bound_ctrl:1
	v_pk_mul_f32 v[82:83], v[28:29], v[50:51]
	ds_read_b128 v[48:51], v109 offset:1424
	v_pk_fma_f32 v[28:29], v[28:29], v[44:45], v[46:47] neg_lo:[0,0,1] neg_hi:[0,0,1]
	v_pk_add_f32 v[26:27], v[28:29], v[26:27]
	v_pk_fma_f32 v[28:29], v[30:31], v[44:45], v[82:83]
	ds_read_b64 v[82:83], v109 offset:1944
	v_pk_add_f32 v[28:29], v[34:35], v[28:29]
	v_mov_b32_dpp v30, v26 row_shr:4 row_mask:0xf bank_mask:0xf bound_ctrl:1
	v_mov_b32_dpp v31, v27 row_shr:4 row_mask:0xf bank_mask:0xf bound_ctrl:1
	v_mov_b32_dpp v34, v28 row_shr:4 row_mask:0xf bank_mask:0xf bound_ctrl:1
	v_mov_b32_dpp v35, v29 row_shr:4 row_mask:0xf bank_mask:0xf bound_ctrl:1
	v_pk_mul_f32 v[44:45], v[86:87], v[34:35]
	v_pk_mul_f32 v[34:35], v[84:85], v[34:35]
	v_pk_fma_f32 v[44:45], v[84:85], v[30:31], v[44:45] neg_lo:[0,0,1] neg_hi:[0,0,1]
	v_pk_fma_f32 v[30:31], v[86:87], v[30:31], v[34:35]
	v_pk_add_f32 v[28:29], v[28:29], v[30:31]
	v_pk_add_f32 v[26:27], v[26:27], v[44:45]
	s_nop 0
	v_mov_b32_dpp v34, v28 row_shr:8 row_mask:0xf bank_mask:0xf bound_ctrl:1
	v_mov_b32_dpp v35, v29 row_shr:8 row_mask:0xf bank_mask:0xf bound_ctrl:1
	v_mov_b32_dpp v30, v26 row_shr:8 row_mask:0xf bank_mask:0xf bound_ctrl:1
	v_mov_b32_dpp v31, v27 row_shr:8 row_mask:0xf bank_mask:0xf bound_ctrl:1
	v_pk_mul_f32 v[44:45], v[90:91], v[34:35]
	v_mov_b32_dpp v24, v32 row_shr:1 row_mask:0xf bank_mask:0xf bound_ctrl:1
	v_pk_fma_f32 v[44:45], v[88:89], v[30:31], v[44:45] neg_lo:[0,0,1] neg_hi:[0,0,1]
	v_mov_b32_dpp v25, v33 row_shr:1 row_mask:0xf bank_mask:0xf bound_ctrl:1
	v_pk_add_f32 v[46:47], v[26:27], v[44:45]
	v_pk_mul_f32 v[26:27], v[88:89], v[34:35]
	v_mov_b32_dpp v22, v20 row_shr:1 row_mask:0xf bank_mask:0xf bound_ctrl:1
	v_pk_fma_f32 v[26:27], v[90:91], v[30:31], v[26:27]
	v_mov_b32_dpp v23, v21 row_shr:1 row_mask:0xf bank_mask:0xf bound_ctrl:1
	v_pk_add_f32 v[44:45], v[28:29], v[26:27]
	v_mov_b32_e32 v26, v16
	v_mov_b32_e32 v27, v18
	v_pk_mul_f32 v[28:29], v[26:27], v[24:25]
	v_mov_b32_e32 v30, v17
	ds_read_b64 v[16:17], v109 offset:912
	v_mov_b32_e32 v31, v19
	ds_read_b64 v[18:19], v109 offset:920
	v_pk_fma_f32 v[28:29], v[30:31], v[22:23], v[28:29]
	v_pk_mul_f32 v[24:25], v[30:31], v[24:25]
	v_pk_add_f32 v[28:29], v[28:29], v[32:33]
	v_pk_fma_f32 v[22:23], v[26:27], v[22:23], v[24:25] neg_lo:[0,0,1] neg_hi:[0,0,1]
	s_nop 0
	v_mov_b32_dpp v32, v28 row_shr:2 row_mask:0xf bank_mask:0xf bound_ctrl:1
	v_mov_b32_dpp v33, v29 row_shr:2 row_mask:0xf bank_mask:0xf bound_ctrl:1
	v_pk_add_f32 v[20:21], v[22:23], v[20:21]
	s_waitcnt lgkmcnt(1)
	v_pk_mul_f32 v[34:35], v[16:17], v[32:33]
	v_mov_b32_dpp v22, v20 row_shr:2 row_mask:0xf bank_mask:0xf bound_ctrl:1
	v_mov_b32_dpp v23, v21 row_shr:2 row_mask:0xf bank_mask:0xf bound_ctrl:1
	s_waitcnt lgkmcnt(0)
; #define SSM_SCAN_STEP(D, SQ) { _Pragma("unroll") for (int r = 0; r < 4; ++r) { \
;                     const float sr = dppf<DPP_SHR(D)>(Er[r]), si = dppf<DPP_SHR(D)>(Ei[r]); \
;                     Er[r] += mr[r] * sr - mi[r] * si; Ei[r] += mr[r] * si + mi[r] * sr; \
;                     if (SQ) { const float nr = mr[r] * mr[r] - mi[r] * mi[r], ni = 2.f * mr[r] * mi[r]; mr[r] = nr; mi[r] = ni; } } }
; template <bool PASS2>
; __device__ __forceinline__ void ssm_phase(const Params& p, const Frame& F0) {
;     ...
;         for (int cc = 0; cc < nch; ++cc) {
;             asm volatile("" ::: "memory");
;             const bool samp = (cc == 4);
;             const int row0 = SSM_ROW0(cc), nsub = SSM_NSUB(cc), js = jsamp;
;             if (samp) {
; #pragma unroll
;                 for (int i = 0; i < 4; ++i) { xs[i] = *(const f32x4*)(p.in[2] + (size_t)(js * NG + g) * 64 + 16 * i + 4 * gq); xs[i + 4] = *(const f32x4*)(p.in[3] + (size_t)(js * NG + g) * 64 + 16 * i + 4 * gq); } }
;             if (cc + 1 < nch) SSM_LOAD_U(ufn, uwn, cc + 1)
;             unsigned hw[4][4];
; #pragma unroll
;             for (int i = 0; i < 4; ++i) {
;                 __builtin_amdgcn_sched_barrier(0);
;                 f32x4 Er = (f32x4){0.f, 0.f, 0.f, 0.f}, Ei = Er;
; #pragma unroll
;                 for (int ks = 0; ks < 4; ++ks) { Er = __builtin_amdgcn_mfma_f32_16x16x32_bf16(frag[(i * 4 + ks) * 64], uf[ks], Er, 0, 0, 0);
;                                                  Ei = __builtin_amdgcn_mfma_f32_16x16x32_bf16(frag[((i + 4) * 4 + ks) * 64], uf[ks], Ei, 0, 0, 0); }
;                 const f32x4 ma = m1t[8 * i], mb = m1t[8 * i + 1];
;                 float mr[4] = {ma[0], ma[2], mb[0], mb[2]}, mi[4] = {ma[1], ma[3], mb[1], mb[3]};
;                 float hr[4], hi[4];
; #pragma unroll
;                 for (int r = 0; r < 4; ++r) { hr[r] = dppf<DPP_ROR(1)>(xs[i][r]); hi[r] = dppf<DPP_ROR(1)>(xs[i + 4][r]);
;                     if (j == 0) { Er[r] += mr[r] * hr[r] - mi[r] * hi[r]; Ei[r] += mr[r] * hi[r] + mi[r] * hr[r]; } }
;     ...
;                 SSM_SCAN_STEP(1, 1) SSM_SCAN_STEP(2, 1) SSM_SCAN_STEP(4, 1) SSM_SCAN_STEP(8, 0)
	v_pk_mul_f32 v[24:25], v[18:19], v[32:33]
	v_pk_fma_f32 v[18:19], v[18:19], v[22:23], v[34:35]
	v_pk_fma_f32 v[16:17], v[16:17], v[22:23], v[24:25] neg_lo:[0,0,1] neg_hi:[0,0,1]
	v_pk_add_f32 v[18:19], v[28:29], v[18:19]
	v_pk_add_f32 v[16:17], v[20:21], v[16:17]
	s_nop 0
	v_mov_b32_dpp v22, v18 row_shr:4 row_mask:0xf bank_mask:0xf bound_ctrl:1
	v_mov_b32_dpp v23, v19 row_shr:4 row_mask:0xf bank_mask:0xf bound_ctrl:1
	v_mov_b32_dpp v20, v16 row_shr:4 row_mask:0xf bank_mask:0xf bound_ctrl:1
	v_mov_b32_dpp v21, v17 row_shr:4 row_mask:0xf bank_mask:0xf bound_ctrl:1
	v_pk_mul_f32 v[24:25], v[50:51], v[22:23]
	v_pk_mul_f32 v[22:23], v[48:49], v[22:23]
	v_pk_fma_f32 v[24:25], v[48:49], v[20:21], v[24:25] neg_lo:[0,0,1] neg_hi:[0,0,1]
	v_pk_fma_f32 v[20:21], v[50:51], v[20:21], v[22:23]
	v_pk_add_f32 v[18:19], v[18:19], v[20:21]
	v_pk_add_f32 v[16:17], v[16:17], v[24:25]
	s_nop 0
	v_mov_b32_dpp v22, v18 row_shr:8 row_mask:0xf bank_mask:0xf bound_ctrl:1
	v_mov_b32_dpp v23, v19 row_shr:8 row_mask:0xf bank_mask:0xf bound_ctrl:1
	v_mov_b32_dpp v20, v16 row_shr:8 row_mask:0xf bank_mask:0xf bound_ctrl:1
	v_mov_b32_dpp v21, v17 row_shr:8 row_mask:0xf bank_mask:0xf bound_ctrl:1
	v_pk_mul_f32 v[24:25], v[82:83], v[22:23]
	s_nop 0
	v_pk_fma_f32 v[24:25], v[78:79], v[20:21], v[24:25] neg_lo:[0,0,1] neg_hi:[0,0,1]
	s_nop 0
	v_pk_add_f32 v[50:51], v[16:17], v[24:25]
	v_pk_mul_f32 v[16:17], v[78:79], v[22:23]
	s_nop 0
	v_pk_fma_f32 v[16:17], v[82:83], v[20:21], v[16:17]
	s_nop 0
	v_pk_add_f32 v[48:49], v[18:19], v[16:17]
	s_addk_i32 s0, 0x80
	s_cmpk_eq_i32 s0, 0x180
	s_cbranch_scc0 .LBB0_527
	ds_read_b128 v[16:19], v105
	ds_read_b128 v[20:23], v105 offset:1024
	ds_read_b128 v[24:27], v105 offset:16384
	ds_read_b128 v[28:31], v105 offset:17408
	v_mov_b32_dpp v65, v72 row_ror:1 row_mask:0xf bank_mask:0xf bound_ctrl:1
	v_mov_b32_dpp v64, v70 row_ror:1 row_mask:0xf bank_mask:0xf bound_ctrl:1
	s_waitcnt vmcnt(3)
	s_waitcnt lgkmcnt(3)
	v_mfma_f32_16x16x32_bf16 v[16:19], v[16:19], v[12:15], 0
	s_waitcnt vmcnt(2)
	s_waitcnt lgkmcnt(2)
	v_mfma_f32_16x16x32_bf16 v[16:19], v[20:23], v[4:7], v[16:19]
	ds_read_b128 v[20:23], v105 offset:2048
	s_waitcnt lgkmcnt(2)
	v_mfma_f32_16x16x32_bf16 v[24:27], v[24:27], v[12:15], 0
	s_waitcnt lgkmcnt(1)
	v_mfma_f32_16x16x32_bf16 v[24:27], v[28:31], v[4:7], v[24:27]
	ds_read_b128 v[28:31], v105 offset:18432
	ds_read_b128 v[32:35], v105 offset:3072
	ds_read_b128 v[78:81], v105 offset:19456
	s_waitcnt vmcnt(1)
	s_waitcnt lgkmcnt(3)
	v_mfma_f32_16x16x32_bf16 v[16:19], v[20:23], v[8:11], v[16:19]
	ds_read_b128 v[20:23], v109
	ds_read_b128 v[82:85], v109 offset:16
	s_waitcnt lgkmcnt(1)
	v_mov_b32_e32 v72, v21
	v_mfma_f32_16x16x32_bf16 v[24:27], v[28:31], v[8:11], v[24:27]
	v_mul_f32_e64 v28, v20, v65
	v_mul_f32_e64 v29, v21, v64
	v_mov_b32_e32 v70, v20
	v_sub_f32_e32 v28, v28, v29
	s_waitcnt vmcnt(0)
	v_mfma_f32_16x16x32_bf16 v[16:19], v[32:35], v[0:3], v[16:19]
	v_mfma_f32_16x16x32_bf16 v[24:27], v[78:81], v[0:3], v[24:27]
	s_nop 6
	v_add_f32_e32 v32, v16, v28
	v_pk_mul_f32 v[28:29], v[20:21], v[64:65]
	ds_read_b64 v[20:21], v109 offset:512
	v_cndmask_b32_e64 v16, v16, v32, s[6:7]
	v_add_f32_e32 v28, v29, v28
	v_add_f32_e32 v33, v24, v28
	v_mov_b32_dpp v29, v73 row_ror:1 row_mask:0xf bank_mask:0xf bound_ctrl:1
	v_mov_b32_dpp v28, v71 row_ror:1 row_mask:0xf bank_mask:0xf bound_ctrl:1
	v_pk_mul_f32 v[30:31], v[22:23], v[28:29] op_sel:[0,1] op_sel_hi:[1,0]
	v_pk_mul_f32 v[28:29], v[22:23], v[28:29]
	v_sub_f32_e32 v30, v30, v31
	v_add_f32_e32 v28, v29, v28
	v_add_f32_e32 v35, v28, v25
	v_mov_b32_dpp v29, v76 row_ror:1 row_mask:0xf bank_mask:0xf bound_ctrl:1
	v_mov_b32_dpp v28, v74 row_ror:1 row_mask:0xf bank_mask:0xf bound_ctrl:1
	v_add_f32_e32 v34, v30, v17
	s_waitcnt lgkmcnt(1)
	v_pk_mul_f32 v[30:31], v[82:83], v[28:29] op_sel:[0,1] op_sel_hi:[1,0]
	v_pk_mul_f32 v[28:29], v[82:83], v[28:29]
	v_sub_f32_e32 v30, v30, v31
	v_add_f32_e32 v28, v29, v28
	v_add_f32_e32 v65, v28, v26
	v_mov_b32_dpp v29, v77 row_ror:1 row_mask:0xf bank_mask:0xf bound_ctrl:1
	v_mov_b32_dpp v28, v75 row_ror:1 row_mask:0xf bank_mask:0xf bound_ctrl:1
	v_add_f32_e32 v64, v30, v18
	v_pk_mul_f32 v[30:31], v[84:85], v[28:29] op_sel:[0,1] op_sel_hi:[1,0]
	v_pk_mul_f32 v[28:29], v[84:85], v[28:29]
	v_sub_f32_e32 v30, v30, v31
	v_add_f32_e32 v28, v29, v28
	v_cndmask_b32_e64 v25, v25, v35, s[6:7]
	v_cndmask_b32_e64 v24, v24, v33, s[6:7]
	v_add_f32_e32 v30, v30, v19
	v_add_f32_e32 v28, v28, v27
	v_cndmask_b32_e64 v17, v17, v34, s[6:7]
	v_mov_b32_dpp v32, v24 row_shr:1 row_mask:0xf bank_mask:0xf bound_ctrl:1
	v_mov_b32_dpp v33, v25 row_shr:1 row_mask:0xf bank_mask:0xf bound_ctrl:1
	v_mov_b32_e32 v73, v23
	v_cndmask_b32_e64 v29, v27, v28, s[6:7]
	v_cndmask_b32_e64 v28, v26, v65, s[6:7]
	v_cndmask_b32_e64 v27, v19, v30, s[6:7]
	v_cndmask_b32_e64 v26, v18, v64, s[6:7]
	v_mov_b32_dpp v30, v16 row_shr:1 row_mask:0xf bank_mask:0xf bound_ctrl:1
	v_mov_b32_dpp v31, v17 row_shr:1 row_mask:0xf bank_mask:0xf bound_ctrl:1
	v_mov_b32_e32 v71, v22
	ds_read_b64 v[22:23], v109 offset:520
	v_pk_mul_f32 v[18:19], v[72:73], v[32:33]
	v_pk_mul_f32 v[32:33], v[70:71], v[32:33]
	v_pk_fma_f32 v[18:19], v[70:71], v[30:31], v[18:19] neg_lo:[0,0,1] neg_hi:[0,0,1]
	v_pk_fma_f32 v[30:31], v[72:73], v[30:31], v[32:33]
	v_pk_add_f32 v[74:75], v[18:19], v[16:17]
	ds_read_b128 v[16:19], v109 offset:1024
	v_pk_add_f32 v[24:25], v[30:31], v[24:25]
	v_mov_b32_dpp v76, v74 row_shr:2 row_mask:0xf bank_mask:0xf bound_ctrl:1
	s_nop 0
	v_mov_b32_dpp v30, v24 row_shr:2 row_mask:0xf bank_mask:0xf bound_ctrl:1
	v_mov_b32_dpp v31, v25 row_shr:2 row_mask:0xf bank_mask:0xf bound_ctrl:1
	v_mov_b32_dpp v77, v75 row_shr:2 row_mask:0xf bank_mask:0xf bound_ctrl:1
	s_waitcnt lgkmcnt(1)
; #define SSM_SCAN_STEP(D, SQ) { _Pragma("unroll") for (int r = 0; r < 4; ++r) { \
;                     const float sr = dppf<DPP_SHR(D)>(Er[r]), si = dppf<DPP_SHR(D)>(Ei[r]); \
;                     Er[r] += mr[r] * sr - mi[r] * si; Ei[r] += mr[r] * si + mi[r] * sr; \
;                     if (SQ) { const float nr = mr[r] * mr[r] - mi[r] * mi[r], ni = 2.f * mr[r] * mi[r]; mr[r] = nr; mi[r] = ni; } } }
; template <bool PASS2>
; __device__ __forceinline__ void ssm_phase(const Params& p, const Frame& F0) {
;     ...
;             for (int i = 0; i < 4; ++i) {
;                 __builtin_amdgcn_sched_barrier(0);
;                 f32x4 Er = (f32x4){0.f, 0.f, 0.f, 0.f}, Ei = Er;
; #pragma unroll
;                 for (int ks = 0; ks < 4; ++ks) { Er = __builtin_amdgcn_mfma_f32_16x16x32_bf16(frag[(i * 4 + ks) * 64], uf[ks], Er, 0, 0, 0);
;                                                  Ei = __builtin_amdgcn_mfma_f32_16x16x32_bf16(frag[((i + 4) * 4 + ks) * 64], uf[ks], Ei, 0, 0, 0); }
;                 const f32x4 ma = m1t[8 * i], mb = m1t[8 * i + 1];
;                 float mr[4] = {ma[0], ma[2], mb[0], mb[2]}, mi[4] = {ma[1], ma[3], mb[1], mb[3]};
;                 float hr[4], hi[4];
; #pragma unroll
;                 for (int r = 0; r < 4; ++r) { hr[r] = dppf<DPP_ROR(1)>(xs[i][r]); hi[r] = dppf<DPP_ROR(1)>(xs[i + 4][r]);
;                     if (j == 0) { Er[r] += mr[r] * hr[r] - mi[r] * hi[r]; Ei[r] += mr[r] * hi[r] + mi[r] * hr[r]; } }
;     ...
;                 SSM_SCAN_STEP(1, 1) SSM_SCAN_STEP(2, 1) SSM_SCAN_STEP(4, 1) SSM_SCAN_STEP(8, 0)
	v_pk_mul_f32 v[32:33], v[22:23], v[30:31]
	v_pk_fma_f32 v[32:33], v[20:21], v[76:77], v[32:33] neg_lo:[0,0,1] neg_hi:[0,0,1]
	v_pk_mul_f32 v[20:21], v[20:21], v[30:31]
	v_pk_fma_f32 v[20:21], v[22:23], v[76:77], v[20:21]
	v_pk_add_f32 v[32:33], v[32:33], v[74:75]
	ds_read_b128 v[72:75], v109 offset:528
	v_pk_add_f32 v[22:23], v[24:25], v[20:21]
	v_mov_b32_dpp v64, v28 row_shr:1 row_mask:0xf bank_mask:0xf bound_ctrl:1
	v_mov_b32_dpp v24, v32 row_shr:4 row_mask:0xf bank_mask:0xf bound_ctrl:1
	v_mov_b32_dpp v30, v22 row_shr:4 row_mask:0xf bank_mask:0xf bound_ctrl:1
	v_mov_b32_dpp v31, v23 row_shr:4 row_mask:0xf bank_mask:0xf bound_ctrl:1
	v_mov_b32_dpp v25, v33 row_shr:4 row_mask:0xf bank_mask:0xf bound_ctrl:1
	s_waitcnt lgkmcnt(1)
	v_pk_mul_f32 v[20:21], v[18:19], v[30:31]
	v_pk_mul_f32 v[30:31], v[16:17], v[30:31]
	v_pk_fma_f32 v[20:21], v[16:17], v[24:25], v[20:21] neg_lo:[0,0,1] neg_hi:[0,0,1]
	v_mov_b32_dpp v65, v29 row_shr:1 row_mask:0xf bank_mask:0xf bound_ctrl:1
	v_pk_add_f32 v[20:21], v[32:33], v[20:21]
	v_pk_fma_f32 v[24:25], v[18:19], v[24:25], v[30:31]
	v_mov_b32_e32 v32, v83
	v_mov_b32_e32 v33, v85
	v_mov_b32_dpp v34, v26 row_shr:1 row_mask:0xf bank_mask:0xf bound_ctrl:1
	v_mov_b32_dpp v35, v27 row_shr:1 row_mask:0xf bank_mask:0xf bound_ctrl:1
	v_pk_add_f32 v[22:23], v[22:23], v[24:25]
	v_mov_b32_e32 v30, v82
	v_mov_b32_e32 v31, v84
	v_pk_mul_f32 v[24:25], v[32:33], v[64:65]
	s_nop 0
	v_pk_fma_f32 v[24:25], v[30:31], v[34:35], v[24:25] neg_lo:[0,0,1] neg_hi:[0,0,1]
	s_nop 0
	v_pk_add_f32 v[70:71], v[24:25], v[26:27]
	ds_read_b128 v[24:27], v109 offset:1040
	v_pk_mul_f32 v[30:31], v[30:31], v[64:65]
	v_pk_fma_f32 v[30:31], v[32:33], v[34:35], v[30:31]
	v_mov_b32_dpp v76, v70 row_shr:2 row_mask:0xf bank_mask:0xf bound_ctrl:1
	v_pk_add_f32 v[28:29], v[30:31], v[28:29]
	v_mov_b32_dpp v77, v71 row_shr:2 row_mask:0xf bank_mask:0xf bound_ctrl:1
	s_nop 0
	v_mov_b32_dpp v30, v28 row_shr:2 row_mask:0xf bank_mask:0xf bound_ctrl:1
	v_mov_b32_dpp v31, v29 row_shr:2 row_mask:0xf bank_mask:0xf bound_ctrl:1
	s_waitcnt lgkmcnt(1)
	v_pk_mul_f32 v[32:33], v[74:75], v[30:31]
	v_pk_mul_f32 v[30:31], v[72:73], v[30:31]
	v_pk_fma_f32 v[32:33], v[72:73], v[76:77], v[32:33] neg_lo:[0,0,1] neg_hi:[0,0,1]
	v_pk_fma_f32 v[30:31], v[74:75], v[76:77], v[30:31]
	v_pk_add_f32 v[30:31], v[28:29], v[30:31]
	v_pk_add_f32 v[32:33], v[70:71], v[32:33]
	s_nop 0
	v_mov_b32_dpp v64, v30 row_shr:4 row_mask:0xf bank_mask:0xf bound_ctrl:1
	v_mov_b32_dpp v65, v31 row_shr:4 row_mask:0xf bank_mask:0xf bound_ctrl:1
	v_mov_b32_dpp v34, v32 row_shr:4 row_mask:0xf bank_mask:0xf bound_ctrl:1
	v_mov_b32_dpp v35, v33 row_shr:4 row_mask:0xf bank_mask:0xf bound_ctrl:1
	s_waitcnt lgkmcnt(0)
	v_pk_mul_f32 v[28:29], v[26:27], v[64:65]
	s_nop 0
	v_pk_fma_f32 v[28:29], v[24:25], v[34:35], v[28:29] neg_lo:[0,0,1] neg_hi:[0,0,1]
	s_nop 0
	v_pk_add_f32 v[28:29], v[32:33], v[28:29]
	v_pk_mul_f32 v[32:33], v[24:25], v[64:65]
	v_mov_b32_dpp v64, v22 row_shr:8 row_mask:0xf bank_mask:0xf bound_ctrl:1
	v_pk_fma_f32 v[32:33], v[26:27], v[34:35], v[32:33]
	v_mov_b32_dpp v65, v23 row_shr:8 row_mask:0xf bank_mask:0xf bound_ctrl:1
	v_pk_add_f32 v[32:33], v[30:31], v[32:33]
	v_mov_b32_dpp v30, v20 row_shr:8 row_mask:0xf bank_mask:0xf bound_ctrl:1
	v_mov_b32_dpp v31, v21 row_shr:8 row_mask:0xf bank_mask:0xf bound_ctrl:1
	v_mov_b32_dpp v34, v28 row_shr:8 row_mask:0xf bank_mask:0xf bound_ctrl:1
	v_mov_b32_dpp v70, v32 row_shr:8 row_mask:0xf bank_mask:0xf bound_ctrl:1
	v_mov_b32_dpp v35, v29 row_shr:8 row_mask:0xf bank_mask:0xf bound_ctrl:1
	v_mov_b32_dpp v71, v33 row_shr:8 row_mask:0xf bank_mask:0xf bound_ctrl:1
	ds_read_b128 v[72:75], v105 offset:4096
	ds_read_b128 v[76:79], v105 offset:5120
	ds_read_b128 v[80:83], v105 offset:20480
	ds_read_b128 v[84:87], v105 offset:21504
	v_mov_b32_dpp v101, v62 row_ror:1 row_mask:0xf bank_mask:0xf bound_ctrl:1
	v_mov_b32_dpp v100, v60 row_ror:1 row_mask:0xf bank_mask:0xf bound_ctrl:1
	s_waitcnt lgkmcnt(3)
	v_mfma_f32_16x16x32_bf16 v[72:75], v[72:75], v[12:15], 0
	v_mov_b32_dpp v63, v63 row_ror:1 row_mask:0xf bank_mask:0xf bound_ctrl:1
	v_mov_b32_dpp v62, v61 row_ror:1 row_mask:0xf bank_mask:0xf bound_ctrl:1
	s_waitcnt lgkmcnt(2)
	v_mfma_f32_16x16x32_bf16 v[72:75], v[76:79], v[4:7], v[72:75]
	ds_read_b128 v[76:79], v105 offset:6144
	s_waitcnt lgkmcnt(2)
	v_mfma_f32_16x16x32_bf16 v[80:83], v[80:83], v[12:15], 0
	s_waitcnt lgkmcnt(1)
	v_mfma_f32_16x16x32_bf16 v[80:83], v[84:87], v[4:7], v[80:83]
	ds_read_b128 v[84:87], v105 offset:22528
	ds_read_b128 v[88:91], v105 offset:7168
	ds_read_b128 v[92:95], v105 offset:23552
	s_waitcnt lgkmcnt(3)
	v_mfma_f32_16x16x32_bf16 v[72:75], v[76:79], v[8:11], v[72:75]
	ds_read_b128 v[76:79], v109 offset:128
	ds_read_b128 v[96:99], v109 offset:144
	s_waitcnt lgkmcnt(4)
	v_mfma_f32_16x16x32_bf16 v[80:83], v[84:87], v[8:11], v[80:83]
	s_waitcnt lgkmcnt(1)
	v_pk_mul_f32 v[84:85], v[76:77], v[100:101] op_sel:[0,1] op_sel_hi:[1,0]
	s_nop 0
	v_sub_f32_e32 v60, v84, v85
	v_mfma_f32_16x16x32_bf16 v[72:75], v[88:91], v[0:3], v[72:75]
	v_mul_f32_e64 v84, v76, v100
	v_mul_f32_e64 v85, v77, v101
	v_mov_b32_e32 v88, v77
	v_mov_b32_e32 v89, v79
	v_mfma_f32_16x16x32_bf16 v[80:83], v[92:95], v[0:3], v[80:83]
	s_nop 2
	v_add_f32_e32 v86, v72, v60
	v_add_f32_e32 v60, v85, v84
	s_nop 2
	v_add_f32_e32 v84, v80, v60
	v_pk_mul_f32 v[60:61], v[78:79], v[62:63] op_sel:[0,1] op_sel_hi:[1,0]
	s_nop 0
	v_sub_f32_e32 v60, v60, v61
	v_add_f32_e32 v85, v60, v73
	v_pk_mul_f32 v[60:61], v[78:79], v[62:63]
	s_nop 0
	v_add_f32_e32 v60, v61, v60
	v_add_f32_e32 v87, v60, v81
	v_mov_b32_dpp v61, v68 row_ror:1 row_mask:0xf bank_mask:0xf bound_ctrl:1
	v_mov_b32_dpp v60, v66 row_ror:1 row_mask:0xf bank_mask:0xf bound_ctrl:1
	s_waitcnt lgkmcnt(0)
; #define SSM_SCAN_STEP(D, SQ) { _Pragma("unroll") for (int r = 0; r < 4; ++r) { \
;                     const float sr = dppf<DPP_SHR(D)>(Er[r]), si = dppf<DPP_SHR(D)>(Ei[r]); \
;                     Er[r] += mr[r] * sr - mi[r] * si; Ei[r] += mr[r] * si + mi[r] * sr; \
;                     if (SQ) { const float nr = mr[r] * mr[r] - mi[r] * mi[r], ni = 2.f * mr[r] * mi[r]; mr[r] = nr; mi[r] = ni; } } }
; template <bool PASS2>
; __device__ __forceinline__ void ssm_phase(const Params& p, const Frame& F0) {
;     ...
;             for (int i = 0; i < 4; ++i) {
;                 __builtin_amdgcn_sched_barrier(0);
;                 f32x4 Er = (f32x4){0.f, 0.f, 0.f, 0.f}, Ei = Er;
; #pragma unroll
;                 for (int ks = 0; ks < 4; ++ks) { Er = __builtin_amdgcn_mfma_f32_16x16x32_bf16(frag[(i * 4 + ks) * 64], uf[ks], Er, 0, 0, 0);
;                                                  Ei = __builtin_amdgcn_mfma_f32_16x16x32_bf16(frag[((i + 4) * 4 + ks) * 64], uf[ks], Ei, 0, 0, 0); }
;                 const f32x4 ma = m1t[8 * i], mb = m1t[8 * i + 1];
;                 float mr[4] = {ma[0], ma[2], mb[0], mb[2]}, mi[4] = {ma[1], ma[3], mb[1], mb[3]};
;                 float hr[4], hi[4];
; #pragma unroll
;                 for (int r = 0; r < 4; ++r) { hr[r] = dppf<DPP_ROR(1)>(xs[i][r]); hi[r] = dppf<DPP_ROR(1)>(xs[i + 4][r]);
;                     if (j == 0) { Er[r] += mr[r] * hr[r] - mi[r] * hi[r]; Ei[r] += mr[r] * hi[r] + mi[r] * hr[r]; } }
;     ...
;                 SSM_SCAN_STEP(1, 1) SSM_SCAN_STEP(2, 1) SSM_SCAN_STEP(4, 1) SSM_SCAN_STEP(8, 0)
	v_pk_mul_f32 v[62:63], v[96:97], v[60:61] op_sel:[0,1] op_sel_hi:[1,0]
	v_pk_mul_f32 v[60:61], v[96:97], v[60:61]
	v_sub_f32_e32 v62, v62, v63
	v_add_f32_e32 v60, v61, v60
	v_add_f32_e32 v66, v60, v82
	v_mov_b32_dpp v61, v69 row_ror:1 row_mask:0xf bank_mask:0xf bound_ctrl:1
	v_mov_b32_dpp v60, v67 row_ror:1 row_mask:0xf bank_mask:0xf bound_ctrl:1
	v_add_f32_e32 v68, v62, v74
	v_pk_mul_f32 v[62:63], v[98:99], v[60:61] op_sel:[0,1] op_sel_hi:[1,0]
	v_pk_mul_f32 v[60:61], v[98:99], v[60:61]
	v_sub_f32_e32 v62, v62, v63
	v_add_f32_e32 v60, v61, v60
	v_add_f32_e32 v60, v60, v83
	v_cndmask_b32_e64 v82, v82, v66, s[6:7]
	v_cndmask_b32_e64 v67, v81, v87, s[6:7]
	v_cndmask_b32_e64 v66, v80, v84, s[6:7]
	v_add_f32_e32 v62, v62, v75
	v_cndmask_b32_e64 v83, v83, v60, s[6:7]
	v_cndmask_b32_e64 v61, v73, v85, s[6:7]
	v_cndmask_b32_e64 v60, v72, v86, s[6:7]
	v_mov_b32_dpp v72, v66 row_shr:1 row_mask:0xf bank_mask:0xf bound_ctrl:1
	v_mov_b32_dpp v73, v67 row_shr:1 row_mask:0xf bank_mask:0xf bound_ctrl:1
	v_cndmask_b32_e64 v75, v75, v62, s[6:7]
	v_cndmask_b32_e64 v74, v74, v68, s[6:7]
	v_mov_b32_dpp v68, v60 row_shr:1 row_mask:0xf bank_mask:0xf bound_ctrl:1
	v_mov_b32_dpp v69, v61 row_shr:1 row_mask:0xf bank_mask:0xf bound_ctrl:1
	v_mov_b32_e32 v86, v76
	v_mov_b32_e32 v87, v78
	ds_read_b128 v[76:79], v109 offset:640
	v_pk_mul_f32 v[62:63], v[88:89], v[72:73]
	v_pk_mul_f32 v[72:73], v[86:87], v[72:73]
	v_pk_fma_f32 v[62:63], v[86:87], v[68:69], v[62:63] neg_lo:[0,0,1] neg_hi:[0,0,1]
	v_pk_fma_f32 v[68:69], v[88:89], v[68:69], v[72:73]
	v_pk_add_f32 v[90:91], v[62:63], v[60:61]
	ds_read_b128 v[60:63], v109 offset:1152
	v_pk_add_f32 v[66:67], v[68:69], v[66:67]
	v_mov_b32_dpp v92, v90 row_shr:2 row_mask:0xf bank_mask:0xf bound_ctrl:1
	s_nop 0
	v_mov_b32_dpp v68, v66 row_shr:2 row_mask:0xf bank_mask:0xf bound_ctrl:1
	v_mov_b32_dpp v69, v67 row_shr:2 row_mask:0xf bank_mask:0xf bound_ctrl:1
	v_mov_b32_dpp v93, v91 row_shr:2 row_mask:0xf bank_mask:0xf bound_ctrl:1
	s_waitcnt lgkmcnt(1)
	v_pk_mul_f32 v[72:73], v[78:79], v[68:69]
	v_pk_mul_f32 v[68:69], v[76:77], v[68:69]
	v_pk_fma_f32 v[68:69], v[78:79], v[92:93], v[68:69]
	v_pk_fma_f32 v[72:73], v[76:77], v[92:93], v[72:73] neg_lo:[0,0,1] neg_hi:[0,0,1]
	v_pk_add_f32 v[68:69], v[66:67], v[68:69]
	v_pk_add_f32 v[72:73], v[72:73], v[90:91]
	ds_read_b128 v[88:91], v109 offset:656
	v_mov_b32_dpp v78, v68 row_shr:4 row_mask:0xf bank_mask:0xf bound_ctrl:1
	v_mov_b32_dpp v79, v69 row_shr:4 row_mask:0xf bank_mask:0xf bound_ctrl:1
	v_mov_b32_dpp v76, v72 row_shr:4 row_mask:0xf bank_mask:0xf bound_ctrl:1
	v_mov_b32_dpp v77, v73 row_shr:4 row_mask:0xf bank_mask:0xf bound_ctrl:1
	s_waitcnt lgkmcnt(1)
	v_pk_mul_f32 v[66:67], v[62:63], v[78:79]
	v_mov_b32_dpp v84, v82 row_shr:1 row_mask:0xf bank_mask:0xf bound_ctrl:1
	v_pk_fma_f32 v[66:67], v[60:61], v[76:77], v[66:67] neg_lo:[0,0,1] neg_hi:[0,0,1]
	v_mov_b32_dpp v85, v83 row_shr:1 row_mask:0xf bank_mask:0xf bound_ctrl:1
	v_pk_add_f32 v[66:67], v[72:73], v[66:67]
	v_pk_mul_f32 v[72:73], v[60:61], v[78:79]
	v_mov_b32_e32 v78, v97
	v_pk_fma_f32 v[72:73], v[62:63], v[76:77], v[72:73]
	v_mov_b32_e32 v79, v99
	v_mov_b32_dpp v80, v74 row_shr:1 row_mask:0xf bank_mask:0xf bound_ctrl:1
	v_mov_b32_dpp v81, v75 row_shr:1 row_mask:0xf bank_mask:0xf bound_ctrl:1
	v_pk_add_f32 v[68:69], v[68:69], v[72:73]
	v_mov_b32_e32 v76, v96
	v_mov_b32_e32 v77, v98
	v_pk_mul_f32 v[72:73], v[78:79], v[84:85]
	s_nop 0
	v_pk_fma_f32 v[72:73], v[76:77], v[80:81], v[72:73] neg_lo:[0,0,1] neg_hi:[0,0,1]
	s_nop 0
	v_pk_add_f32 v[86:87], v[72:73], v[74:75]
	ds_read_b128 v[72:75], v109 offset:1168
	v_pk_mul_f32 v[76:77], v[76:77], v[84:85]
	v_pk_fma_f32 v[76:77], v[78:79], v[80:81], v[76:77]
	v_mov_b32_dpp v92, v86 row_shr:2 row_mask:0xf bank_mask:0xf bound_ctrl:1
	v_pk_add_f32 v[76:77], v[76:77], v[82:83]
	v_mov_b32_dpp v93, v87 row_shr:2 row_mask:0xf bank_mask:0xf bound_ctrl:1
	s_nop 0
	v_mov_b32_dpp v78, v76 row_shr:2 row_mask:0xf bank_mask:0xf bound_ctrl:1
	v_mov_b32_dpp v79, v77 row_shr:2 row_mask:0xf bank_mask:0xf bound_ctrl:1
	s_waitcnt lgkmcnt(1)
	v_pk_mul_f32 v[80:81], v[90:91], v[78:79]
	v_pk_mul_f32 v[78:79], v[88:89], v[78:79]
	v_pk_fma_f32 v[80:81], v[88:89], v[92:93], v[80:81] neg_lo:[0,0,1] neg_hi:[0,0,1]
	v_pk_fma_f32 v[78:79], v[90:91], v[92:93], v[78:79]
	v_pk_add_f32 v[78:79], v[76:77], v[78:79]
	v_pk_add_f32 v[80:81], v[86:87], v[80:81]
	s_nop 0
	v_mov_b32_dpp v84, v78 row_shr:4 row_mask:0xf bank_mask:0xf bound_ctrl:1
	v_mov_b32_dpp v85, v79 row_shr:4 row_mask:0xf bank_mask:0xf bound_ctrl:1
	v_mov_b32_dpp v82, v80 row_shr:4 row_mask:0xf bank_mask:0xf bound_ctrl:1
	v_mov_b32_dpp v83, v81 row_shr:4 row_mask:0xf bank_mask:0xf bound_ctrl:1
	s_waitcnt lgkmcnt(0)
	v_pk_mul_f32 v[76:77], v[74:75], v[84:85]
	s_nop 0
	v_pk_fma_f32 v[76:77], v[72:73], v[82:83], v[76:77] neg_lo:[0,0,1] neg_hi:[0,0,1]
	s_nop 0
	v_pk_add_f32 v[76:77], v[80:81], v[76:77]
	v_pk_mul_f32 v[80:81], v[72:73], v[84:85]
	v_mov_b32_dpp v84, v68 row_shr:8 row_mask:0xf bank_mask:0xf bound_ctrl:1
	v_pk_fma_f32 v[80:81], v[74:75], v[82:83], v[80:81]
	v_mov_b32_dpp v85, v69 row_shr:8 row_mask:0xf bank_mask:0xf bound_ctrl:1
	v_pk_add_f32 v[80:81], v[78:79], v[80:81]
	v_mov_b32_dpp v78, v66 row_shr:8 row_mask:0xf bank_mask:0xf bound_ctrl:1
	v_mov_b32_dpp v79, v67 row_shr:8 row_mask:0xf bank_mask:0xf bound_ctrl:1
	v_mov_b32_dpp v82, v76 row_shr:8 row_mask:0xf bank_mask:0xf bound_ctrl:1
	v_mov_b32_dpp v86, v80 row_shr:8 row_mask:0xf bank_mask:0xf bound_ctrl:1
	v_mov_b32_dpp v83, v77 row_shr:8 row_mask:0xf bank_mask:0xf bound_ctrl:1
	v_mov_b32_dpp v87, v81 row_shr:8 row_mask:0xf bank_mask:0xf bound_ctrl:1
	ds_read_b128 v[88:91], v105 offset:8192
	ds_read_b128 v[92:95], v105 offset:9216
	ds_read_b128 v[96:99], v105 offset:24576
	ds_read_b128 v[100:103], v105 offset:25600
	v_mov_b32_dpp v123, v54 row_ror:1 row_mask:0xf bank_mask:0xf bound_ctrl:1
	v_mov_b32_dpp v122, v52 row_ror:1 row_mask:0xf bank_mask:0xf bound_ctrl:1
	s_waitcnt lgkmcnt(3)
; #define SSM_SCAN_STEP(D, SQ) { _Pragma("unroll") for (int r = 0; r < 4; ++r) { \
;                     const float sr = dppf<DPP_SHR(D)>(Er[r]), si = dppf<DPP_SHR(D)>(Ei[r]); \
;                     Er[r] += mr[r] * sr - mi[r] * si; Ei[r] += mr[r] * si + mi[r] * sr; \
;                     if (SQ) { const float nr = mr[r] * mr[r] - mi[r] * mi[r], ni = 2.f * mr[r] * mi[r]; mr[r] = nr; mi[r] = ni; } } }
; template <bool PASS2>
; __device__ __forceinline__ void ssm_phase(const Params& p, const Frame& F0) {
;     ...
;             for (int i = 0; i < 4; ++i) {
;                 __builtin_amdgcn_sched_barrier(0);
;                 f32x4 Er = (f32x4){0.f, 0.f, 0.f, 0.f}, Ei = Er;
; #pragma unroll
;                 for (int ks = 0; ks < 4; ++ks) { Er = __builtin_amdgcn_mfma_f32_16x16x32_bf16(frag[(i * 4 + ks) * 64], uf[ks], Er, 0, 0, 0);
;                                                  Ei = __builtin_amdgcn_mfma_f32_16x16x32_bf16(frag[((i + 4) * 4 + ks) * 64], uf[ks], Ei, 0, 0, 0); }
;                 const f32x4 ma = m1t[8 * i], mb = m1t[8 * i + 1];
;                 float mr[4] = {ma[0], ma[2], mb[0], mb[2]}, mi[4] = {ma[1], ma[3], mb[1], mb[3]};
;                 float hr[4], hi[4];
; #pragma unroll
;                 for (int r = 0; r < 4; ++r) { hr[r] = dppf<DPP_ROR(1)>(xs[i][r]); hi[r] = dppf<DPP_ROR(1)>(xs[i + 4][r]);
;                     if (j == 0) { Er[r] += mr[r] * hr[r] - mi[r] * hi[r]; Ei[r] += mr[r] * hi[r] + mi[r] * hr[r]; } }
;     ...
;                 SSM_SCAN_STEP(1, 1) SSM_SCAN_STEP(2, 1) SSM_SCAN_STEP(4, 1) SSM_SCAN_STEP(8, 0)
	v_mfma_f32_16x16x32_bf16 v[88:91], v[88:91], v[12:15], 0
	v_mov_b32_dpp v55, v55 row_ror:1 row_mask:0xf bank_mask:0xf bound_ctrl:1
	v_mov_b32_dpp v54, v53 row_ror:1 row_mask:0xf bank_mask:0xf bound_ctrl:1
	s_waitcnt lgkmcnt(2)
	v_mfma_f32_16x16x32_bf16 v[88:91], v[92:95], v[4:7], v[88:91]
	ds_read_b128 v[92:95], v105 offset:10240
	s_waitcnt lgkmcnt(2)
	v_mfma_f32_16x16x32_bf16 v[96:99], v[96:99], v[12:15], 0
	s_waitcnt lgkmcnt(1)
	v_mfma_f32_16x16x32_bf16 v[96:99], v[100:103], v[4:7], v[96:99]
	ds_read_b128 v[100:103], v105 offset:26624
	ds_read_b128 v[110:113], v105 offset:11264
	ds_read_b128 v[114:117], v105 offset:27648
	s_waitcnt lgkmcnt(3)
	v_mfma_f32_16x16x32_bf16 v[88:91], v[92:95], v[8:11], v[88:91]
	ds_read_b128 v[92:95], v109 offset:256
	ds_read_b128 v[118:121], v109 offset:272
	s_waitcnt lgkmcnt(4)
	v_mfma_f32_16x16x32_bf16 v[96:99], v[100:103], v[8:11], v[96:99]
	s_waitcnt lgkmcnt(1)
	v_pk_mul_f32 v[100:101], v[92:93], v[122:123] op_sel:[0,1] op_sel_hi:[1,0]
	s_nop 0
	v_sub_f32_e32 v52, v100, v101
	v_mfma_f32_16x16x32_bf16 v[88:91], v[110:113], v[0:3], v[88:91]
	v_mul_f32_e64 v100, v92, v122
	v_mul_f32_e64 v101, v93, v123
	v_mov_b32_e32 v110, v93
	v_mov_b32_e32 v111, v95
	v_mfma_f32_16x16x32_bf16 v[96:99], v[114:117], v[0:3], v[96:99]
	s_nop 2
	v_add_f32_e32 v102, v88, v52
	v_add_f32_e32 v52, v101, v100
	s_nop 2
	v_add_f32_e32 v100, v96, v52
	v_pk_mul_f32 v[52:53], v[94:95], v[54:55] op_sel:[0,1] op_sel_hi:[1,0]
	s_nop 0
	v_sub_f32_e32 v52, v52, v53
	v_add_f32_e32 v101, v52, v89
	v_pk_mul_f32 v[52:53], v[94:95], v[54:55]
	s_nop 0
	v_add_f32_e32 v52, v53, v52
	v_add_f32_e32 v103, v52, v97
	v_mov_b32_dpp v53, v58 row_ror:1 row_mask:0xf bank_mask:0xf bound_ctrl:1
	v_mov_b32_dpp v52, v56 row_ror:1 row_mask:0xf bank_mask:0xf bound_ctrl:1
	s_waitcnt lgkmcnt(0)
	v_pk_mul_f32 v[54:55], v[118:119], v[52:53] op_sel:[0,1] op_sel_hi:[1,0]
	v_pk_mul_f32 v[52:53], v[118:119], v[52:53]
	v_sub_f32_e32 v54, v54, v55
	v_add_f32_e32 v52, v53, v52
	v_add_f32_e32 v56, v52, v98
	v_mov_b32_dpp v53, v59 row_ror:1 row_mask:0xf bank_mask:0xf bound_ctrl:1
	v_mov_b32_dpp v52, v57 row_ror:1 row_mask:0xf bank_mask:0xf bound_ctrl:1
	v_add_f32_e32 v58, v54, v90
	v_pk_mul_f32 v[54:55], v[120:121], v[52:53] op_sel:[0,1] op_sel_hi:[1,0]
	v_pk_mul_f32 v[52:53], v[120:121], v[52:53]
	v_sub_f32_e32 v54, v54, v55
	v_add_f32_e32 v52, v53, v52
	v_add_f32_e32 v52, v52, v99
	v_cndmask_b32_e64 v98, v98, v56, s[6:7]
	v_cndmask_b32_e64 v57, v97, v103, s[6:7]
	v_cndmask_b32_e64 v56, v96, v100, s[6:7]
	v_add_f32_e32 v54, v54, v91
	v_cndmask_b32_e64 v99, v99, v52, s[6:7]
	v_cndmask_b32_e64 v53, v89, v101, s[6:7]
	v_cndmask_b32_e64 v52, v88, v102, s[6:7]
	v_mov_b32_dpp v88, v56 row_shr:1 row_mask:0xf bank_mask:0xf bound_ctrl:1
	v_mov_b32_dpp v89, v57 row_shr:1 row_mask:0xf bank_mask:0xf bound_ctrl:1
	v_cndmask_b32_e64 v91, v91, v54, s[6:7]
	v_cndmask_b32_e64 v90, v90, v58, s[6:7]
	v_mov_b32_dpp v58, v52 row_shr:1 row_mask:0xf bank_mask:0xf bound_ctrl:1
	v_mov_b32_dpp v59, v53 row_shr:1 row_mask:0xf bank_mask:0xf bound_ctrl:1
	v_mov_b32_e32 v102, v92
	v_mov_b32_e32 v103, v94
	ds_read_b128 v[92:95], v109 offset:768
	v_pk_mul_f32 v[54:55], v[110:111], v[88:89]
	v_pk_mul_f32 v[88:89], v[102:103], v[88:89]
	v_pk_fma_f32 v[54:55], v[102:103], v[58:59], v[54:55] neg_lo:[0,0,1] neg_hi:[0,0,1]
	v_pk_fma_f32 v[58:59], v[110:111], v[58:59], v[88:89]
	v_pk_add_f32 v[112:113], v[54:55], v[52:53]
	ds_read_b128 v[52:55], v109 offset:1280
	v_pk_add_f32 v[56:57], v[58:59], v[56:57]
	v_mov_b32_dpp v114, v112 row_shr:2 row_mask:0xf bank_mask:0xf bound_ctrl:1
	s_nop 0
	v_mov_b32_dpp v58, v56 row_shr:2 row_mask:0xf bank_mask:0xf bound_ctrl:1
	v_mov_b32_dpp v59, v57 row_shr:2 row_mask:0xf bank_mask:0xf bound_ctrl:1
	v_mov_b32_dpp v115, v113 row_shr:2 row_mask:0xf bank_mask:0xf bound_ctrl:1
	s_waitcnt lgkmcnt(1)
	v_pk_mul_f32 v[88:89], v[94:95], v[58:59]
	v_pk_mul_f32 v[58:59], v[92:93], v[58:59]
	v_pk_fma_f32 v[58:59], v[94:95], v[114:115], v[58:59]
	v_pk_fma_f32 v[88:89], v[92:93], v[114:115], v[88:89] neg_lo:[0,0,1] neg_hi:[0,0,1]
	v_pk_add_f32 v[58:59], v[56:57], v[58:59]
	v_pk_add_f32 v[88:89], v[88:89], v[112:113]
	ds_read_b128 v[110:113], v109 offset:784
	v_mov_b32_dpp v94, v58 row_shr:4 row_mask:0xf bank_mask:0xf bound_ctrl:1
	v_mov_b32_dpp v95, v59 row_shr:4 row_mask:0xf bank_mask:0xf bound_ctrl:1
	v_mov_b32_dpp v92, v88 row_shr:4 row_mask:0xf bank_mask:0xf bound_ctrl:1
	v_mov_b32_dpp v93, v89 row_shr:4 row_mask:0xf bank_mask:0xf bound_ctrl:1
	s_waitcnt lgkmcnt(1)
	v_pk_mul_f32 v[56:57], v[54:55], v[94:95]
	v_mov_b32_dpp v100, v98 row_shr:1 row_mask:0xf bank_mask:0xf bound_ctrl:1
	v_pk_fma_f32 v[56:57], v[52:53], v[92:93], v[56:57] neg_lo:[0,0,1] neg_hi:[0,0,1]
	v_mov_b32_dpp v101, v99 row_shr:1 row_mask:0xf bank_mask:0xf bound_ctrl:1
	v_pk_add_f32 v[56:57], v[88:89], v[56:57]
	v_pk_mul_f32 v[88:89], v[52:53], v[94:95]
	v_mov_b32_e32 v94, v119
	v_pk_fma_f32 v[88:89], v[54:55], v[92:93], v[88:89]
	v_mov_b32_e32 v95, v121
	v_mov_b32_dpp v96, v90 row_shr:1 row_mask:0xf bank_mask:0xf bound_ctrl:1
	v_mov_b32_dpp v97, v91 row_shr:1 row_mask:0xf bank_mask:0xf bound_ctrl:1
	v_pk_add_f32 v[58:59], v[58:59], v[88:89]
	v_mov_b32_e32 v92, v118
	v_mov_b32_e32 v93, v120
	v_pk_mul_f32 v[88:89], v[94:95], v[100:101]
	s_nop 0
	v_pk_fma_f32 v[88:89], v[92:93], v[96:97], v[88:89] neg_lo:[0,0,1] neg_hi:[0,0,1]
	s_nop 0
	v_pk_add_f32 v[102:103], v[88:89], v[90:91]
	ds_read_b128 v[88:91], v109 offset:1296
	v_pk_mul_f32 v[92:93], v[92:93], v[100:101]
	v_pk_fma_f32 v[92:93], v[94:95], v[96:97], v[92:93]
	v_mov_b32_dpp v114, v102 row_shr:2 row_mask:0xf bank_mask:0xf bound_ctrl:1
	v_pk_add_f32 v[92:93], v[92:93], v[98:99]
	v_mov_b32_dpp v115, v103 row_shr:2 row_mask:0xf bank_mask:0xf bound_ctrl:1
	s_nop 0
	v_mov_b32_dpp v94, v92 row_shr:2 row_mask:0xf bank_mask:0xf bound_ctrl:1
	v_mov_b32_dpp v95, v93 row_shr:2 row_mask:0xf bank_mask:0xf bound_ctrl:1
	s_waitcnt lgkmcnt(1)
; #define SSM_SCAN_STEP(D, SQ) { _Pragma("unroll") for (int r = 0; r < 4; ++r) { \
;                     const float sr = dppf<DPP_SHR(D)>(Er[r]), si = dppf<DPP_SHR(D)>(Ei[r]); \
;                     Er[r] += mr[r] * sr - mi[r] * si; Ei[r] += mr[r] * si + mi[r] * sr; \
;                     if (SQ) { const float nr = mr[r] * mr[r] - mi[r] * mi[r], ni = 2.f * mr[r] * mi[r]; mr[r] = nr; mi[r] = ni; } } }
; template <bool PASS2>
; __device__ __forceinline__ void ssm_phase(const Params& p, const Frame& F0) {
;     ...
;             for (int i = 0; i < 4; ++i) {
;                 __builtin_amdgcn_sched_barrier(0);
;                 f32x4 Er = (f32x4){0.f, 0.f, 0.f, 0.f}, Ei = Er;
; #pragma unroll
;                 for (int ks = 0; ks < 4; ++ks) { Er = __builtin_amdgcn_mfma_f32_16x16x32_bf16(frag[(i * 4 + ks) * 64], uf[ks], Er, 0, 0, 0);
;                                                  Ei = __builtin_amdgcn_mfma_f32_16x16x32_bf16(frag[((i + 4) * 4 + ks) * 64], uf[ks], Ei, 0, 0, 0); }
;                 const f32x4 ma = m1t[8 * i], mb = m1t[8 * i + 1];
;                 float mr[4] = {ma[0], ma[2], mb[0], mb[2]}, mi[4] = {ma[1], ma[3], mb[1], mb[3]};
;                 float hr[4], hi[4];
; #pragma unroll
;                 for (int r = 0; r < 4; ++r) { hr[r] = dppf<DPP_ROR(1)>(xs[i][r]); hi[r] = dppf<DPP_ROR(1)>(xs[i + 4][r]);
;                     if (j == 0) { Er[r] += mr[r] * hr[r] - mi[r] * hi[r]; Ei[r] += mr[r] * hi[r] + mi[r] * hr[r]; } }
;     ...
;                 SSM_SCAN_STEP(1, 1) SSM_SCAN_STEP(2, 1) SSM_SCAN_STEP(4, 1) SSM_SCAN_STEP(8, 0)
	v_pk_mul_f32 v[96:97], v[112:113], v[94:95]
	v_pk_mul_f32 v[94:95], v[110:111], v[94:95]
	v_pk_fma_f32 v[96:97], v[110:111], v[114:115], v[96:97] neg_lo:[0,0,1] neg_hi:[0,0,1]
	v_pk_fma_f32 v[94:95], v[112:113], v[114:115], v[94:95]
	v_pk_add_f32 v[94:95], v[92:93], v[94:95]
	v_pk_add_f32 v[96:97], v[102:103], v[96:97]
	s_nop 0
	v_mov_b32_dpp v100, v94 row_shr:4 row_mask:0xf bank_mask:0xf bound_ctrl:1
	v_mov_b32_dpp v101, v95 row_shr:4 row_mask:0xf bank_mask:0xf bound_ctrl:1
	v_mov_b32_dpp v98, v96 row_shr:4 row_mask:0xf bank_mask:0xf bound_ctrl:1
	v_mov_b32_dpp v99, v97 row_shr:4 row_mask:0xf bank_mask:0xf bound_ctrl:1
	s_waitcnt lgkmcnt(0)
	v_pk_mul_f32 v[92:93], v[90:91], v[100:101]
	s_nop 0
	v_pk_fma_f32 v[92:93], v[88:89], v[98:99], v[92:93] neg_lo:[0,0,1] neg_hi:[0,0,1]
	s_nop 0
	v_pk_add_f32 v[92:93], v[96:97], v[92:93]
	v_pk_mul_f32 v[96:97], v[88:89], v[100:101]
	v_mov_b32_dpp v100, v58 row_shr:8 row_mask:0xf bank_mask:0xf bound_ctrl:1
	v_pk_fma_f32 v[96:97], v[90:91], v[98:99], v[96:97]
	v_mov_b32_dpp v101, v59 row_shr:8 row_mask:0xf bank_mask:0xf bound_ctrl:1
	v_pk_add_f32 v[96:97], v[94:95], v[96:97]
	v_mov_b32_dpp v94, v56 row_shr:8 row_mask:0xf bank_mask:0xf bound_ctrl:1
	v_mov_b32_dpp v95, v57 row_shr:8 row_mask:0xf bank_mask:0xf bound_ctrl:1
	v_mov_b32_dpp v98, v92 row_shr:8 row_mask:0xf bank_mask:0xf bound_ctrl:1
	v_mov_b32_dpp v102, v96 row_shr:8 row_mask:0xf bank_mask:0xf bound_ctrl:1
	v_mov_b32_dpp v99, v93 row_shr:8 row_mask:0xf bank_mask:0xf bound_ctrl:1
	v_mov_b32_dpp v103, v97 row_shr:8 row_mask:0xf bank_mask:0xf bound_ctrl:1
	ds_read_b128 v[110:113], v105 offset:12288
	ds_read_b128 v[114:117], v105 offset:28672
	v_mov_b32_dpp v47, v47 row_ror:1 row_mask:0xf bank_mask:0xf bound_ctrl:1
	s_waitcnt lgkmcnt(1)
	v_mfma_f32_16x16x32_bf16 v[110:113], v[110:113], v[12:15], 0
	s_waitcnt lgkmcnt(0)
	v_mfma_f32_16x16x32_bf16 v[12:15], v[114:117], v[12:15], 0
	ds_read_b128 v[114:117], v105 offset:13312
	s_waitcnt lgkmcnt(0)
	v_mfma_f32_16x16x32_bf16 v[110:113], v[114:117], v[4:7], v[110:113]
	ds_read_b128 v[114:117], v105 offset:29696
	s_waitcnt lgkmcnt(0)
	v_mfma_f32_16x16x32_bf16 v[4:7], v[114:117], v[4:7], v[12:15]
	s_nop 2
	ds_read_b128 v[12:15], v105 offset:14336
	s_waitcnt lgkmcnt(0)
	v_mfma_f32_16x16x32_bf16 v[12:15], v[12:15], v[8:11], v[110:113]
	s_nop 2
	ds_read_b128 v[110:113], v105 offset:30720
	s_waitcnt lgkmcnt(0)
	v_mfma_f32_16x16x32_bf16 v[4:7], v[110:113], v[8:11], v[4:7]
	ds_read_b128 v[8:11], v105 offset:15360
	v_mov_b32_dpp v111, v46 row_ror:1 row_mask:0xf bank_mask:0xf bound_ctrl:1
	v_mov_b32_dpp v110, v44 row_ror:1 row_mask:0xf bank_mask:0xf bound_ctrl:1
	s_waitcnt lgkmcnt(0)
	v_mfma_f32_16x16x32_bf16 v[8:11], v[8:11], v[0:3], v[12:15]
	s_nop 2
	ds_read_b128 v[12:15], v105 offset:31744
	v_mov_b32_dpp v46, v45 row_ror:1 row_mask:0xf bank_mask:0xf bound_ctrl:1
	s_waitcnt lgkmcnt(0)
	v_mfma_f32_16x16x32_bf16 v[0:3], v[12:15], v[0:3], v[4:7]
	s_nop 2
	ds_read_b128 v[4:7], v109 offset:384
	ds_read_b128 v[12:15], v109 offset:400
	s_waitcnt lgkmcnt(1)
	v_pk_mul_f32 v[112:113], v[4:5], v[110:111] op_sel:[0,1] op_sel_hi:[1,0]
	s_nop 0
	v_sub_f32_e32 v44, v112, v113
	v_pk_mul_f32 v[110:111], v[4:5], v[110:111]
	v_add_f32_e32 v112, v8, v44
	v_add_f32_e32 v44, v111, v110
	v_add_f32_e32 v110, v0, v44
	v_pk_mul_f32 v[44:45], v[6:7], v[46:47] op_sel:[0,1] op_sel_hi:[1,0]
	v_mov_b32_e32 v114, v5
	v_sub_f32_e32 v44, v44, v45
	v_add_f32_e32 v111, v44, v9
	v_pk_mul_f32 v[44:45], v[6:7], v[46:47]
	v_mov_b32_e32 v115, v7
	v_add_f32_e32 v44, v45, v44
	v_add_f32_e32 v113, v44, v1
	v_mov_b32_dpp v45, v50 row_ror:1 row_mask:0xf bank_mask:0xf bound_ctrl:1
	v_mov_b32_dpp v44, v48 row_ror:1 row_mask:0xf bank_mask:0xf bound_ctrl:1
	s_waitcnt lgkmcnt(0)
	v_pk_mul_f32 v[46:47], v[12:13], v[44:45] op_sel:[0,1] op_sel_hi:[1,0]
	v_pk_mul_f32 v[44:45], v[12:13], v[44:45]
	v_sub_f32_e32 v46, v46, v47
	v_add_f32_e32 v44, v45, v44
	v_add_f32_e32 v50, v44, v2
	v_mov_b32_dpp v45, v51 row_ror:1 row_mask:0xf bank_mask:0xf bound_ctrl:1
	v_mov_b32_dpp v44, v49 row_ror:1 row_mask:0xf bank_mask:0xf bound_ctrl:1
	v_add_f32_e32 v48, v46, v10
	v_pk_mul_f32 v[46:47], v[14:15], v[44:45] op_sel:[0,1] op_sel_hi:[1,0]
	v_pk_mul_f32 v[44:45], v[14:15], v[44:45]
	v_sub_f32_e32 v46, v46, v47
	v_add_f32_e32 v49, v46, v11
	v_add_f32_e32 v44, v45, v44
	v_cndmask_b32_e64 v47, v1, v113, s[6:7]
	v_cndmask_b32_e64 v46, v0, v110, s[6:7]
	v_add_f32_e32 v44, v44, v3
	v_cndmask_b32_e64 v11, v11, v49, s[6:7]
	v_cndmask_b32_e64 v10, v10, v48, s[6:7]
	v_cndmask_b32_e64 v1, v9, v111, s[6:7]
	v_cndmask_b32_e64 v0, v8, v112, s[6:7]
	v_mov_b32_dpp v48, v46 row_shr:1 row_mask:0xf bank_mask:0xf bound_ctrl:1
	v_mov_b32_dpp v49, v47 row_shr:1 row_mask:0xf bank_mask:0xf bound_ctrl:1
	v_cndmask_b32_e64 v45, v3, v44, s[6:7]
	v_cndmask_b32_e64 v44, v2, v50, s[6:7]
	v_mov_b32_dpp v8, v0 row_shr:1 row_mask:0xf bank_mask:0xf bound_ctrl:1
	v_mov_b32_dpp v9, v1 row_shr:1 row_mask:0xf bank_mask:0xf bound_ctrl:1
	v_mov_b32_e32 v112, v4
	ds_read_b64 v[4:5], v109 offset:896
	v_mov_b32_e32 v113, v6
	ds_read_b64 v[6:7], v109 offset:904
	v_pk_mul_f32 v[2:3], v[114:115], v[48:49]
	v_pk_mul_f32 v[48:49], v[112:113], v[48:49]
	v_pk_fma_f32 v[2:3], v[112:113], v[8:9], v[2:3] neg_lo:[0,0,1] neg_hi:[0,0,1]
	v_pk_fma_f32 v[8:9], v[114:115], v[8:9], v[48:49]
	v_pk_add_f32 v[116:117], v[2:3], v[0:1]
	ds_read_b128 v[0:3], v109 offset:1408
	v_pk_add_f32 v[8:9], v[8:9], v[46:47]
	v_mov_b32_dpp v118, v116 row_shr:2 row_mask:0xf bank_mask:0xf bound_ctrl:1
	s_nop 0
	v_mov_b32_dpp v46, v8 row_shr:2 row_mask:0xf bank_mask:0xf bound_ctrl:1
	v_mov_b32_dpp v47, v9 row_shr:2 row_mask:0xf bank_mask:0xf bound_ctrl:1
	v_mov_b32_dpp v119, v117 row_shr:2 row_mask:0xf bank_mask:0xf bound_ctrl:1
	s_waitcnt lgkmcnt(1)
; #define SSM_SCAN_STEP(D, SQ) { _Pragma("unroll") for (int r = 0; r < 4; ++r) { \
;                     const float sr = dppf<DPP_SHR(D)>(Er[r]), si = dppf<DPP_SHR(D)>(Ei[r]); \
;                     Er[r] += mr[r] * sr - mi[r] * si; Ei[r] += mr[r] * si + mi[r] * sr; \
;                     if (SQ) { const float nr = mr[r] * mr[r] - mi[r] * mi[r], ni = 2.f * mr[r] * mi[r]; mr[r] = nr; mi[r] = ni; } } }
; template <bool PASS2>
; __device__ __forceinline__ void ssm_phase(const Params& p, const Frame& F0) {
;     ...
;             for (int i = 0; i < 4; ++i) {
;                 __builtin_amdgcn_sched_barrier(0);
;                 f32x4 Er = (f32x4){0.f, 0.f, 0.f, 0.f}, Ei = Er;
; #pragma unroll
;                 for (int ks = 0; ks < 4; ++ks) { Er = __builtin_amdgcn_mfma_f32_16x16x32_bf16(frag[(i * 4 + ks) * 64], uf[ks], Er, 0, 0, 0);
;                                                  Ei = __builtin_amdgcn_mfma_f32_16x16x32_bf16(frag[((i + 4) * 4 + ks) * 64], uf[ks], Ei, 0, 0, 0); }
;                 const f32x4 ma = m1t[8 * i], mb = m1t[8 * i + 1];
;                 float mr[4] = {ma[0], ma[2], mb[0], mb[2]}, mi[4] = {ma[1], ma[3], mb[1], mb[3]};
;                 float hr[4], hi[4];
; #pragma unroll
;                 for (int r = 0; r < 4; ++r) { hr[r] = dppf<DPP_ROR(1)>(xs[i][r]); hi[r] = dppf<DPP_ROR(1)>(xs[i + 4][r]);
;                     if (j == 0) { Er[r] += mr[r] * hr[r] - mi[r] * hi[r]; Ei[r] += mr[r] * hi[r] + mi[r] * hr[r]; } }
;     ...
;                 SSM_SCAN_STEP(1, 1) SSM_SCAN_STEP(2, 1) SSM_SCAN_STEP(4, 1) SSM_SCAN_STEP(8, 0)
;     ...
;         if constexpr (!PASS2) { if (j == 15) { float* wb = Wst + (size_t)((g * 2 + b) * 32 + wch) * 128;
	v_pk_mul_f32 v[48:49], v[6:7], v[46:47]
	v_pk_fma_f32 v[48:49], v[4:5], v[118:119], v[48:49] neg_lo:[0,0,1] neg_hi:[0,0,1]
	v_pk_mul_f32 v[4:5], v[4:5], v[46:47]
	v_pk_fma_f32 v[4:5], v[6:7], v[118:119], v[4:5]
	v_pk_add_f32 v[48:49], v[48:49], v[116:117]
	v_pk_add_f32 v[6:7], v[8:9], v[4:5]
	v_mov_b32_dpp v110, v44 row_shr:1 row_mask:0xf bank_mask:0xf bound_ctrl:1
	v_mov_b32_dpp v8, v48 row_shr:4 row_mask:0xf bank_mask:0xf bound_ctrl:1
	v_mov_b32_dpp v46, v6 row_shr:4 row_mask:0xf bank_mask:0xf bound_ctrl:1
	v_mov_b32_dpp v47, v7 row_shr:4 row_mask:0xf bank_mask:0xf bound_ctrl:1
	v_mov_b32_dpp v9, v49 row_shr:4 row_mask:0xf bank_mask:0xf bound_ctrl:1
	s_waitcnt lgkmcnt(0)
	v_pk_mul_f32 v[4:5], v[2:3], v[46:47]
	v_pk_mul_f32 v[46:47], v[0:1], v[46:47]
	v_pk_fma_f32 v[4:5], v[0:1], v[8:9], v[4:5] neg_lo:[0,0,1] neg_hi:[0,0,1]
	v_mov_b32_dpp v111, v45 row_shr:1 row_mask:0xf bank_mask:0xf bound_ctrl:1
	v_pk_add_f32 v[4:5], v[48:49], v[4:5]
	v_pk_fma_f32 v[8:9], v[2:3], v[8:9], v[46:47]
	v_mov_b32_e32 v48, v13
	v_mov_b32_e32 v49, v15
	v_mov_b32_dpp v50, v10 row_shr:1 row_mask:0xf bank_mask:0xf bound_ctrl:1
	v_mov_b32_dpp v51, v11 row_shr:1 row_mask:0xf bank_mask:0xf bound_ctrl:1
	v_pk_add_f32 v[6:7], v[6:7], v[8:9]
	v_mov_b32_e32 v46, v12
	ds_read_b64 v[12:13], v109 offset:912
	v_mov_b32_e32 v47, v14
	ds_read_b64 v[14:15], v109 offset:920
	v_pk_mul_f32 v[8:9], v[48:49], v[110:111]
	s_nop 0
	v_pk_fma_f32 v[8:9], v[46:47], v[50:51], v[8:9] neg_lo:[0,0,1] neg_hi:[0,0,1]
	s_nop 0
	v_pk_add_f32 v[112:113], v[8:9], v[10:11]
	ds_read_b128 v[8:11], v109 offset:1424
	v_pk_mul_f32 v[46:47], v[46:47], v[110:111]
	v_pk_fma_f32 v[46:47], v[48:49], v[50:51], v[46:47]
	v_mov_b32_dpp v114, v112 row_shr:2 row_mask:0xf bank_mask:0xf bound_ctrl:1
	v_pk_add_f32 v[44:45], v[46:47], v[44:45]
	v_mov_b32_dpp v115, v113 row_shr:2 row_mask:0xf bank_mask:0xf bound_ctrl:1
	s_nop 0
	v_mov_b32_dpp v46, v44 row_shr:2 row_mask:0xf bank_mask:0xf bound_ctrl:1
	v_mov_b32_dpp v47, v45 row_shr:2 row_mask:0xf bank_mask:0xf bound_ctrl:1
	s_waitcnt lgkmcnt(1)
	v_pk_mul_f32 v[48:49], v[14:15], v[46:47]
	v_pk_fma_f32 v[48:49], v[12:13], v[114:115], v[48:49] neg_lo:[0,0,1] neg_hi:[0,0,1]
	v_pk_mul_f32 v[12:13], v[12:13], v[46:47]
	v_pk_fma_f32 v[12:13], v[14:15], v[114:115], v[12:13]
	v_pk_add_f32 v[48:49], v[112:113], v[48:49]
	v_pk_add_f32 v[14:15], v[44:45], v[12:13]
	s_nop 0
	v_mov_b32_dpp v44, v48 row_shr:4 row_mask:0xf bank_mask:0xf bound_ctrl:1
	v_mov_b32_dpp v46, v14 row_shr:4 row_mask:0xf bank_mask:0xf bound_ctrl:1
	v_mov_b32_dpp v47, v15 row_shr:4 row_mask:0xf bank_mask:0xf bound_ctrl:1
	v_mov_b32_dpp v45, v49 row_shr:4 row_mask:0xf bank_mask:0xf bound_ctrl:1
	s_waitcnt lgkmcnt(0)
	v_pk_mul_f32 v[12:13], v[10:11], v[46:47]
	v_pk_mul_f32 v[46:47], v[8:9], v[46:47]
	v_pk_fma_f32 v[12:13], v[8:9], v[44:45], v[12:13] neg_lo:[0,0,1] neg_hi:[0,0,1]
	v_pk_fma_f32 v[44:45], v[10:11], v[44:45], v[46:47]
	v_pk_add_f32 v[12:13], v[48:49], v[12:13]
	v_pk_add_f32 v[44:45], v[14:15], v[44:45]
	v_mov_b32_dpp v14, v4 row_shr:8 row_mask:0xf bank_mask:0xf bound_ctrl:1
	v_mov_b32_dpp v46, v6 row_shr:8 row_mask:0xf bank_mask:0xf bound_ctrl:1
	v_mov_b32_dpp v15, v5 row_shr:8 row_mask:0xf bank_mask:0xf bound_ctrl:1
	v_mov_b32_dpp v47, v7 row_shr:8 row_mask:0xf bank_mask:0xf bound_ctrl:1
	v_mov_b32_dpp v48, v12 row_shr:8 row_mask:0xf bank_mask:0xf bound_ctrl:1
	v_mov_b32_dpp v50, v44 row_shr:8 row_mask:0xf bank_mask:0xf bound_ctrl:1
	v_mov_b32_dpp v49, v13 row_shr:8 row_mask:0xf bank_mask:0xf bound_ctrl:1
	v_mov_b32_dpp v51, v45 row_shr:8 row_mask:0xf bank_mask:0xf bound_ctrl:1
	s_and_saveexec_b64 s[0:1], s[8:9]
	s_cbranch_execz .LBB0_520
; #define SSM_SCAN_STEP(D, SQ) { _Pragma("unroll") for (int r = 0; r < 4; ++r) { \
;                     const float sr = dppf<DPP_SHR(D)>(Er[r]), si = dppf<DPP_SHR(D)>(Ei[r]); \
;                     Er[r] += mr[r] * sr - mi[r] * si; Ei[r] += mr[r] * si + mi[r] * sr; \
;                     if (SQ) { const float nr = mr[r] * mr[r] - mi[r] * mi[r], ni = 2.f * mr[r] * mi[r]; mr[r] = nr; mi[r] = ni; } } }
; template <bool PASS2>
; __device__ __forceinline__ void ssm_phase(const Params& p, const Frame& F0) {
;     ...
;                 SSM_SCAN_STEP(1, 1) SSM_SCAN_STEP(2, 1) SSM_SCAN_STEP(4, 1) SSM_SCAN_STEP(8, 0)
;     ...
;         if constexpr (!PASS2) { if (j == 15) { float* wb = Wst + (size_t)((g * 2 + b) * 32 + wch) * 128;
; #pragma unroll
;                 for (int i = 0; i < 4; ++i) { *(f32x4*)(wb + 16 * i + 4 * gq) = xs[i]; *(f32x4*)(wb + 64 + 16 * i + 4 * gq) = xs[i + 4]; } } }
	v_pk_mul_f32 v[112:113], v[54:55], v[54:55]
	v_pk_add_f32 v[110:111], v[52:53], v[52:53]
	v_pk_mul_f32 v[116:117], v[90:91], v[90:91]
	v_pk_fma_f32 v[112:113], v[52:53], v[52:53], v[112:113] neg_lo:[0,0,1] neg_hi:[0,0,1]
	v_pk_add_f32 v[114:115], v[88:89], v[88:89]
	v_pk_mul_f32 v[110:111], v[54:55], v[110:111]
	v_pk_fma_f32 v[88:89], v[88:89], v[88:89], v[116:117] neg_lo:[0,0,1] neg_hi:[0,0,1]
	v_pk_mul_f32 v[52:53], v[112:113], v[100:101]
	v_pk_mul_f32 v[90:91], v[90:91], v[114:115]
	v_pk_mul_f32 v[54:55], v[88:89], v[102:103]
	v_pk_fma_f32 v[52:53], v[110:111], v[94:95], v[52:53]
	v_pk_fma_f32 v[54:55], v[90:91], v[98:99], v[54:55]
	v_pk_add_f32 v[52:53], v[58:59], v[52:53]
	v_pk_mul_f32 v[58:59], v[110:111], v[100:101]
	v_pk_mul_f32 v[90:91], v[90:91], v[102:103]
	v_pk_fma_f32 v[58:59], v[112:113], v[94:95], v[58:59] neg_lo:[0,0,1] neg_hi:[0,0,1]
	v_pk_fma_f32 v[88:89], v[88:89], v[98:99], v[90:91] neg_lo:[0,0,1] neg_hi:[0,0,1]
	v_pk_mul_f32 v[90:91], v[62:63], v[62:63]
	v_pk_add_f32 v[56:57], v[56:57], v[58:59]
	v_pk_add_f32 v[58:59], v[92:93], v[88:89]
	v_pk_add_f32 v[88:89], v[60:61], v[60:61]
	v_pk_mul_f32 v[94:95], v[74:75], v[74:75]
	v_pk_fma_f32 v[90:91], v[60:61], v[60:61], v[90:91] neg_lo:[0,0,1] neg_hi:[0,0,1]
	v_pk_add_f32 v[92:93], v[72:73], v[72:73]
	v_pk_mul_f32 v[88:89], v[62:63], v[88:89]
	v_pk_fma_f32 v[72:73], v[72:73], v[72:73], v[94:95] neg_lo:[0,0,1] neg_hi:[0,0,1]
	v_pk_mul_f32 v[60:61], v[90:91], v[84:85]
	v_pk_mul_f32 v[74:75], v[74:75], v[92:93]
	v_pk_mul_f32 v[62:63], v[72:73], v[86:87]
	v_pk_fma_f32 v[60:61], v[88:89], v[78:79], v[60:61]
	v_pk_fma_f32 v[62:63], v[74:75], v[82:83], v[62:63]
	v_pk_add_f32 v[60:61], v[68:69], v[60:61]
	v_pk_mul_f32 v[68:69], v[88:89], v[84:85]
	v_pk_mul_f32 v[74:75], v[74:75], v[86:87]
	v_pk_fma_f32 v[68:69], v[90:91], v[78:79], v[68:69] neg_lo:[0,0,1] neg_hi:[0,0,1]
	v_pk_fma_f32 v[72:73], v[72:73], v[82:83], v[74:75] neg_lo:[0,0,1] neg_hi:[0,0,1]
	v_pk_mul_f32 v[74:75], v[18:19], v[18:19]
	v_pk_add_f32 v[66:67], v[66:67], v[68:69]
	v_pk_add_f32 v[68:69], v[76:77], v[72:73]
	v_pk_add_f32 v[72:73], v[16:17], v[16:17]
	v_pk_mul_f32 v[78:79], v[26:27], v[26:27]
	v_pk_fma_f32 v[74:75], v[16:17], v[16:17], v[74:75] neg_lo:[0,0,1] neg_hi:[0,0,1]
	v_pk_add_f32 v[76:77], v[24:25], v[24:25]
	v_pk_mul_f32 v[72:73], v[18:19], v[72:73]
	v_pk_fma_f32 v[24:25], v[24:25], v[24:25], v[78:79] neg_lo:[0,0,1] neg_hi:[0,0,1]
	v_pk_mul_f32 v[16:17], v[74:75], v[64:65]
	v_pk_mul_f32 v[26:27], v[26:27], v[76:77]
	v_pk_mul_f32 v[18:19], v[24:25], v[70:71]
	v_pk_fma_f32 v[16:17], v[72:73], v[30:31], v[16:17]
	v_pk_fma_f32 v[18:19], v[26:27], v[34:35], v[18:19]
	v_pk_add_f32 v[16:17], v[22:23], v[16:17]
	v_pk_mul_f32 v[22:23], v[72:73], v[64:65]
	v_pk_mul_f32 v[26:27], v[26:27], v[70:71]
	v_pk_fma_f32 v[22:23], v[74:75], v[30:31], v[22:23] neg_lo:[0,0,1] neg_hi:[0,0,1]
	v_pk_fma_f32 v[24:25], v[24:25], v[34:35], v[26:27] neg_lo:[0,0,1] neg_hi:[0,0,1]
	v_pk_mul_f32 v[30:31], v[2:3], v[2:3]
	v_pk_add_f32 v[20:21], v[20:21], v[22:23]
	v_pk_add_f32 v[22:23], v[28:29], v[24:25]
	v_pk_mul_f32 v[26:27], v[10:11], v[10:11]
	v_pk_add_f32 v[28:29], v[0:1], v[0:1]
	v_pk_fma_f32 v[30:31], v[0:1], v[0:1], v[30:31] neg_lo:[0,0,1] neg_hi:[0,0,1]
	s_lshl_b32 s10, s16, 6
	s_lshl_b32 s16, s17, 5
	v_pk_add_f32 v[24:25], v[8:9], v[8:9]
	v_pk_mul_f32 v[28:29], v[2:3], v[28:29]
	v_pk_fma_f32 v[8:9], v[8:9], v[8:9], v[26:27] neg_lo:[0,0,1] neg_hi:[0,0,1]
	v_pk_mul_f32 v[0:1], v[30:31], v[46:47]
	s_add_i32 s16, s18, s16
	v_pk_mul_f32 v[10:11], v[10:11], v[24:25]
	v_pk_mul_f32 v[2:3], v[8:9], v[50:51]
	v_pk_fma_f32 v[0:1], v[28:29], v[14:15], v[0:1]
	s_add_i32 s16, s16, s10
	v_pk_fma_f32 v[2:3], v[10:11], v[48:49], v[2:3]
	v_pk_add_f32 v[0:1], v[6:7], v[0:1]
	v_pk_mul_f32 v[6:7], v[28:29], v[46:47]
	v_pk_mul_f32 v[10:11], v[10:11], v[50:51]
	s_ashr_i32 s17, s16, 31
	v_pk_fma_f32 v[6:7], v[30:31], v[14:15], v[6:7] neg_lo:[0,0,1] neg_hi:[0,0,1]
	v_pk_fma_f32 v[8:9], v[8:9], v[48:49], v[10:11] neg_lo:[0,0,1] neg_hi:[0,0,1]
	s_lshl_b64 s[16:17], s[16:17], 9
	v_pk_add_f32 v[4:5], v[4:5], v[6:7]
	v_pk_add_f32 v[6:7], v[12:13], v[8:9]
	v_lshl_add_u64 v[8:9], v[40:41], 0, s[16:17]
	v_pk_add_f32 v[54:55], v[96:97], v[54:55]
	v_pk_add_f32 v[62:63], v[80:81], v[62:63]
	v_pk_add_f32 v[18:19], v[32:33], v[18:19]
	v_pk_add_f32 v[2:3], v[44:45], v[2:3]
	global_store_dwordx4 v[8:9], v[20:23], off
	global_store_dwordx4 v[8:9], v[16:19], off offset:256
	global_store_dwordx4 v[8:9], v[66:69], off offset:64
	global_store_dwordx4 v[8:9], v[60:63], off offset:320
	global_store_dwordx4 v[8:9], v[56:59], off offset:128
	global_store_dwordx4 v[8:9], v[52:55], off offset:384
	global_store_dwordx4 v[8:9], v[4:7], off offset:192
	global_store_dwordx4 v[8:9], v[0:3], off offset:448
	s_branch .LBB0_520

; #define LAS __attribute__((address_space(3)))
; template <bool PASS2>
; __device__ __forceinline__ void ssm_phase(const Params& p, const Frame& F0) {
;     ...
;         { const u32x4* src = (const u32x4*)((const bf16_t*)(p.ws + WS_SSMW) + (size_t)g * SSM_FRAG_ELEMS);
;           for (int e = F.tid; e < SSM_FRAG_ELEMS / 8; e += 512) ((LAS u32x4*)F.lds)[e] = src[e];
;           if (F.tid < 64) ((LAS f32x2*)(F.lds + SSM_M1_OFF))[F.tid] = ((const f32x2*)(p.ws + WS_M1))[g * 64 + F.tid]; }
.LBB0_610:
	s_or_b64 exec, exec, s[16:17]
	s_lshl_b32 s0, s90, 2
	s_and_b32 s0, s0, 28
	s_and_b32 s3, s3, 3
	s_or_b32 s3, s0, s3
	s_and_saveexec_b64 s[16:17], s[6:7]
	s_cbranch_execz .LBB0_612
	v_lshl_add_u32 v2, s3, 6, v92
	v_ashrrev_i32_e32 v3, 31, v2
	v_lshl_add_u64 v[2:3], v[2:3], 3, s[68:69]
	global_load_dwordx2 v[2:3], v[2:3], off
	s_waitcnt vmcnt(0)
	ds_write_b64 v103, v[2:3]
	v_bfe_u32 v26, v103, 3, 1
	v_lshlrev_b32_e32 v26, 2, v26
	v_sub_u32_e32 v26, v103, v26
	v_mul_f32_e32 v27, v3, v3
	v_add_f32_e32 v28, v2, v2
	v_fma_f32 v29, v2, v2, -v27
	v_mul_f32_e32 v30, v28, v3
	ds_write_b32 v26, v29 offset:512
	ds_write_b32 v26, v30 offset:520
	v_mul_f32_e32 v27, v30, v30
	v_add_f32_e32 v28, v29, v29
	v_fma_f32 v31, v29, v29, -v27
	v_mul_f32_e32 v32, v28, v30
	ds_write_b32 v26, v31 offset:1024
	ds_write_b32 v26, v32 offset:1032
	v_mul_f32_e32 v27, v32, v32
	v_add_f32_e32 v28, v31, v31
	v_fma_f32 v29, v31, v31, -v27
	v_mul_f32_e32 v30, v28, v32
	ds_write_b32 v26, v29 offset:1536
	ds_write_b32 v26, v30 offset:1544

; __device__ __forceinline__ unsigned cvt_pk_bf16(float lo, float hi) { unsigned r; asm("v_cvt_pk_bf16_f32 %0, %1, %2" : "=v"(r) : "v"(lo), "v"(hi)); return r; }
; #define SSM_SCAN_STEP(D, SQ) { _Pragma("unroll") for (int r = 0; r < 4; ++r) { \
;                     const float sr = dppf<DPP_SHR(D)>(Er[r]), si = dppf<DPP_SHR(D)>(Ei[r]); \
;                     Er[r] += mr[r] * sr - mi[r] * si; Ei[r] += mr[r] * si + mi[r] * sr; \
;                     if (SQ) { const float nr = mr[r] * mr[r] - mi[r] * mi[r], ni = 2.f * mr[r] * mi[r]; mr[r] = nr; mi[r] = ni; } } }
; template <bool PASS2>
; __device__ __forceinline__ void ssm_phase(const Params& p, const Frame& F0) {
;     ...
;             for (int i = 0; i < 4; ++i) {
;                 __builtin_amdgcn_sched_barrier(0);
;                 f32x4 Er = (f32x4){0.f, 0.f, 0.f, 0.f}, Ei = Er;
; #pragma unroll
;                 for (int ks = 0; ks < 4; ++ks) { Er = __builtin_amdgcn_mfma_f32_16x16x32_bf16(frag[(i * 4 + ks) * 64], uf[ks], Er, 0, 0, 0);
;                                                  Ei = __builtin_amdgcn_mfma_f32_16x16x32_bf16(frag[((i + 4) * 4 + ks) * 64], uf[ks], Ei, 0, 0, 0); }
;                 const f32x4 ma = m1t[8 * i], mb = m1t[8 * i + 1];
;                 float mr[4] = {ma[0], ma[2], mb[0], mb[2]}, mi[4] = {ma[1], ma[3], mb[1], mb[3]};
;                 float hr[4], hi[4];
; #pragma unroll
;                 for (int r = 0; r < 4; ++r) { hr[r] = dppf<DPP_ROR(1)>(xs[i][r]); hi[r] = dppf<DPP_ROR(1)>(xs[i + 4][r]);
;                     if (j == 0) { Er[r] += mr[r] * hr[r] - mi[r] * hi[r]; Ei[r] += mr[r] * hi[r] + mi[r] * hr[r]; } }
;     ...
;                 SSM_SCAN_STEP(1, 1) SSM_SCAN_STEP(2, 1) SSM_SCAN_STEP(4, 1) SSM_SCAN_STEP(8, 0)
;     ...
;                 if constexpr (PASS2) {
;                     float vr[4], vi[4];
; #pragma unroll
;                     for (int r = 0; r < 4; ++r) { const float pr_ = dppf<DPP_ROR(1)>(Er[r]), pi_ = dppf<DPP_ROR(1)>(Ei[r]); vr[r] = (j == 0) ? hr[r] : pr_; vi[r] = (j == 0) ? hi[r] : pi_; }
;                     hw[i >> 1][2 * (i & 1)] = cvt_pk_bf16(vr[0], vr[1]); hw[i >> 1][2 * (i & 1) + 1] = cvt_pk_bf16(vr[2], vr[3]);
;                     hw[2 + (i >> 1)][2 * (i & 1)] = cvt_pk_bf16(vi[0], vi[1]); hw[2 + (i >> 1)][2 * (i & 1) + 1] = cvt_pk_bf16(vi[2], vi[3]);
.Lssmw_2:
	ds_read_b128 v[84:87], v105 offset:3072
	ds_read_b128 v[88:91], v105 offset:19456
	s_waitcnt lgkmcnt(2)
	v_mfma_f32_16x16x32_bf16 v[76:79], v[80:83], v[64:67], v[76:79]
	v_mov_b32_dpp v83, v38 row_ror:1 row_mask:0xf bank_mask:0xf bound_ctrl:1
	v_mov_b32_dpp v82, v42 row_ror:1 row_mask:0xf bank_mask:0xf bound_ctrl:1
	v_mfma_f32_16x16x32_bf16 v[68:71], v[72:75], v[64:67], v[68:71]
	ds_read_b128 v[72:75], v198
	ds_read_b128 v[204:207], v198 offset:16
	ds_read_b128 v[208:211], v198 offset:1024
	ds_read_b128 v[212:215], v198 offset:1536
	s_waitcnt lgkmcnt(3)
	v_pk_mul_f32 v[80:81], v[72:73], v[2:3] op_sel:[0,1] op_sel_hi:[1,0]
	v_mfma_f32_16x16x32_bf16 v[76:79], v[88:91], v[60:63], v[76:79]
	v_sub_f32_e32 v1, v80, v81
	v_pk_mul_f32 v[80:81], v[72:73], v[2:3]
	v_mov_b32_e32 v90, v73
	v_mfma_f32_16x16x32_bf16 v[68:71], v[84:87], v[60:63], v[68:71]
	v_add_f32_e32 v36, v81, v80
	v_mov_b32_dpp v81, v37 row_ror:1 row_mask:0xf bank_mask:0xf bound_ctrl:1
	v_mov_b32_dpp v80, v41 row_ror:1 row_mask:0xf bank_mask:0xf bound_ctrl:1
	s_nop 0
	v_add_f32_e32 v40, v76, v36
	v_pk_mul_f32 v[36:37], v[74:75], v[80:81] op_sel:[0,1] op_sel_hi:[1,0]
	v_mov_b32_dpp v85, v39 row_ror:1 row_mask:0xf bank_mask:0xf bound_ctrl:1
	v_sub_f32_e32 v36, v36, v37
	v_add_f32_e32 v41, v36, v69
	v_pk_mul_f32 v[36:37], v[74:75], v[80:81]
	v_mov_b32_dpp v84, v43 row_ror:1 row_mask:0xf bank_mask:0xf bound_ctrl:1
	v_add_f32_e32 v36, v37, v36
	v_add_f32_e32 v86, v36, v77
	s_waitcnt lgkmcnt(2)
	v_pk_mul_f32 v[36:37], v[204:205], v[82:83] op_sel:[0,1] op_sel_hi:[1,0]
	v_add_f32_e32 v1, v68, v1
	v_sub_f32_e32 v36, v36, v37
	v_add_f32_e32 v42, v36, v70
	v_pk_mul_f32 v[36:37], v[204:205], v[82:83]
	v_cndmask_b32_e64 v42, v70, v42, s[10:11]
	v_add_f32_e32 v36, v37, v36
	v_add_f32_e32 v38, v36, v78
	v_pk_mul_f32 v[36:37], v[206:207], v[84:85] op_sel:[0,1] op_sel_hi:[1,0]
	v_cndmask_b32_e64 v41, v69, v41, s[10:11]
	v_sub_f32_e32 v36, v36, v37
	v_add_f32_e32 v43, v36, v71
	v_pk_mul_f32 v[36:37], v[206:207], v[84:85]
	v_cndmask_b32_e64 v43, v71, v43, s[10:11]
	v_add_f32_e32 v36, v37, v36
	v_add_f32_e32 v36, v36, v79
	v_cndmask_b32_e64 v39, v79, v36, s[10:11]
	v_cndmask_b32_e64 v37, v77, v86, s[10:11]
	v_cndmask_b32_e64 v36, v76, v40, s[10:11]
	v_cndmask_b32_e64 v40, v68, v1, s[10:11]
	v_mov_b32_dpp v71, v37 row_shr:1 row_mask:0xf bank_mask:0xf bound_ctrl:1
	v_mov_b32_dpp v70, v36 row_shr:1 row_mask:0xf bank_mask:0xf bound_ctrl:1
	v_mov_b32_e32 v86, v72
	v_mov_b32_e32 v87, v74
	v_mov_b32_dpp v68, v40 row_shr:1 row_mask:0xf bank_mask:0xf bound_ctrl:1
	v_mov_b32_dpp v69, v41 row_shr:1 row_mask:0xf bank_mask:0xf bound_ctrl:1
	v_pk_mul_f32 v[88:89], v[86:87], v[70:71]
	v_mov_b32_e32 v91, v75
	ds_read_b128 v[72:75], v198 offset:512
	v_pk_fma_f32 v[88:89], v[90:91], v[68:69], v[88:89]
	v_pk_add_f32 v[36:37], v[88:89], v[36:37]
	v_pk_mul_f32 v[70:71], v[90:91], v[70:71]
	ds_read_b64 v[90:91], v198 offset:1040
	v_pk_fma_f32 v[68:69], v[86:87], v[68:69], v[70:71] neg_lo:[0,0,1] neg_hi:[0,0,1]
	v_mov_b32_dpp v88, v36 row_shr:2 row_mask:0xf bank_mask:0xf bound_ctrl:1
	v_mov_b32_dpp v89, v37 row_shr:2 row_mask:0xf bank_mask:0xf bound_ctrl:1
	v_pk_add_f32 v[40:41], v[68:69], v[40:41]
	s_waitcnt lgkmcnt(1)
	v_pk_mul_f32 v[200:201], v[72:73], v[88:89]
	v_pk_mul_f32 v[70:71], v[74:75], v[88:89]
	v_mov_b32_dpp v68, v40 row_shr:2 row_mask:0xf bank_mask:0xf bound_ctrl:1
	v_mov_b32_dpp v69, v41 row_shr:2 row_mask:0xf bank_mask:0xf bound_ctrl:1
	v_pk_fma_f32 v[70:71], v[72:73], v[68:69], v[70:71] neg_lo:[0,0,1] neg_hi:[0,0,1]
	v_pk_fma_f32 v[68:69], v[74:75], v[68:69], v[200:201]
	ds_read_b64 v[74:75], v198 offset:536
	ds_read_b64 v[200:201], v198 offset:1048
	v_pk_add_f32 v[36:37], v[36:37], v[68:69]
	v_pk_add_f32 v[40:41], v[70:71], v[40:41]
	s_nop 0
	v_mov_b32_dpp v70, v36 row_shr:4 row_mask:0xf bank_mask:0xf bound_ctrl:1
	v_mov_b32_dpp v71, v37 row_shr:4 row_mask:0xf bank_mask:0xf bound_ctrl:1
	v_mov_b32_dpp v68, v40 row_shr:4 row_mask:0xf bank_mask:0xf bound_ctrl:1
	v_mov_b32_dpp v69, v41 row_shr:4 row_mask:0xf bank_mask:0xf bound_ctrl:1
	v_pk_mul_f32 v[72:73], v[210:211], v[70:71]
	v_pk_mul_f32 v[70:71], v[208:209], v[70:71]
	v_pk_fma_f32 v[72:73], v[208:209], v[68:69], v[72:73] neg_lo:[0,0,1] neg_hi:[0,0,1]
	v_pk_fma_f32 v[68:69], v[210:211], v[68:69], v[70:71]
	v_pk_add_f32 v[68:69], v[36:37], v[68:69]
	v_pk_add_f32 v[40:41], v[40:41], v[72:73]
	s_nop 0
	v_mov_b32_dpp v72, v68 row_shr:8 row_mask:0xf bank_mask:0xf bound_ctrl:1
	v_mov_b32_dpp v73, v69 row_shr:8 row_mask:0xf bank_mask:0xf bound_ctrl:1
	v_mov_b32_dpp v70, v40 row_shr:8 row_mask:0xf bank_mask:0xf bound_ctrl:1
	v_mov_b32_dpp v71, v41 row_shr:8 row_mask:0xf bank_mask:0xf bound_ctrl:1
	v_pk_mul_f32 v[36:37], v[214:215], v[72:73]
	v_cndmask_b32_e64 v38, v78, v38, s[10:11]
	v_pk_fma_f32 v[36:37], v[212:213], v[70:71], v[36:37] neg_lo:[0,0,1] neg_hi:[0,0,1]
	v_mov_b32_dpp v79, v39 row_shr:1 row_mask:0xf bank_mask:0xf bound_ctrl:1
	v_pk_add_f32 v[36:37], v[40:41], v[36:37]
	v_pk_mul_f32 v[40:41], v[212:213], v[72:73]
	v_mov_b32_dpp v78, v38 row_shr:1 row_mask:0xf bank_mask:0xf bound_ctrl:1
	v_pk_fma_f32 v[40:41], v[214:215], v[70:71], v[40:41]
	v_mov_b32_dpp v76, v42 row_shr:1 row_mask:0xf bank_mask:0xf bound_ctrl:1
	v_pk_add_f32 v[40:41], v[68:69], v[40:41]
	v_mov_b32_e32 v68, v204
	v_mov_b32_e32 v69, v206
	v_mov_b32_dpp v77, v43 row_shr:1 row_mask:0xf bank_mask:0xf bound_ctrl:1
	v_pk_mul_f32 v[70:71], v[68:69], v[78:79]
	v_mov_b32_e32 v72, v205
	v_mov_b32_e32 v73, v207
	ds_read_b128 v[204:207], v198 offset:1552
	v_pk_fma_f32 v[70:71], v[72:73], v[76:77], v[70:71]
	v_pk_add_f32 v[38:39], v[70:71], v[38:39]
	ds_read_b64 v[70:71], v198 offset:528
	v_pk_mul_f32 v[72:73], v[72:73], v[78:79]
	v_mov_b32_dpp v86, v38 row_shr:2 row_mask:0xf bank_mask:0xf bound_ctrl:1
	v_pk_fma_f32 v[68:69], v[68:69], v[76:77], v[72:73] neg_lo:[0,0,1] neg_hi:[0,0,1]
	v_mov_b32_dpp v87, v39 row_shr:2 row_mask:0xf bank_mask:0xf bound_ctrl:1
	v_pk_add_f32 v[42:43], v[68:69], v[42:43]
	s_waitcnt lgkmcnt(0)
; __device__ __forceinline__ unsigned cvt_pk_bf16(float lo, float hi) { unsigned r; asm("v_cvt_pk_bf16_f32 %0, %1, %2" : "=v"(r) : "v"(lo), "v"(hi)); return r; }
; #define SSM_SCAN_STEP(D, SQ) { _Pragma("unroll") for (int r = 0; r < 4; ++r) { \
;                     const float sr = dppf<DPP_SHR(D)>(Er[r]), si = dppf<DPP_SHR(D)>(Ei[r]); \
;                     Er[r] += mr[r] * sr - mi[r] * si; Ei[r] += mr[r] * si + mi[r] * sr; \
;                     if (SQ) { const float nr = mr[r] * mr[r] - mi[r] * mi[r], ni = 2.f * mr[r] * mi[r]; mr[r] = nr; mi[r] = ni; } } }
; template <bool PASS2>
; __device__ __forceinline__ void ssm_phase(const Params& p, const Frame& F0) {
;     ...
;                 SSM_SCAN_STEP(1, 1) SSM_SCAN_STEP(2, 1) SSM_SCAN_STEP(4, 1) SSM_SCAN_STEP(8, 0)
;     ...
;                 if constexpr (PASS2) {
;                     float vr[4], vi[4];
; #pragma unroll
;                     for (int r = 0; r < 4; ++r) { const float pr_ = dppf<DPP_ROR(1)>(Er[r]), pi_ = dppf<DPP_ROR(1)>(Ei[r]); vr[r] = (j == 0) ? hr[r] : pr_; vi[r] = (j == 0) ? hi[r] : pi_; }
;                     hw[i >> 1][2 * (i & 1)] = cvt_pk_bf16(vr[0], vr[1]); hw[i >> 1][2 * (i & 1) + 1] = cvt_pk_bf16(vr[2], vr[3]);
;                     hw[2 + (i >> 1)][2 * (i & 1)] = cvt_pk_bf16(vi[0], vi[1]); hw[2 + (i >> 1)][2 * (i & 1) + 1] = cvt_pk_bf16(vi[2], vi[3]);
;                 }
;                 xs[i] = Er; xs[i + 4] = Ei;
	v_pk_mul_f32 v[88:89], v[70:71], v[86:87]
	v_mov_b32_dpp v68, v42 row_shr:2 row_mask:0xf bank_mask:0xf bound_ctrl:1
	v_mov_b32_dpp v69, v43 row_shr:2 row_mask:0xf bank_mask:0xf bound_ctrl:1
	v_pk_mul_f32 v[72:73], v[74:75], v[86:87]
	v_pk_fma_f32 v[70:71], v[70:71], v[68:69], v[72:73] neg_lo:[0,0,1] neg_hi:[0,0,1]
	v_pk_fma_f32 v[68:69], v[74:75], v[68:69], v[88:89]
	v_pk_add_f32 v[38:39], v[38:39], v[68:69]
	v_pk_add_f32 v[42:43], v[42:43], v[70:71]
	s_nop 0
	v_mov_b32_dpp v70, v38 row_shr:4 row_mask:0xf bank_mask:0xf bound_ctrl:1
	v_mov_b32_dpp v71, v39 row_shr:4 row_mask:0xf bank_mask:0xf bound_ctrl:1
	v_mov_b32_dpp v68, v42 row_shr:4 row_mask:0xf bank_mask:0xf bound_ctrl:1
	v_mov_b32_dpp v69, v43 row_shr:4 row_mask:0xf bank_mask:0xf bound_ctrl:1
	v_pk_mul_f32 v[72:73], v[200:201], v[70:71]
	v_pk_mul_f32 v[70:71], v[90:91], v[70:71]
	v_pk_fma_f32 v[72:73], v[90:91], v[68:69], v[72:73] neg_lo:[0,0,1] neg_hi:[0,0,1]
	v_pk_fma_f32 v[68:69], v[200:201], v[68:69], v[70:71]
	v_pk_add_f32 v[68:69], v[38:39], v[68:69]
	v_pk_add_f32 v[42:43], v[42:43], v[72:73]
	s_nop 0
	v_mov_b32_dpp v72, v68 row_shr:8 row_mask:0xf bank_mask:0xf bound_ctrl:1
	v_mov_b32_dpp v73, v69 row_shr:8 row_mask:0xf bank_mask:0xf bound_ctrl:1
	v_mov_b32_dpp v70, v42 row_shr:8 row_mask:0xf bank_mask:0xf bound_ctrl:1
	v_mov_b32_dpp v71, v43 row_shr:8 row_mask:0xf bank_mask:0xf bound_ctrl:1
	v_pk_mul_f32 v[38:39], v[206:207], v[72:73]
	v_mov_b32_dpp v1, v36 row_ror:1 row_mask:0xf bank_mask:0xf bound_ctrl:1
	v_pk_fma_f32 v[38:39], v[204:205], v[70:71], v[38:39] neg_lo:[0,0,1] neg_hi:[0,0,1]
	v_cndmask_b32_e64 v1, v1, v3, s[10:11]
	v_pk_add_f32 v[38:39], v[42:43], v[38:39]
	v_pk_mul_f32 v[42:43], v[204:205], v[72:73]
	v_mov_b32_dpp v3, v37 row_ror:1 row_mask:0xf bank_mask:0xf bound_ctrl:1
	v_pk_fma_f32 v[42:43], v[206:207], v[70:71], v[42:43]
	v_mov_b32_dpp v71, v39 row_ror:1 row_mask:0xf bank_mask:0xf bound_ctrl:1
	v_pk_add_f32 v[42:43], v[68:69], v[42:43]
	v_mov_b32_dpp v68, v40 row_ror:1 row_mask:0xf bank_mask:0xf bound_ctrl:1
	v_cndmask_b32_e64 v2, v68, v2, s[10:11]
	v_mov_b32_dpp v69, v38 row_ror:1 row_mask:0xf bank_mask:0xf bound_ctrl:1
	v_mov_b32_dpp v68, v41 row_ror:1 row_mask:0xf bank_mask:0xf bound_ctrl:1
	v_mov_b32_dpp v70, v42 row_ror:1 row_mask:0xf bank_mask:0xf bound_ctrl:1
	v_mov_b32_dpp v72, v43 row_ror:1 row_mask:0xf bank_mask:0xf bound_ctrl:1
	v_cndmask_b32_e64 v68, v68, v80, s[10:11]
	v_cndmask_b32_e64 v69, v69, v83, s[10:11]
	v_cndmask_b32_e64 v70, v70, v82, s[10:11]
	v_cndmask_b32_e64 v71, v71, v85, s[10:11]
	v_cndmask_b32_e64 v74, v72, v84, s[10:11]
	v_cndmask_b32_e64 v3, v3, v81, s[10:11]
	v_cvt_pk_bf16_f32 v72, v1, v3
	v_cvt_pk_bf16_f32 v73, v69, v71
	v_cvt_pk_bf16_f32 v68, v2, v68
	v_cvt_pk_bf16_f32 v69, v70, v74
	ds_read_b128 v[74:77], v105 offset:4096
	ds_read_b128 v[78:81], v105 offset:5120
	ds_read_b128 v[82:85], v105 offset:20480
	ds_read_b128 v[86:89], v105 offset:21504
	v_mov_b32_dpp v3, v28 row_ror:1 row_mask:0xf bank_mask:0xf bound_ctrl:1
	s_and_b32 s98, s3, 0x180
	s_cbranch_scc1 .Lssmw_3
	s_waitcnt vmcnt(4)
.Lssmw_3:
	v_mov_b32_dpp v2, v32 row_ror:1 row_mask:0xf bank_mask:0xf bound_ctrl:1
	s_waitcnt lgkmcnt(3)
	v_mfma_f32_16x16x32_bf16 v[74:77], v[74:77], v[56:59], 0
	s_waitcnt lgkmcnt(1)
	v_mfma_f32_16x16x32_bf16 v[82:85], v[82:85], v[56:59], 0
	v_mfma_f32_16x16x32_bf16 v[74:77], v[78:81], v[52:55], v[74:77]
	ds_read_b128 v[78:81], v105 offset:6144
	s_waitcnt lgkmcnt(1)
	v_mfma_f32_16x16x32_bf16 v[82:85], v[86:89], v[52:55], v[82:85]
	ds_read_b128 v[86:89], v105 offset:22528
	ds_read_b128 v[204:207], v105 offset:7168
	ds_read_b128 v[208:211], v105 offset:23552
	s_waitcnt lgkmcnt(2)
	v_mfma_f32_16x16x32_bf16 v[82:85], v[86:89], v[64:67], v[82:85]
	v_mov_b32_dpp v87, v30 row_ror:1 row_mask:0xf bank_mask:0xf bound_ctrl:1
	v_mov_b32_dpp v86, v34 row_ror:1 row_mask:0xf bank_mask:0xf bound_ctrl:1
	v_mov_b32_dpp v89, v31 row_ror:1 row_mask:0xf bank_mask:0xf bound_ctrl:1
	v_mfma_f32_16x16x32_bf16 v[74:77], v[78:81], v[64:67], v[74:77]
	ds_read_b128 v[78:81], v198 offset:128
	ds_read_b128 v[212:215], v198 offset:144
	ds_read_b128 v[216:219], v198 offset:1664
	v_mov_b32_dpp v88, v35 row_ror:1 row_mask:0xf bank_mask:0xf bound_ctrl:1
	s_waitcnt lgkmcnt(2)
	v_pk_mul_f32 v[70:71], v[78:79], v[2:3] op_sel:[0,1] op_sel_hi:[1,0]
	v_mfma_f32_16x16x32_bf16 v[82:85], v[208:211], v[60:63], v[82:85]
	ds_read_b128 v[208:211], v198 offset:1152
	v_sub_f32_e32 v1, v70, v71
	v_pk_mul_f32 v[70:71], v[78:79], v[2:3]
	v_mov_b32_e32 v91, v80
	v_mfma_f32_16x16x32_bf16 v[74:77], v[204:207], v[60:63], v[74:77]
	v_add_f32_e32 v28, v71, v70
	v_mov_b32_dpp v71, v29 row_ror:1 row_mask:0xf bank_mask:0xf bound_ctrl:1
	v_mov_b32_dpp v70, v33 row_ror:1 row_mask:0xf bank_mask:0xf bound_ctrl:1
	s_nop 0
	v_add_f32_e32 v32, v82, v28
	v_pk_mul_f32 v[28:29], v[80:81], v[70:71] op_sel:[0,1] op_sel_hi:[1,0]
	s_nop 1
	v_add_f32_e32 v1, v74, v1
	v_sub_f32_e32 v28, v28, v29
	v_add_f32_e32 v33, v28, v75
	v_pk_mul_f32 v[28:29], v[80:81], v[70:71]
	v_cndmask_b32_e64 v33, v75, v33, s[10:11]
	v_add_f32_e32 v28, v29, v28
	v_add_f32_e32 v90, v28, v83
	s_waitcnt lgkmcnt(2)
; #define SSM_SCAN_STEP(D, SQ) { _Pragma("unroll") for (int r = 0; r < 4; ++r) { \
;                     const float sr = dppf<DPP_SHR(D)>(Er[r]), si = dppf<DPP_SHR(D)>(Ei[r]); \
;                     Er[r] += mr[r] * sr - mi[r] * si; Ei[r] += mr[r] * si + mi[r] * sr; \
;                     if (SQ) { const float nr = mr[r] * mr[r] - mi[r] * mi[r], ni = 2.f * mr[r] * mi[r]; mr[r] = nr; mi[r] = ni; } } }
; template <bool PASS2>
; __device__ __forceinline__ void ssm_phase(const Params& p, const Frame& F0) {
;     ...
;                 for (int r = 0; r < 4; ++r) { hr[r] = dppf<DPP_ROR(1)>(xs[i][r]); hi[r] = dppf<DPP_ROR(1)>(xs[i + 4][r]);
;                     if (j == 0) { Er[r] += mr[r] * hr[r] - mi[r] * hi[r]; Ei[r] += mr[r] * hi[r] + mi[r] * hr[r]; } }
;     ...
;                 SSM_SCAN_STEP(1, 1) SSM_SCAN_STEP(2, 1) SSM_SCAN_STEP(4, 1) SSM_SCAN_STEP(8, 0)
	v_pk_mul_f32 v[28:29], v[212:213], v[86:87] op_sel:[0,1] op_sel_hi:[1,0]
	v_mov_b32_dpp v75, v33 row_shr:1 row_mask:0xf bank_mask:0xf bound_ctrl:1
	v_sub_f32_e32 v28, v28, v29
	v_add_f32_e32 v34, v28, v76
	v_pk_mul_f32 v[28:29], v[212:213], v[86:87]
	v_cndmask_b32_e64 v34, v76, v34, s[10:11]
	v_add_f32_e32 v28, v29, v28
	v_add_f32_e32 v30, v28, v84
	v_pk_mul_f32 v[28:29], v[214:215], v[88:89] op_sel:[0,1] op_sel_hi:[1,0]
	v_mov_b32_e32 v204, v79
	v_sub_f32_e32 v28, v28, v29
	v_add_f32_e32 v35, v28, v77
	v_pk_mul_f32 v[28:29], v[214:215], v[88:89]
	v_cndmask_b32_e64 v35, v77, v35, s[10:11]
	v_add_f32_e32 v28, v29, v28
	v_add_f32_e32 v28, v28, v85
	v_cndmask_b32_e64 v31, v85, v28, s[10:11]
	v_cndmask_b32_e64 v29, v83, v90, s[10:11]
	v_cndmask_b32_e64 v28, v82, v32, s[10:11]
	v_cndmask_b32_e64 v32, v74, v1, s[10:11]
	v_mov_b32_dpp v77, v29 row_shr:1 row_mask:0xf bank_mask:0xf bound_ctrl:1
	v_mov_b32_dpp v76, v28 row_shr:1 row_mask:0xf bank_mask:0xf bound_ctrl:1
	v_mov_b32_e32 v90, v78
	v_mov_b32_dpp v74, v32 row_shr:1 row_mask:0xf bank_mask:0xf bound_ctrl:1
	v_pk_mul_f32 v[200:201], v[90:91], v[76:77]
	v_mov_b32_e32 v205, v81
	ds_read_b128 v[78:81], v198 offset:640
	v_pk_fma_f32 v[200:201], v[204:205], v[74:75], v[200:201]
	v_pk_add_f32 v[28:29], v[200:201], v[28:29]
	v_pk_mul_f32 v[76:77], v[204:205], v[76:77]
	v_pk_fma_f32 v[74:75], v[90:91], v[74:75], v[76:77] neg_lo:[0,0,1] neg_hi:[0,0,1]
	v_mov_b32_dpp v200, v28 row_shr:2 row_mask:0xf bank_mask:0xf bound_ctrl:1
	v_mov_b32_dpp v201, v29 row_shr:2 row_mask:0xf bank_mask:0xf bound_ctrl:1
	v_pk_add_f32 v[32:33], v[74:75], v[32:33]
	s_waitcnt lgkmcnt(0)
	v_pk_mul_f32 v[206:207], v[78:79], v[200:201]
	v_pk_mul_f32 v[76:77], v[80:81], v[200:201]
	v_mov_b32_dpp v74, v32 row_shr:2 row_mask:0xf bank_mask:0xf bound_ctrl:1
	v_mov_b32_dpp v75, v33 row_shr:2 row_mask:0xf bank_mask:0xf bound_ctrl:1
	v_pk_fma_f32 v[76:77], v[78:79], v[74:75], v[76:77] neg_lo:[0,0,1] neg_hi:[0,0,1]
	v_pk_fma_f32 v[74:75], v[80:81], v[74:75], v[206:207]
	ds_read_b64 v[80:81], v198 offset:664
	ds_read_b128 v[204:207], v198 offset:1168
	v_pk_add_f32 v[28:29], v[28:29], v[74:75]
	v_pk_add_f32 v[32:33], v[76:77], v[32:33]
	s_nop 0
	v_mov_b32_dpp v76, v28 row_shr:4 row_mask:0xf bank_mask:0xf bound_ctrl:1
	v_mov_b32_dpp v77, v29 row_shr:4 row_mask:0xf bank_mask:0xf bound_ctrl:1
	v_mov_b32_dpp v74, v32 row_shr:4 row_mask:0xf bank_mask:0xf bound_ctrl:1
	v_mov_b32_dpp v75, v33 row_shr:4 row_mask:0xf bank_mask:0xf bound_ctrl:1
	v_pk_mul_f32 v[78:79], v[210:211], v[76:77]
	v_pk_mul_f32 v[76:77], v[208:209], v[76:77]
	v_pk_fma_f32 v[78:79], v[208:209], v[74:75], v[78:79] neg_lo:[0,0,1] neg_hi:[0,0,1]
	v_pk_fma_f32 v[74:75], v[210:211], v[74:75], v[76:77]
	ds_read_b128 v[208:211], v198 offset:1680
	v_pk_add_f32 v[74:75], v[28:29], v[74:75]
	v_pk_add_f32 v[32:33], v[32:33], v[78:79]
	s_nop 0
	v_mov_b32_dpp v78, v74 row_shr:8 row_mask:0xf bank_mask:0xf bound_ctrl:1
	v_mov_b32_dpp v79, v75 row_shr:8 row_mask:0xf bank_mask:0xf bound_ctrl:1
	v_mov_b32_dpp v76, v32 row_shr:8 row_mask:0xf bank_mask:0xf bound_ctrl:1
	v_mov_b32_dpp v77, v33 row_shr:8 row_mask:0xf bank_mask:0xf bound_ctrl:1
	v_pk_mul_f32 v[28:29], v[218:219], v[78:79]
	v_cndmask_b32_e64 v30, v84, v30, s[10:11]
	v_pk_fma_f32 v[28:29], v[216:217], v[76:77], v[28:29] neg_lo:[0,0,1] neg_hi:[0,0,1]
	v_mov_b32_dpp v85, v31 row_shr:1 row_mask:0xf bank_mask:0xf bound_ctrl:1
	v_pk_add_f32 v[28:29], v[32:33], v[28:29]
	v_pk_mul_f32 v[32:33], v[216:217], v[78:79]
	v_mov_b32_dpp v84, v30 row_shr:1 row_mask:0xf bank_mask:0xf bound_ctrl:1
	v_pk_fma_f32 v[32:33], v[218:219], v[76:77], v[32:33]
	v_mov_b32_dpp v82, v34 row_shr:1 row_mask:0xf bank_mask:0xf bound_ctrl:1
	v_pk_add_f32 v[32:33], v[74:75], v[32:33]
	v_mov_b32_e32 v74, v212
	v_mov_b32_e32 v75, v214
	v_mov_b32_dpp v83, v35 row_shr:1 row_mask:0xf bank_mask:0xf bound_ctrl:1
	v_pk_mul_f32 v[76:77], v[74:75], v[84:85]
	v_mov_b32_e32 v78, v213
	v_mov_b32_e32 v79, v215
	v_pk_fma_f32 v[76:77], v[78:79], v[82:83], v[76:77]
	v_pk_add_f32 v[30:31], v[76:77], v[30:31]
	ds_read_b64 v[76:77], v198 offset:656
	v_pk_mul_f32 v[78:79], v[78:79], v[84:85]
	v_mov_b32_dpp v90, v30 row_shr:2 row_mask:0xf bank_mask:0xf bound_ctrl:1
	v_pk_fma_f32 v[74:75], v[74:75], v[82:83], v[78:79] neg_lo:[0,0,1] neg_hi:[0,0,1]
	v_mov_b32_dpp v91, v31 row_shr:2 row_mask:0xf bank_mask:0xf bound_ctrl:1
	v_pk_add_f32 v[34:35], v[74:75], v[34:35]
	s_waitcnt lgkmcnt(0)
; __device__ __forceinline__ unsigned cvt_pk_bf16(float lo, float hi) { unsigned r; asm("v_cvt_pk_bf16_f32 %0, %1, %2" : "=v"(r) : "v"(lo), "v"(hi)); return r; }
; #define SSM_SCAN_STEP(D, SQ) { _Pragma("unroll") for (int r = 0; r < 4; ++r) { \
;                     const float sr = dppf<DPP_SHR(D)>(Er[r]), si = dppf<DPP_SHR(D)>(Ei[r]); \
;                     Er[r] += mr[r] * sr - mi[r] * si; Ei[r] += mr[r] * si + mi[r] * sr; \
;                     if (SQ) { const float nr = mr[r] * mr[r] - mi[r] * mi[r], ni = 2.f * mr[r] * mi[r]; mr[r] = nr; mi[r] = ni; } } }
; template <bool PASS2>
; __device__ __forceinline__ void ssm_phase(const Params& p, const Frame& F0) {
;     ...
;                 SSM_SCAN_STEP(1, 1) SSM_SCAN_STEP(2, 1) SSM_SCAN_STEP(4, 1) SSM_SCAN_STEP(8, 0)
;     ...
;                 if constexpr (PASS2) {
;                     float vr[4], vi[4];
; #pragma unroll
;                     for (int r = 0; r < 4; ++r) { const float pr_ = dppf<DPP_ROR(1)>(Er[r]), pi_ = dppf<DPP_ROR(1)>(Ei[r]); vr[r] = (j == 0) ? hr[r] : pr_; vi[r] = (j == 0) ? hi[r] : pi_; }
;                     hw[i >> 1][2 * (i & 1)] = cvt_pk_bf16(vr[0], vr[1]); hw[i >> 1][2 * (i & 1) + 1] = cvt_pk_bf16(vr[2], vr[3]);
;                     hw[2 + (i >> 1)][2 * (i & 1)] = cvt_pk_bf16(vi[0], vi[1]); hw[2 + (i >> 1)][2 * (i & 1) + 1] = cvt_pk_bf16(vi[2], vi[3]);
;                 }
;                 xs[i] = Er; xs[i + 4] = Ei;
	v_pk_mul_f32 v[200:201], v[76:77], v[90:91]
	v_mov_b32_dpp v74, v34 row_shr:2 row_mask:0xf bank_mask:0xf bound_ctrl:1
	v_mov_b32_dpp v75, v35 row_shr:2 row_mask:0xf bank_mask:0xf bound_ctrl:1
	v_pk_mul_f32 v[78:79], v[80:81], v[90:91]
	v_pk_fma_f32 v[76:77], v[76:77], v[74:75], v[78:79] neg_lo:[0,0,1] neg_hi:[0,0,1]
	v_pk_fma_f32 v[74:75], v[80:81], v[74:75], v[200:201]
	v_pk_add_f32 v[30:31], v[30:31], v[74:75]
	v_pk_add_f32 v[34:35], v[34:35], v[76:77]
	s_nop 0
	v_mov_b32_dpp v76, v30 row_shr:4 row_mask:0xf bank_mask:0xf bound_ctrl:1
	v_mov_b32_dpp v77, v31 row_shr:4 row_mask:0xf bank_mask:0xf bound_ctrl:1
	v_mov_b32_dpp v74, v34 row_shr:4 row_mask:0xf bank_mask:0xf bound_ctrl:1
	v_mov_b32_dpp v75, v35 row_shr:4 row_mask:0xf bank_mask:0xf bound_ctrl:1
	v_pk_mul_f32 v[78:79], v[206:207], v[76:77]
	v_pk_mul_f32 v[76:77], v[204:205], v[76:77]
	v_pk_fma_f32 v[78:79], v[204:205], v[74:75], v[78:79] neg_lo:[0,0,1] neg_hi:[0,0,1]
	v_pk_fma_f32 v[74:75], v[206:207], v[74:75], v[76:77]
	v_pk_add_f32 v[74:75], v[30:31], v[74:75]
	v_pk_add_f32 v[34:35], v[34:35], v[78:79]
	s_nop 0
	v_mov_b32_dpp v78, v74 row_shr:8 row_mask:0xf bank_mask:0xf bound_ctrl:1
	v_mov_b32_dpp v79, v75 row_shr:8 row_mask:0xf bank_mask:0xf bound_ctrl:1
	v_mov_b32_dpp v76, v34 row_shr:8 row_mask:0xf bank_mask:0xf bound_ctrl:1
	v_mov_b32_dpp v77, v35 row_shr:8 row_mask:0xf bank_mask:0xf bound_ctrl:1
	v_pk_mul_f32 v[30:31], v[210:211], v[78:79]
	v_mov_b32_dpp v1, v28 row_ror:1 row_mask:0xf bank_mask:0xf bound_ctrl:1
	v_pk_fma_f32 v[30:31], v[208:209], v[76:77], v[30:31] neg_lo:[0,0,1] neg_hi:[0,0,1]
	v_cndmask_b32_e64 v1, v1, v3, s[10:11]
	v_pk_add_f32 v[30:31], v[34:35], v[30:31]
	v_pk_mul_f32 v[34:35], v[208:209], v[78:79]
	v_mov_b32_dpp v3, v29 row_ror:1 row_mask:0xf bank_mask:0xf bound_ctrl:1
	v_pk_fma_f32 v[34:35], v[210:211], v[76:77], v[34:35]
	v_cndmask_b32_e64 v3, v3, v71, s[10:11]
	v_pk_add_f32 v[34:35], v[74:75], v[34:35]
	v_mov_b32_dpp v74, v32 row_ror:1 row_mask:0xf bank_mask:0xf bound_ctrl:1
	v_cndmask_b32_e64 v2, v74, v2, s[10:11]
	v_mov_b32_dpp v71, v30 row_ror:1 row_mask:0xf bank_mask:0xf bound_ctrl:1
	v_mov_b32_dpp v74, v33 row_ror:1 row_mask:0xf bank_mask:0xf bound_ctrl:1
	v_cndmask_b32_e64 v70, v74, v70, s[10:11]
	v_mov_b32_dpp v75, v35 row_ror:1 row_mask:0xf bank_mask:0xf bound_ctrl:1
	v_mov_b32_dpp v74, v34 row_ror:1 row_mask:0xf bank_mask:0xf bound_ctrl:1
	v_cndmask_b32_e64 v76, v74, v86, s[10:11]
	v_cndmask_b32_e64 v71, v71, v87, s[10:11]
	v_mov_b32_dpp v74, v31 row_ror:1 row_mask:0xf bank_mask:0xf bound_ctrl:1
	v_cndmask_b32_e64 v77, v74, v89, s[10:11]
	v_cndmask_b32_e64 v78, v75, v88, s[10:11]
	v_cvt_pk_bf16_f32 v74, v1, v3
	v_cvt_pk_bf16_f32 v75, v71, v77
	v_cvt_pk_bf16_f32 v70, v2, v70
	v_cvt_pk_bf16_f32 v71, v76, v78
	ds_read_b128 v[76:79], v105 offset:8192
	ds_read_b128 v[80:83], v105 offset:9216
	ds_read_b128 v[84:87], v105 offset:24576
	ds_read_b128 v[88:91], v105 offset:25600
	s_and_b32 s98, s3, 0x180
	s_cbranch_scc1 .Lssmw_4
	s_waitcnt vmcnt(3)

; #define SSM_SCAN_STEP(D, SQ) { _Pragma("unroll") for (int r = 0; r < 4; ++r) { \
;                     const float sr = dppf<DPP_SHR(D)>(Er[r]), si = dppf<DPP_SHR(D)>(Ei[r]); \
;                     Er[r] += mr[r] * sr - mi[r] * si; Ei[r] += mr[r] * si + mi[r] * sr; \
;                     if (SQ) { const float nr = mr[r] * mr[r] - mi[r] * mi[r], ni = 2.f * mr[r] * mi[r]; mr[r] = nr; mi[r] = ni; } } }
; template <bool PASS2>
; __device__ __forceinline__ void ssm_phase(const Params& p, const Frame& F0) {
;     ...
;             for (int i = 0; i < 4; ++i) {
;                 __builtin_amdgcn_sched_barrier(0);
;                 f32x4 Er = (f32x4){0.f, 0.f, 0.f, 0.f}, Ei = Er;
; #pragma unroll
;                 for (int ks = 0; ks < 4; ++ks) { Er = __builtin_amdgcn_mfma_f32_16x16x32_bf16(frag[(i * 4 + ks) * 64], uf[ks], Er, 0, 0, 0);
;                                                  Ei = __builtin_amdgcn_mfma_f32_16x16x32_bf16(frag[((i + 4) * 4 + ks) * 64], uf[ks], Ei, 0, 0, 0); }
;                 const f32x4 ma = m1t[8 * i], mb = m1t[8 * i + 1];
;                 float mr[4] = {ma[0], ma[2], mb[0], mb[2]}, mi[4] = {ma[1], ma[3], mb[1], mb[3]};
;                 float hr[4], hi[4];
; #pragma unroll
;                 for (int r = 0; r < 4; ++r) { hr[r] = dppf<DPP_ROR(1)>(xs[i][r]); hi[r] = dppf<DPP_ROR(1)>(xs[i + 4][r]);
;                     if (j == 0) { Er[r] += mr[r] * hr[r] - mi[r] * hi[r]; Ei[r] += mr[r] * hi[r] + mi[r] * hr[r]; } }
;     ...
;                 SSM_SCAN_STEP(1, 1) SSM_SCAN_STEP(2, 1) SSM_SCAN_STEP(4, 1) SSM_SCAN_STEP(8, 0)
.Lssmw_5:
	v_mov_b32_dpp v2, v24 row_ror:1 row_mask:0xf bank_mask:0xf bound_ctrl:1
	s_waitcnt lgkmcnt(3)
	v_mfma_f32_16x16x32_bf16 v[76:79], v[76:79], v[56:59], 0
	v_mov_b32_dpp v201, v23 row_ror:1 row_mask:0xf bank_mask:0xf bound_ctrl:1
	v_mov_b32_dpp v200, v27 row_ror:1 row_mask:0xf bank_mask:0xf bound_ctrl:1
	s_waitcnt lgkmcnt(1)
	v_mfma_f32_16x16x32_bf16 v[84:87], v[84:87], v[56:59], 0
	v_mfma_f32_16x16x32_bf16 v[76:79], v[80:83], v[52:55], v[76:79]
	ds_read_b128 v[80:83], v105 offset:10240
	s_waitcnt lgkmcnt(1)
	v_mfma_f32_16x16x32_bf16 v[84:87], v[88:91], v[52:55], v[84:87]
	ds_read_b128 v[88:91], v105 offset:26624
	ds_read_b128 v[204:207], v105 offset:11264
	ds_read_b128 v[208:211], v105 offset:27648
	s_waitcnt lgkmcnt(2)
	v_mfma_f32_16x16x32_bf16 v[84:87], v[88:91], v[64:67], v[84:87]
	v_mov_b32_dpp v91, v22 row_ror:1 row_mask:0xf bank_mask:0xf bound_ctrl:1
	v_mov_b32_dpp v90, v26 row_ror:1 row_mask:0xf bank_mask:0xf bound_ctrl:1
	v_mfma_f32_16x16x32_bf16 v[76:79], v[80:83], v[64:67], v[76:79]
	ds_read_b128 v[80:83], v198 offset:256
	ds_read_b128 v[212:215], v198 offset:272
	ds_read_b128 v[216:219], v198 offset:1280
	ds_read_b128 v[220:223], v198 offset:1792
	s_waitcnt lgkmcnt(3)
	v_pk_mul_f32 v[88:89], v[80:81], v[2:3] op_sel:[0,1] op_sel_hi:[1,0]
	v_mfma_f32_16x16x32_bf16 v[84:87], v[208:211], v[60:63], v[84:87]
	v_sub_f32_e32 v1, v88, v89
	v_pk_mul_f32 v[88:89], v[80:81], v[2:3]
	v_mov_b32_e32 v208, v81
	v_mfma_f32_16x16x32_bf16 v[76:79], v[204:207], v[60:63], v[76:79]
	v_add_f32_e32 v20, v89, v88
	v_mov_b32_dpp v89, v21 row_ror:1 row_mask:0xf bank_mask:0xf bound_ctrl:1
	v_mov_b32_dpp v88, v25 row_ror:1 row_mask:0xf bank_mask:0xf bound_ctrl:1
	s_nop 0
	v_add_f32_e32 v24, v84, v20
	v_pk_mul_f32 v[20:21], v[82:83], v[88:89] op_sel:[0,1] op_sel_hi:[1,0]
	s_nop 1
	v_add_f32_e32 v1, v76, v1
	v_sub_f32_e32 v20, v20, v21
	v_add_f32_e32 v25, v20, v77
	v_pk_mul_f32 v[20:21], v[82:83], v[88:89]
	v_cndmask_b32_e64 v25, v77, v25, s[10:11]
	v_add_f32_e32 v20, v21, v20
	v_add_f32_e32 v199, v20, v85
	s_waitcnt lgkmcnt(2)
	v_pk_mul_f32 v[20:21], v[212:213], v[90:91] op_sel:[0,1] op_sel_hi:[1,0]
	v_mov_b32_e32 v204, v80
	v_sub_f32_e32 v20, v20, v21
	v_add_f32_e32 v26, v20, v78
	v_pk_mul_f32 v[20:21], v[212:213], v[90:91]
	v_cndmask_b32_e64 v26, v78, v26, s[10:11]
	v_add_f32_e32 v20, v21, v20
	v_add_f32_e32 v22, v20, v86
	v_pk_mul_f32 v[20:21], v[214:215], v[200:201] op_sel:[0,1] op_sel_hi:[1,0]
	v_mov_b32_e32 v205, v82
	v_sub_f32_e32 v20, v20, v21
	v_add_f32_e32 v27, v20, v79
	v_pk_mul_f32 v[20:21], v[214:215], v[200:201]
	v_cndmask_b32_e64 v27, v79, v27, s[10:11]
	v_add_f32_e32 v20, v21, v20
	v_add_f32_e32 v20, v20, v87
	v_cndmask_b32_e64 v23, v87, v20, s[10:11]
	v_cndmask_b32_e64 v21, v85, v199, s[10:11]
	v_cndmask_b32_e64 v20, v84, v24, s[10:11]
	v_cndmask_b32_e64 v24, v76, v1, s[10:11]
	v_mov_b32_dpp v79, v21 row_shr:1 row_mask:0xf bank_mask:0xf bound_ctrl:1
	v_mov_b32_dpp v78, v20 row_shr:1 row_mask:0xf bank_mask:0xf bound_ctrl:1
	v_mov_b32_dpp v76, v24 row_shr:1 row_mask:0xf bank_mask:0xf bound_ctrl:1
	v_mov_b32_dpp v77, v25 row_shr:1 row_mask:0xf bank_mask:0xf bound_ctrl:1
	v_pk_mul_f32 v[206:207], v[204:205], v[78:79]
	v_mov_b32_e32 v209, v83
	ds_read_b128 v[80:83], v198 offset:768
	v_pk_fma_f32 v[206:207], v[208:209], v[76:77], v[206:207]
	v_pk_add_f32 v[20:21], v[206:207], v[20:21]
	v_pk_mul_f32 v[78:79], v[208:209], v[78:79]
	v_pk_fma_f32 v[76:77], v[204:205], v[76:77], v[78:79] neg_lo:[0,0,1] neg_hi:[0,0,1]
	v_mov_b32_dpp v206, v20 row_shr:2 row_mask:0xf bank_mask:0xf bound_ctrl:1
	v_mov_b32_dpp v207, v21 row_shr:2 row_mask:0xf bank_mask:0xf bound_ctrl:1
	v_pk_add_f32 v[24:25], v[76:77], v[24:25]
	s_waitcnt lgkmcnt(0)
	v_pk_mul_f32 v[210:211], v[80:81], v[206:207]
	v_pk_mul_f32 v[78:79], v[82:83], v[206:207]
	v_mov_b32_dpp v76, v24 row_shr:2 row_mask:0xf bank_mask:0xf bound_ctrl:1
	v_mov_b32_dpp v77, v25 row_shr:2 row_mask:0xf bank_mask:0xf bound_ctrl:1
	v_pk_fma_f32 v[78:79], v[80:81], v[76:77], v[78:79] neg_lo:[0,0,1] neg_hi:[0,0,1]
	v_pk_fma_f32 v[76:77], v[82:83], v[76:77], v[210:211]
	ds_read_b64 v[82:83], v198 offset:792
	ds_read_b128 v[208:211], v198 offset:1296
	v_pk_add_f32 v[20:21], v[20:21], v[76:77]
	v_pk_add_f32 v[24:25], v[78:79], v[24:25]
	s_nop 0
	v_mov_b32_dpp v78, v20 row_shr:4 row_mask:0xf bank_mask:0xf bound_ctrl:1
	v_mov_b32_dpp v79, v21 row_shr:4 row_mask:0xf bank_mask:0xf bound_ctrl:1
	v_mov_b32_dpp v76, v24 row_shr:4 row_mask:0xf bank_mask:0xf bound_ctrl:1
	v_mov_b32_dpp v77, v25 row_shr:4 row_mask:0xf bank_mask:0xf bound_ctrl:1
	v_pk_mul_f32 v[80:81], v[218:219], v[78:79]
	v_pk_mul_f32 v[78:79], v[216:217], v[78:79]
	v_pk_fma_f32 v[80:81], v[216:217], v[76:77], v[80:81] neg_lo:[0,0,1] neg_hi:[0,0,1]
	v_pk_fma_f32 v[76:77], v[218:219], v[76:77], v[78:79]
	v_pk_add_f32 v[76:77], v[20:21], v[76:77]
	v_pk_add_f32 v[24:25], v[24:25], v[80:81]
	s_nop 0
	v_mov_b32_dpp v80, v76 row_shr:8 row_mask:0xf bank_mask:0xf bound_ctrl:1
	v_mov_b32_dpp v81, v77 row_shr:8 row_mask:0xf bank_mask:0xf bound_ctrl:1
	v_mov_b32_dpp v78, v24 row_shr:8 row_mask:0xf bank_mask:0xf bound_ctrl:1
	v_mov_b32_dpp v79, v25 row_shr:8 row_mask:0xf bank_mask:0xf bound_ctrl:1
	v_pk_mul_f32 v[20:21], v[222:223], v[80:81]
	v_cndmask_b32_e64 v22, v86, v22, s[10:11]
	v_pk_fma_f32 v[20:21], v[220:221], v[78:79], v[20:21] neg_lo:[0,0,1] neg_hi:[0,0,1]
	v_mov_b32_dpp v87, v23 row_shr:1 row_mask:0xf bank_mask:0xf bound_ctrl:1
	v_pk_add_f32 v[20:21], v[24:25], v[20:21]
	v_pk_mul_f32 v[24:25], v[220:221], v[80:81]
	v_mov_b32_dpp v86, v22 row_shr:1 row_mask:0xf bank_mask:0xf bound_ctrl:1
	v_pk_fma_f32 v[24:25], v[222:223], v[78:79], v[24:25]
	v_mov_b32_dpp v84, v26 row_shr:1 row_mask:0xf bank_mask:0xf bound_ctrl:1
	v_pk_add_f32 v[24:25], v[76:77], v[24:25]
	v_mov_b32_e32 v76, v212
	v_mov_b32_e32 v77, v214
	v_mov_b32_dpp v85, v27 row_shr:1 row_mask:0xf bank_mask:0xf bound_ctrl:1
	v_pk_mul_f32 v[78:79], v[76:77], v[86:87]
	v_mov_b32_e32 v80, v213
	v_mov_b32_e32 v81, v215
	ds_read_b128 v[212:215], v198 offset:1808
	v_pk_fma_f32 v[78:79], v[80:81], v[84:85], v[78:79]
	v_pk_add_f32 v[22:23], v[78:79], v[22:23]
	ds_read_b64 v[78:79], v198 offset:784
	v_pk_mul_f32 v[80:81], v[80:81], v[86:87]
	v_mov_b32_dpp v204, v22 row_shr:2 row_mask:0xf bank_mask:0xf bound_ctrl:1
	v_pk_fma_f32 v[76:77], v[76:77], v[84:85], v[80:81] neg_lo:[0,0,1] neg_hi:[0,0,1]
	v_mov_b32_dpp v205, v23 row_shr:2 row_mask:0xf bank_mask:0xf bound_ctrl:1
	v_pk_add_f32 v[26:27], v[76:77], v[26:27]
	s_waitcnt lgkmcnt(0)
; __device__ __forceinline__ unsigned cvt_pk_bf16(float lo, float hi) { unsigned r; asm("v_cvt_pk_bf16_f32 %0, %1, %2" : "=v"(r) : "v"(lo), "v"(hi)); return r; }
; #define SSM_SCAN_STEP(D, SQ) { _Pragma("unroll") for (int r = 0; r < 4; ++r) { \
;                     const float sr = dppf<DPP_SHR(D)>(Er[r]), si = dppf<DPP_SHR(D)>(Ei[r]); \
;                     Er[r] += mr[r] * sr - mi[r] * si; Ei[r] += mr[r] * si + mi[r] * sr; \
;                     if (SQ) { const float nr = mr[r] * mr[r] - mi[r] * mi[r], ni = 2.f * mr[r] * mi[r]; mr[r] = nr; mi[r] = ni; } } }
; template <bool PASS2>
; __device__ __forceinline__ void ssm_phase(const Params& p, const Frame& F0) {
;     ...
;                 for (int r = 0; r < 4; ++r) { hr[r] = dppf<DPP_ROR(1)>(xs[i][r]); hi[r] = dppf<DPP_ROR(1)>(xs[i + 4][r]);
;                     if (j == 0) { Er[r] += mr[r] * hr[r] - mi[r] * hi[r]; Ei[r] += mr[r] * hi[r] + mi[r] * hr[r]; } }
;     ...
;                 SSM_SCAN_STEP(1, 1) SSM_SCAN_STEP(2, 1) SSM_SCAN_STEP(4, 1) SSM_SCAN_STEP(8, 0)
;     ...
;                 if constexpr (PASS2) {
;                     float vr[4], vi[4];
; #pragma unroll
;                     for (int r = 0; r < 4; ++r) { const float pr_ = dppf<DPP_ROR(1)>(Er[r]), pi_ = dppf<DPP_ROR(1)>(Ei[r]); vr[r] = (j == 0) ? hr[r] : pr_; vi[r] = (j == 0) ? hi[r] : pi_; }
;                     hw[i >> 1][2 * (i & 1)] = cvt_pk_bf16(vr[0], vr[1]); hw[i >> 1][2 * (i & 1) + 1] = cvt_pk_bf16(vr[2], vr[3]);
;                     hw[2 + (i >> 1)][2 * (i & 1)] = cvt_pk_bf16(vi[0], vi[1]); hw[2 + (i >> 1)][2 * (i & 1) + 1] = cvt_pk_bf16(vi[2], vi[3]);
;                 }
;                 xs[i] = Er; xs[i + 4] = Ei;
	v_pk_mul_f32 v[206:207], v[78:79], v[204:205]
	v_mov_b32_dpp v76, v26 row_shr:2 row_mask:0xf bank_mask:0xf bound_ctrl:1
	v_mov_b32_dpp v77, v27 row_shr:2 row_mask:0xf bank_mask:0xf bound_ctrl:1
	v_pk_mul_f32 v[80:81], v[82:83], v[204:205]
	v_pk_fma_f32 v[78:79], v[78:79], v[76:77], v[80:81] neg_lo:[0,0,1] neg_hi:[0,0,1]
	v_pk_fma_f32 v[76:77], v[82:83], v[76:77], v[206:207]
	v_pk_add_f32 v[22:23], v[22:23], v[76:77]
	v_pk_add_f32 v[26:27], v[26:27], v[78:79]
	s_nop 0
	v_mov_b32_dpp v78, v22 row_shr:4 row_mask:0xf bank_mask:0xf bound_ctrl:1
	v_mov_b32_dpp v79, v23 row_shr:4 row_mask:0xf bank_mask:0xf bound_ctrl:1
	v_mov_b32_dpp v76, v26 row_shr:4 row_mask:0xf bank_mask:0xf bound_ctrl:1
	v_mov_b32_dpp v77, v27 row_shr:4 row_mask:0xf bank_mask:0xf bound_ctrl:1
	v_pk_mul_f32 v[80:81], v[210:211], v[78:79]
	v_pk_mul_f32 v[78:79], v[208:209], v[78:79]
	v_pk_fma_f32 v[80:81], v[208:209], v[76:77], v[80:81] neg_lo:[0,0,1] neg_hi:[0,0,1]
	v_pk_fma_f32 v[76:77], v[210:211], v[76:77], v[78:79]
	v_pk_add_f32 v[76:77], v[22:23], v[76:77]
	v_pk_add_f32 v[26:27], v[26:27], v[80:81]
	s_nop 0
	v_mov_b32_dpp v80, v76 row_shr:8 row_mask:0xf bank_mask:0xf bound_ctrl:1
	v_mov_b32_dpp v81, v77 row_shr:8 row_mask:0xf bank_mask:0xf bound_ctrl:1
	v_mov_b32_dpp v78, v26 row_shr:8 row_mask:0xf bank_mask:0xf bound_ctrl:1
	v_mov_b32_dpp v79, v27 row_shr:8 row_mask:0xf bank_mask:0xf bound_ctrl:1
	v_pk_mul_f32 v[22:23], v[214:215], v[80:81]
	v_mov_b32_dpp v1, v20 row_ror:1 row_mask:0xf bank_mask:0xf bound_ctrl:1
	v_pk_fma_f32 v[22:23], v[212:213], v[78:79], v[22:23] neg_lo:[0,0,1] neg_hi:[0,0,1]
	v_cndmask_b32_e64 v1, v1, v3, s[10:11]
	v_pk_add_f32 v[22:23], v[26:27], v[22:23]
	v_pk_mul_f32 v[26:27], v[212:213], v[80:81]
	v_mov_b32_dpp v3, v21 row_ror:1 row_mask:0xf bank_mask:0xf bound_ctrl:1
	v_pk_fma_f32 v[26:27], v[214:215], v[78:79], v[26:27]
	v_mov_b32_dpp v79, v23 row_ror:1 row_mask:0xf bank_mask:0xf bound_ctrl:1
	v_pk_add_f32 v[26:27], v[76:77], v[26:27]
	v_mov_b32_dpp v76, v24 row_ror:1 row_mask:0xf bank_mask:0xf bound_ctrl:1
	v_cndmask_b32_e64 v2, v76, v2, s[10:11]
	v_mov_b32_dpp v77, v22 row_ror:1 row_mask:0xf bank_mask:0xf bound_ctrl:1
	v_mov_b32_dpp v76, v25 row_ror:1 row_mask:0xf bank_mask:0xf bound_ctrl:1
	v_mov_b32_dpp v78, v26 row_ror:1 row_mask:0xf bank_mask:0xf bound_ctrl:1
	v_mov_b32_dpp v80, v27 row_ror:1 row_mask:0xf bank_mask:0xf bound_ctrl:1
	v_cndmask_b32_e64 v76, v76, v88, s[10:11]
	v_cndmask_b32_e64 v77, v77, v91, s[10:11]
	v_cndmask_b32_e64 v78, v78, v90, s[10:11]
	v_cndmask_b32_e64 v79, v79, v201, s[10:11]
	v_cndmask_b32_e64 v82, v80, v200, s[10:11]
	v_cndmask_b32_e64 v3, v3, v89, s[10:11]
	v_cvt_pk_bf16_f32 v80, v1, v3
	v_cvt_pk_bf16_f32 v81, v77, v79
	v_cvt_pk_bf16_f32 v76, v2, v76
	v_cvt_pk_bf16_f32 v77, v78, v82
	ds_read_b128 v[82:85], v105 offset:12288
	ds_read_b128 v[86:89], v105 offset:13312
	ds_read_b128 v[204:207], v105 offset:28672
	ds_read_b128 v[208:211], v105 offset:29696
	v_mov_b32_dpp v3, v44 row_ror:1 row_mask:0xf bank_mask:0xf bound_ctrl:1
	s_and_b32 s98, s3, 0x180
	s_cbranch_scc1 .Lssmw_6
	s_waitcnt vmcnt(0)
.Lssmw_6:
	v_mov_b32_dpp v2, v48 row_ror:1 row_mask:0xf bank_mask:0xf bound_ctrl:1
	s_waitcnt lgkmcnt(3)
	v_mfma_f32_16x16x32_bf16 v[82:85], v[82:85], v[56:59], 0
	v_mov_b32_dpp v91, v46 row_ror:1 row_mask:0xf bank_mask:0xf bound_ctrl:1
	v_mov_b32_dpp v90, v50 row_ror:1 row_mask:0xf bank_mask:0xf bound_ctrl:1
	v_mov_b32_dpp v201, v47 row_ror:1 row_mask:0xf bank_mask:0xf bound_ctrl:1
	s_waitcnt lgkmcnt(1)
	v_mfma_f32_16x16x32_bf16 v[204:207], v[204:207], v[56:59], 0
	v_mov_b32_dpp v200, v51 row_ror:1 row_mask:0xf bank_mask:0xf bound_ctrl:1
	v_mfma_f32_16x16x32_bf16 v[82:85], v[86:89], v[52:55], v[82:85]
	ds_read_b128 v[86:89], v105 offset:14336
	s_waitcnt lgkmcnt(1)
	v_mfma_f32_16x16x32_bf16 v[204:207], v[208:211], v[52:55], v[204:207]
	ds_read_b128 v[208:211], v105 offset:30720
	ds_read_b128 v[212:215], v105 offset:15360
	ds_read_b128 v[216:219], v105 offset:31744
	s_waitcnt lgkmcnt(2)
	v_mfma_f32_16x16x32_bf16 v[204:207], v[208:211], v[64:67], v[204:207]
	v_mfma_f32_16x16x32_bf16 v[82:85], v[86:89], v[64:67], v[82:85]
	ds_read_b128 v[86:89], v198 offset:384
	ds_read_b128 v[220:223], v198 offset:400
	ds_read_b128 v[224:227], v198 offset:1920
	s_waitcnt lgkmcnt(2)
	v_pk_mul_f32 v[78:79], v[86:87], v[2:3] op_sel:[0,1] op_sel_hi:[1,0]
	v_mfma_f32_16x16x32_bf16 v[204:207], v[216:219], v[60:63], v[204:207]
	ds_read_b128 v[216:219], v198 offset:1408
	v_sub_f32_e32 v1, v78, v79
	v_pk_mul_f32 v[78:79], v[86:87], v[2:3]
	v_mov_b32_e32 v208, v86
	v_mfma_f32_16x16x32_bf16 v[82:85], v[212:215], v[60:63], v[82:85]
	v_add_f32_e32 v44, v79, v78
	v_mov_b32_dpp v79, v45 row_ror:1 row_mask:0xf bank_mask:0xf bound_ctrl:1
	v_mov_b32_dpp v78, v49 row_ror:1 row_mask:0xf bank_mask:0xf bound_ctrl:1
	s_nop 0
	v_add_f32_e32 v48, v204, v44
	v_pk_mul_f32 v[44:45], v[88:89], v[78:79] op_sel:[0,1] op_sel_hi:[1,0]
	s_nop 1
	v_add_f32_e32 v1, v82, v1
	v_sub_f32_e32 v44, v44, v45
	v_add_f32_e32 v49, v44, v83
	v_pk_mul_f32 v[44:45], v[88:89], v[78:79]
	v_cndmask_b32_e64 v49, v83, v49, s[10:11]
	v_add_f32_e32 v44, v45, v44
	v_add_f32_e32 v199, v44, v205
	s_waitcnt lgkmcnt(2)
; #define SSM_SCAN_STEP(D, SQ) { _Pragma("unroll") for (int r = 0; r < 4; ++r) { \
;                     const float sr = dppf<DPP_SHR(D)>(Er[r]), si = dppf<DPP_SHR(D)>(Ei[r]); \
;                     Er[r] += mr[r] * sr - mi[r] * si; Ei[r] += mr[r] * si + mi[r] * sr; \
;                     if (SQ) { const float nr = mr[r] * mr[r] - mi[r] * mi[r], ni = 2.f * mr[r] * mi[r]; mr[r] = nr; mi[r] = ni; } } }
; template <bool PASS2>
; __device__ __forceinline__ void ssm_phase(const Params& p, const Frame& F0) {
;     ...
;                 for (int r = 0; r < 4; ++r) { hr[r] = dppf<DPP_ROR(1)>(xs[i][r]); hi[r] = dppf<DPP_ROR(1)>(xs[i + 4][r]);
;                     if (j == 0) { Er[r] += mr[r] * hr[r] - mi[r] * hi[r]; Ei[r] += mr[r] * hi[r] + mi[r] * hr[r]; } }
;     ...
;                 SSM_SCAN_STEP(1, 1) SSM_SCAN_STEP(2, 1) SSM_SCAN_STEP(4, 1) SSM_SCAN_STEP(8, 0)
	v_pk_mul_f32 v[44:45], v[220:221], v[90:91] op_sel:[0,1] op_sel_hi:[1,0]
	v_mov_b32_e32 v209, v88
	v_sub_f32_e32 v44, v44, v45
	v_add_f32_e32 v50, v44, v84
	v_pk_mul_f32 v[44:45], v[220:221], v[90:91]
	v_cndmask_b32_e64 v50, v84, v50, s[10:11]
	v_add_f32_e32 v44, v45, v44
	v_add_f32_e32 v46, v44, v206
	v_pk_mul_f32 v[44:45], v[222:223], v[200:201] op_sel:[0,1] op_sel_hi:[1,0]
	v_mov_b32_dpp v83, v49 row_shr:1 row_mask:0xf bank_mask:0xf bound_ctrl:1
	v_sub_f32_e32 v44, v44, v45
	v_add_f32_e32 v51, v44, v85
	v_pk_mul_f32 v[44:45], v[222:223], v[200:201]
	v_cndmask_b32_e64 v51, v85, v51, s[10:11]
	v_add_f32_e32 v44, v45, v44
	v_add_f32_e32 v44, v44, v207
	v_cndmask_b32_e64 v47, v207, v44, s[10:11]
	v_cndmask_b32_e64 v45, v205, v199, s[10:11]
	v_cndmask_b32_e64 v44, v204, v48, s[10:11]
	v_cndmask_b32_e64 v48, v82, v1, s[10:11]
	v_mov_b32_dpp v85, v45 row_shr:1 row_mask:0xf bank_mask:0xf bound_ctrl:1
	v_mov_b32_dpp v84, v44 row_shr:1 row_mask:0xf bank_mask:0xf bound_ctrl:1
	v_mov_b32_dpp v82, v48 row_shr:1 row_mask:0xf bank_mask:0xf bound_ctrl:1
	v_pk_mul_f32 v[210:211], v[208:209], v[84:85]
	v_mov_b32_e32 v212, v87
	v_mov_b32_e32 v213, v89
	ds_read_b128 v[86:89], v198 offset:896
	v_pk_fma_f32 v[210:211], v[212:213], v[82:83], v[210:211]
	v_pk_add_f32 v[44:45], v[210:211], v[44:45]
	v_pk_mul_f32 v[84:85], v[212:213], v[84:85]
	v_pk_fma_f32 v[82:83], v[208:209], v[82:83], v[84:85] neg_lo:[0,0,1] neg_hi:[0,0,1]
	v_mov_b32_dpp v210, v44 row_shr:2 row_mask:0xf bank_mask:0xf bound_ctrl:1
	v_mov_b32_dpp v211, v45 row_shr:2 row_mask:0xf bank_mask:0xf bound_ctrl:1
	v_pk_add_f32 v[48:49], v[82:83], v[48:49]
	s_waitcnt lgkmcnt(0)
	v_pk_mul_f32 v[214:215], v[86:87], v[210:211]
	v_pk_mul_f32 v[84:85], v[88:89], v[210:211]
	v_mov_b32_dpp v82, v48 row_shr:2 row_mask:0xf bank_mask:0xf bound_ctrl:1
	v_mov_b32_dpp v83, v49 row_shr:2 row_mask:0xf bank_mask:0xf bound_ctrl:1
	v_pk_fma_f32 v[84:85], v[86:87], v[82:83], v[84:85] neg_lo:[0,0,1] neg_hi:[0,0,1]
	v_pk_fma_f32 v[82:83], v[88:89], v[82:83], v[214:215]
	ds_read_b64 v[88:89], v198 offset:920
	ds_read_b128 v[212:215], v198 offset:1424
	v_pk_add_f32 v[44:45], v[44:45], v[82:83]
	v_pk_add_f32 v[48:49], v[84:85], v[48:49]
	s_nop 0
	v_mov_b32_dpp v84, v44 row_shr:4 row_mask:0xf bank_mask:0xf bound_ctrl:1
	v_mov_b32_dpp v85, v45 row_shr:4 row_mask:0xf bank_mask:0xf bound_ctrl:1
	v_mov_b32_dpp v82, v48 row_shr:4 row_mask:0xf bank_mask:0xf bound_ctrl:1
	v_mov_b32_dpp v83, v49 row_shr:4 row_mask:0xf bank_mask:0xf bound_ctrl:1
	v_pk_mul_f32 v[86:87], v[218:219], v[84:85]
	v_pk_mul_f32 v[84:85], v[216:217], v[84:85]
	v_pk_fma_f32 v[86:87], v[216:217], v[82:83], v[86:87] neg_lo:[0,0,1] neg_hi:[0,0,1]
	v_pk_fma_f32 v[82:83], v[218:219], v[82:83], v[84:85]
	ds_read_b128 v[216:219], v198 offset:1936
	v_pk_add_f32 v[82:83], v[44:45], v[82:83]
	v_pk_add_f32 v[48:49], v[48:49], v[86:87]
	s_nop 0
	v_mov_b32_dpp v86, v82 row_shr:8 row_mask:0xf bank_mask:0xf bound_ctrl:1
	v_mov_b32_dpp v87, v83 row_shr:8 row_mask:0xf bank_mask:0xf bound_ctrl:1
	v_mov_b32_dpp v84, v48 row_shr:8 row_mask:0xf bank_mask:0xf bound_ctrl:1
	v_mov_b32_dpp v85, v49 row_shr:8 row_mask:0xf bank_mask:0xf bound_ctrl:1
	v_pk_mul_f32 v[44:45], v[226:227], v[86:87]
	v_cndmask_b32_e64 v46, v206, v46, s[10:11]
	v_pk_fma_f32 v[44:45], v[224:225], v[84:85], v[44:45] neg_lo:[0,0,1] neg_hi:[0,0,1]
	v_mov_b32_dpp v207, v47 row_shr:1 row_mask:0xf bank_mask:0xf bound_ctrl:1
	v_pk_add_f32 v[44:45], v[48:49], v[44:45]
	v_pk_mul_f32 v[48:49], v[224:225], v[86:87]
	v_mov_b32_dpp v206, v46 row_shr:1 row_mask:0xf bank_mask:0xf bound_ctrl:1
	v_pk_fma_f32 v[48:49], v[226:227], v[84:85], v[48:49]
	v_mov_b32_dpp v204, v50 row_shr:1 row_mask:0xf bank_mask:0xf bound_ctrl:1
	v_pk_add_f32 v[48:49], v[82:83], v[48:49]
	v_mov_b32_e32 v82, v220
	v_mov_b32_e32 v83, v222
	v_mov_b32_dpp v205, v51 row_shr:1 row_mask:0xf bank_mask:0xf bound_ctrl:1
	v_pk_mul_f32 v[84:85], v[82:83], v[206:207]
	v_mov_b32_e32 v86, v221
	v_mov_b32_e32 v87, v223
	v_pk_fma_f32 v[84:85], v[86:87], v[204:205], v[84:85]
	v_pk_add_f32 v[46:47], v[84:85], v[46:47]
	ds_read_b64 v[84:85], v198 offset:912
	v_pk_mul_f32 v[86:87], v[86:87], v[206:207]
	v_mov_b32_dpp v208, v46 row_shr:2 row_mask:0xf bank_mask:0xf bound_ctrl:1
	v_pk_fma_f32 v[82:83], v[82:83], v[204:205], v[86:87] neg_lo:[0,0,1] neg_hi:[0,0,1]
	v_mov_b32_dpp v209, v47 row_shr:2 row_mask:0xf bank_mask:0xf bound_ctrl:1
	v_pk_add_f32 v[50:51], v[82:83], v[50:51]
	s_waitcnt lgkmcnt(0)
; __device__ __forceinline__ unsigned cvt_pk_bf16(float lo, float hi) { unsigned r; asm("v_cvt_pk_bf16_f32 %0, %1, %2" : "=v"(r) : "v"(lo), "v"(hi)); return r; }
; __device__ __forceinline__ float bf_lo(unsigned w) { return __uint_as_float(w << 16); }
; __device__ __forceinline__ float bf_hi(unsigned w) { return __uint_as_float(w & 0xffff0000u); }
; template <bool PASS2>
; __device__ __forceinline__ void ssm_phase(const Params& p, const Frame& F0) {
;     ...
;             if constexpr (PASS2) {
;                 bf16x8 hf[4];
; #pragma unroll
;                 for (int kap = 0; kap < 4; ++kap) hf[kap] = __builtin_bit_cast(bf16x8, (u32x4){hw[kap][0], hw[kap][1], hw[kap][2], hw[kap][3]});
;                 const f32x4 dv = *(const f32x4*)(p.in[16] + g * 16 + 4 * gq);
; #pragma unroll
;                 for (int t = 0; t < 8; ++t) {
;                     asm volatile("" ::: "memory");
;                     f32x4 y = (f32x4){0.f, 0.f, 0.f, 0.f};
; #pragma unroll
;                     for (int ks = 0; ks < 4; ++ks) y = __builtin_amdgcn_mfma_f32_16x16x32_bf16(frag[(32 + t * 4 + ks) * 64], uf[ks], y, 0, 0, 0);
; #pragma unroll
;                     for (int kap = 0; kap < 4; ++kap) y = __builtin_amdgcn_mfma_f32_16x16x32_bf16(frag[(64 + t * 4 + kap) * 64], hf[kap], y, 0, 0, 0);
;                     if (j < nsub) {
;                         const size_t off = (size_t)(row0 + 8 * j + t) * DSSM + g * 16 + 4 * gq;
;                         const u32x2 uu = uw[t];
;                         const float z0 = gelu_tanh(y[0] + dv[0] * bf_lo(uu.x)), z1 = gelu_tanh(y[1] + dv[1] * bf_hi(uu.x)), z2 = gelu_tanh(y[2] + dv[2] * bf_lo(uu.y)), z3 = gelu_tanh(y[3] + dv[3] * bf_hi(uu.y));
;                         *(u32x2*)(Zb + off) = (u32x2){cvt_pk_bf16(z0, z1), cvt_pk_bf16(z2, z3)};
;                     }
	v_pk_mul_f32 v[210:211], v[84:85], v[208:209]
	v_mov_b32_dpp v82, v50 row_shr:2 row_mask:0xf bank_mask:0xf bound_ctrl:1
	v_mov_b32_dpp v83, v51 row_shr:2 row_mask:0xf bank_mask:0xf bound_ctrl:1
	v_pk_mul_f32 v[86:87], v[88:89], v[208:209]
	v_pk_fma_f32 v[84:85], v[84:85], v[82:83], v[86:87] neg_lo:[0,0,1] neg_hi:[0,0,1]
	v_pk_fma_f32 v[82:83], v[88:89], v[82:83], v[210:211]
	v_pk_add_f32 v[46:47], v[46:47], v[82:83]
	v_pk_add_f32 v[50:51], v[50:51], v[84:85]
	s_nop 0
	v_mov_b32_dpp v84, v46 row_shr:4 row_mask:0xf bank_mask:0xf bound_ctrl:1
	v_mov_b32_dpp v85, v47 row_shr:4 row_mask:0xf bank_mask:0xf bound_ctrl:1
	v_mov_b32_dpp v82, v50 row_shr:4 row_mask:0xf bank_mask:0xf bound_ctrl:1
	v_mov_b32_dpp v83, v51 row_shr:4 row_mask:0xf bank_mask:0xf bound_ctrl:1
	v_pk_mul_f32 v[86:87], v[214:215], v[84:85]
	v_pk_mul_f32 v[84:85], v[212:213], v[84:85]
	v_pk_fma_f32 v[86:87], v[212:213], v[82:83], v[86:87] neg_lo:[0,0,1] neg_hi:[0,0,1]
	v_pk_fma_f32 v[82:83], v[214:215], v[82:83], v[84:85]
	v_pk_add_f32 v[82:83], v[46:47], v[82:83]
	v_pk_add_f32 v[50:51], v[50:51], v[86:87]
	s_nop 0
	v_mov_b32_dpp v86, v82 row_shr:8 row_mask:0xf bank_mask:0xf bound_ctrl:1
	v_mov_b32_dpp v87, v83 row_shr:8 row_mask:0xf bank_mask:0xf bound_ctrl:1
	v_mov_b32_dpp v84, v50 row_shr:8 row_mask:0xf bank_mask:0xf bound_ctrl:1
	v_mov_b32_dpp v85, v51 row_shr:8 row_mask:0xf bank_mask:0xf bound_ctrl:1
	v_pk_mul_f32 v[46:47], v[218:219], v[86:87]
	v_mov_b32_dpp v1, v44 row_ror:1 row_mask:0xf bank_mask:0xf bound_ctrl:1
	v_pk_fma_f32 v[46:47], v[216:217], v[84:85], v[46:47] neg_lo:[0,0,1] neg_hi:[0,0,1]
	v_cndmask_b32_e64 v1, v1, v3, s[10:11]
	v_pk_add_f32 v[46:47], v[50:51], v[46:47]
	v_pk_mul_f32 v[50:51], v[216:217], v[86:87]
	v_mov_b32_dpp v3, v45 row_ror:1 row_mask:0xf bank_mask:0xf bound_ctrl:1
	v_pk_fma_f32 v[50:51], v[218:219], v[84:85], v[50:51]
	v_cndmask_b32_e64 v3, v3, v79, s[10:11]
	v_pk_add_f32 v[50:51], v[82:83], v[50:51]
	v_mov_b32_dpp v82, v48 row_ror:1 row_mask:0xf bank_mask:0xf bound_ctrl:1
	v_cndmask_b32_e64 v2, v82, v2, s[10:11]
	v_mov_b32_dpp v79, v46 row_ror:1 row_mask:0xf bank_mask:0xf bound_ctrl:1
	v_mov_b32_dpp v82, v49 row_ror:1 row_mask:0xf bank_mask:0xf bound_ctrl:1
	v_cndmask_b32_e64 v78, v82, v78, s[10:11]
	v_mov_b32_dpp v83, v51 row_ror:1 row_mask:0xf bank_mask:0xf bound_ctrl:1
	v_mov_b32_dpp v82, v50 row_ror:1 row_mask:0xf bank_mask:0xf bound_ctrl:1
	v_cndmask_b32_e64 v84, v82, v90, s[10:11]
	v_cndmask_b32_e64 v79, v79, v91, s[10:11]
	v_mov_b32_dpp v82, v47 row_ror:1 row_mask:0xf bank_mask:0xf bound_ctrl:1
	v_cndmask_b32_e64 v85, v82, v201, s[10:11]
	v_cndmask_b32_e64 v86, v83, v200, s[10:11]
	v_cvt_pk_bf16_f32 v82, v1, v3
	v_cvt_pk_bf16_f32 v83, v79, v85
	v_cvt_pk_bf16_f32 v78, v2, v78
	v_cvt_pk_bf16_f32 v79, v84, v86
	global_load_dwordx4 v[84:87], v[140:141], off
	ds_read_b128 v[88:91], v105 offset:32768
	ds_read_b128 v[204:207], v105 offset:33792
	ds_read_b128 v[208:211], v105 offset:34816
	v_add_u32_e32 v2, s26, v159
	s_waitcnt lgkmcnt(2)
	v_mfma_f32_16x16x32_bf16 v[88:91], v[88:91], v[56:59], 0
	s_waitcnt lgkmcnt(1)
	v_mfma_f32_16x16x32_bf16 v[88:91], v[204:207], v[52:55], v[88:91]
	ds_read_b128 v[204:207], v105 offset:35840
	s_waitcnt lgkmcnt(1)
	v_mfma_f32_16x16x32_bf16 v[88:91], v[208:211], v[64:67], v[88:91]
	ds_read_b128 v[208:211], v164
	s_waitcnt lgkmcnt(1)
	v_mfma_f32_16x16x32_bf16 v[88:91], v[204:207], v[60:63], v[88:91]
	ds_read_b128 v[204:207], v165
	s_waitcnt lgkmcnt(1)
	v_mfma_f32_16x16x32_bf16 v[88:91], v[208:211], v[72:75], v[88:91]
	ds_read_b128 v[208:211], v166
	s_waitcnt lgkmcnt(1)
	v_mfma_f32_16x16x32_bf16 v[88:91], v[204:207], v[80:83], v[88:91]
	ds_read_b128 v[204:207], v167
	s_waitcnt lgkmcnt(1)
	v_mfma_f32_16x16x32_bf16 v[88:91], v[208:211], v[68:71], v[88:91]
	s_waitcnt lgkmcnt(0)
	v_mfma_f32_16x16x32_bf16 v[88:91], v[204:207], v[76:79], v[88:91]
	s_and_saveexec_b64 s[26:27], s[24:25]
	s_cbranch_execz .LBB0_648
	v_lshlrev_b32_e32 v1, 16, v156
	s_waitcnt vmcnt(0)
	s_nop 3
	v_fma_f32 v1, v84, v1, v88
	v_mul_f32_e32 v3, v1, v1
	v_fmamk_f32 v3, v3, 0xbdd2d3e8, v93
	v_mul_f32_e32 v3, v1, v3
	v_exp_f32_e32 v88, v3
	v_and_b32_e32 v3, 0xffff0000, v156
	v_lshlrev_b32_e32 v199, 16, v157
	v_and_b32_e32 v157, 0xffff0000, v157
	v_fma_f32 v89, v85, v3, v89
	v_fma_f32 v90, v86, v199, v90
	v_fmac_f32_e32 v91, v87, v157
	v_mul_f32_e32 v3, v89, v89
	v_mul_f32_e32 v199, v90, v90
	v_mul_f32_e32 v157, v91, v91
	v_fmamk_f32 v3, v3, 0xbdd2d3e8, v93
	v_fmamk_f32 v199, v199, 0xbdd2d3e8, v93
	v_fmamk_f32 v157, v157, 0xbdd2d3e8, v93
	v_mul_f32_e32 v3, v89, v3
	v_mul_f32_e32 v199, v90, v199
	v_mul_f32_e32 v157, v91, v157
	v_exp_f32_e32 v156, v3
	v_exp_f32_e32 v199, v199
	v_exp_f32_e32 v157, v157
	v_add_f32_e32 v88, 1.0, v88
	v_add_f32_e32 v156, 1.0, v156
	v_add_f32_e32 v199, 1.0, v199
	v_add_f32_e32 v157, 1.0, v157
	v_rcp_f32_e32 v88, v88
	v_rcp_f32_e32 v156, v156
	v_rcp_f32_e32 v199, v199
	v_rcp_f32_e32 v157, v157
	v_ashrrev_i32_e32 v3, 31, v2
	v_mul_f32_e32 v1, v1, v88
	v_mul_f32_e32 v88, v89, v156
	v_mul_f32_e32 v89, v90, v199
	v_mul_f32_e32 v90, v91, v157
	v_cvt_pk_bf16_f32 v89, v89, v90
	v_lshlrev_b64 v[90:91], 10, v[2:3]
	v_lshl_add_u64 v[90:91], v[134:135], 0, v[90:91]
	v_cvt_pk_bf16_f32 v88, v1, v88
	global_store_dwordx2 v[90:91], v[88:89], off
